# SCAN phase rewritten by hand: chain loads prefetched 22 items ahead through two register rings, work spread over waves 0-1 of all blocks, n/min chain on one extra wave per chain
# speedup vs baseline: 1.7859x; 1.0156x over previous
.LBB1_811:
	s_and_b64 vcc, exec, s[30:31]
	s_cbranch_vccz .LBB1_861
	s_mov_b64 exec, -1
	v_lshrrev_b32_e32 v220, 6, v162
	v_readlane_b32 s2, v242, 0
	s_load_dwordx4 s[64:67], s[0:1], 0x178
	s_load_dwordx4 s[68:71], s[0:1], 0x188
	s_load_dwordx4 s[72:75], s[0:1], 0x198
	v_readfirstlane_b32 s4, v220
	s_cmp_lt_u32 s4, 2
	s_cbranch_scc0 .Lgs_notc
	s_lshl_b32 s5, s2, 1
	s_add_u32 s5, s5, s4
	s_lshr_b32 s6, s5, 5
	s_and_b32 s5, s5, 31
	s_lshl_b32 s5, s5, 6
	v_add_u32_e32 v236, s5, v168
	v_lshlrev_b32_e32 v236, 4, v236
	s_lshr_b32 s7, s6, 4
	s_and_b32 s8, s6, 15
	s_mul_i32 s8, s8, 66
	s_mul_i32 s9, s7, 1056
	s_add_u32 s8, s8, s9
	s_cmp_eq_u32 s7, 0
	s_cselect_b32 s9, 64, 65
	s_cselect_b32 s10, 1, -1
	s_mov_b32 s11, 0x7fff0000
	s_movk_i32 s14, 66
	s_cselect_b32 s11, s14, s11
	s_add_u32 s9, s9, s8
	s_add_u32 s11, s11, s8
	v_cmp_gt_u32_e32 vcc, 2, v168
	v_add_u32_e32 v220, 64, v168
	v_add_u32_e32 v221, -2, v168
	v_cndmask_b32_e32 v220, v221, v220, vcc
	v_sub_u32_e32 v221, 65, v168
	s_cmp_eq_u32 s7, 0
	s_cselect_b64 s[18:19], -1, 0
	v_and_b32_e32 v222, 1, v168
	v_cndmask_b32_e64 v220, v221, v220, s[18:19]
	v_add_u32_e32 v223, 62, v222
	v_sub_u32_e32 v224, 1, v222
	v_cndmask_b32_e64 v223, v224, v223, s[18:19]
	v_add_u32_e32 v220, s8, v220
	v_add_u32_e32 v223, s8, v223
	v_lshlrev_b32_e32 v220, 3, v220
	v_lshlrev_b32_e32 v223, 3, v223
	s_waitcnt lgkmcnt(0)
	global_load_dwordx2 v[232:233], v220, s[72:73]
	global_load_dwordx2 v[234:235], v223, s[72:73]
	v_mov_b32_e32 v0, 0
	v_mov_b32_e32 v1, 0
	v_mov_b32_e32 v2, 0
	v_mov_b32_e32 v3, 0
	v_mov_b32_e32 v4, 0
	v_mov_b32_e32 v5, 0
	v_mov_b32_e32 v6, 0
	v_mov_b32_e32 v7, 0
	v_mov_b32_e32 v228, 0xf149f2ca
	s_waitcnt lgkmcnt(0)
	s_mov_b32 s12, s9
	s_mov_b32 s13, s9
	s_lshl_b32 s14, s12, 15
	s_add_u32 s16, s64, s14
	s_addc_u32 s17, s65, 0
	global_load_dwordx4 v[8:11], v236, s[16:17]
	s_add_i32 s12, s12, s10
	s_cmp_eq_u32 s12, s11
	s_cselect_b32 s12, s8, s12
	s_lshl_b32 s14, s12, 15
	s_add_u32 s16, s64, s14
	s_addc_u32 s17, s65, 0
	global_load_dwordx4 v[12:15], v236, s[16:17]
	s_add_i32 s12, s12, s10
	s_cmp_eq_u32 s12, s11
	s_cselect_b32 s12, s8, s12
	s_lshl_b32 s14, s12, 15
	s_add_u32 s16, s64, s14
	s_addc_u32 s17, s65, 0
	global_load_dwordx4 v[16:19], v236, s[16:17]
	s_add_i32 s12, s12, s10
	s_cmp_eq_u32 s12, s11
	s_cselect_b32 s12, s8, s12
	s_lshl_b32 s14, s12, 15
	s_add_u32 s16, s64, s14
	s_addc_u32 s17, s65, 0
	global_load_dwordx4 v[20:23], v236, s[16:17]
	s_add_i32 s12, s12, s10
	s_cmp_eq_u32 s12, s11
	s_cselect_b32 s12, s8, s12
	s_lshl_b32 s14, s12, 15
	s_add_u32 s16, s64, s14
	s_addc_u32 s17, s65, 0
	global_load_dwordx4 v[24:27], v236, s[16:17]
	s_add_i32 s12, s12, s10
	s_cmp_eq_u32 s12, s11
	s_cselect_b32 s12, s8, s12
	s_lshl_b32 s14, s12, 15
	s_add_u32 s16, s64, s14
	s_addc_u32 s17, s65, 0
	global_load_dwordx4 v[28:31], v236, s[16:17]
	s_add_i32 s12, s12, s10
	s_cmp_eq_u32 s12, s11
	s_cselect_b32 s12, s8, s12
	s_lshl_b32 s14, s12, 15
	s_add_u32 s16, s64, s14
	s_addc_u32 s17, s65, 0
	global_load_dwordx4 v[32:35], v236, s[16:17]
	s_add_i32 s12, s12, s10
	s_cmp_eq_u32 s12, s11
	s_cselect_b32 s12, s8, s12
	s_lshl_b32 s14, s12, 15
	s_add_u32 s16, s64, s14
	s_addc_u32 s17, s65, 0
	global_load_dwordx4 v[36:39], v236, s[16:17]
	s_add_i32 s12, s12, s10
	s_cmp_eq_u32 s12, s11
	s_cselect_b32 s12, s8, s12
	s_lshl_b32 s14, s12, 15
	s_add_u32 s16, s64, s14
	s_addc_u32 s17, s65, 0
	global_load_dwordx4 v[40:43], v236, s[16:17]
	s_add_i32 s12, s12, s10
	s_cmp_eq_u32 s12, s11
	s_cselect_b32 s12, s8, s12
	s_lshl_b32 s14, s12, 15
	s_add_u32 s16, s64, s14
	s_addc_u32 s17, s65, 0
	global_load_dwordx4 v[44:47], v236, s[16:17]
	s_add_i32 s12, s12, s10
	s_cmp_eq_u32 s12, s11
	s_cselect_b32 s12, s8, s12
	s_lshl_b32 s14, s12, 15
	s_add_u32 s16, s64, s14
	s_addc_u32 s17, s65, 0
	global_load_dwordx4 v[48:51], v236, s[16:17]
	s_add_i32 s12, s12, s10
	s_cmp_eq_u32 s12, s11
	s_cselect_b32 s12, s8, s12
	s_lshl_b32 s14, s12, 15
	s_add_u32 s16, s64, s14
	s_addc_u32 s17, s65, 0
	global_load_dwordx4 v[52:55], v236, s[16:17]
	s_add_i32 s12, s12, s10
	s_cmp_eq_u32 s12, s11
	s_cselect_b32 s12, s8, s12
	s_lshl_b32 s14, s12, 15
	s_add_u32 s16, s64, s14
	s_addc_u32 s17, s65, 0
	global_load_dwordx4 v[56:59], v236, s[16:17]
	s_add_i32 s12, s12, s10
	s_cmp_eq_u32 s12, s11
	s_cselect_b32 s12, s8, s12
	s_lshl_b32 s14, s12, 15
	s_add_u32 s16, s64, s14
	s_addc_u32 s17, s65, 0
	global_load_dwordx4 v[60:63], v236, s[16:17]
	s_add_i32 s12, s12, s10
	s_cmp_eq_u32 s12, s11
	s_cselect_b32 s12, s8, s12
	s_lshl_b32 s14, s12, 15
	s_add_u32 s16, s64, s14
	s_addc_u32 s17, s65, 0
	global_load_dwordx4 v[64:67], v236, s[16:17]
	s_add_i32 s12, s12, s10
	s_cmp_eq_u32 s12, s11
	s_cselect_b32 s12, s8, s12
	s_lshl_b32 s14, s12, 15
	s_add_u32 s16, s64, s14
	s_addc_u32 s17, s65, 0
	global_load_dwordx4 v[68:71], v236, s[16:17]
	s_add_i32 s12, s12, s10
	s_cmp_eq_u32 s12, s11
	s_cselect_b32 s12, s8, s12
	s_lshl_b32 s14, s12, 15
	s_add_u32 s16, s64, s14
	s_addc_u32 s17, s65, 0
	global_load_dwordx4 v[72:75], v236, s[16:17]
	s_add_i32 s12, s12, s10
	s_cmp_eq_u32 s12, s11
	s_cselect_b32 s12, s8, s12
	s_lshl_b32 s14, s12, 15
	s_add_u32 s16, s64, s14
	s_addc_u32 s17, s65, 0
	global_load_dwordx4 v[76:79], v236, s[16:17]
	s_add_i32 s12, s12, s10
	s_cmp_eq_u32 s12, s11
	s_cselect_b32 s12, s8, s12
	s_lshl_b32 s14, s12, 15
	s_add_u32 s16, s64, s14
	s_addc_u32 s17, s65, 0
	global_load_dwordx4 v[80:83], v236, s[16:17]
	s_add_i32 s12, s12, s10
	s_cmp_eq_u32 s12, s11
	s_cselect_b32 s12, s8, s12
	s_lshl_b32 s14, s12, 15
	s_add_u32 s16, s64, s14
	s_addc_u32 s17, s65, 0
	global_load_dwordx4 v[84:87], v236, s[16:17]
	s_add_i32 s12, s12, s10
	s_cmp_eq_u32 s12, s11
	s_cselect_b32 s12, s8, s12
	s_lshl_b32 s14, s12, 15
	s_add_u32 s16, s64, s14
	s_addc_u32 s17, s65, 0
	global_load_dwordx4 v[88:91], v236, s[16:17]
	s_add_i32 s12, s12, s10
	s_cmp_eq_u32 s12, s11
	s_cselect_b32 s12, s8, s12
	s_lshl_b32 s14, s12, 15
	s_add_u32 s16, s64, s14
	s_addc_u32 s17, s65, 0
	global_load_dwordx4 v[92:95], v236, s[16:17]
	s_add_i32 s12, s12, s10
	s_cmp_eq_u32 s12, s11
	s_cselect_b32 s12, s8, s12
	s_lshl_b32 s14, s12, 15
	s_add_u32 s16, s64, s14
	s_addc_u32 s17, s65, 0
	global_load_dwordx4 v[96:99], v236, s[16:17]
	s_add_i32 s12, s12, s10
	s_cmp_eq_u32 s12, s11
	s_cselect_b32 s12, s8, s12
	s_lshl_b32 s14, s12, 15
	s_add_u32 s16, s64, s14
	s_addc_u32 s17, s65, 0
	global_load_dwordx4 v[100:103], v236, s[16:17]
	s_add_i32 s12, s12, s10
	s_cmp_eq_u32 s12, s11
	s_cselect_b32 s12, s8, s12
	s_lshl_b32 s14, s12, 15
	s_add_u32 s16, s64, s14
	s_addc_u32 s17, s65, 0
	global_load_dwordx4 v[104:107], v236, s[16:17]
	s_add_i32 s12, s12, s10
	s_cmp_eq_u32 s12, s11
	s_cselect_b32 s12, s8, s12
	s_lshl_b32 s14, s12, 15
	s_add_u32 s16, s64, s14
	s_addc_u32 s17, s65, 0
	global_load_dwordx4 v[108:111], v236, s[16:17]
	s_add_i32 s12, s12, s10
	s_cmp_eq_u32 s12, s11
	s_cselect_b32 s12, s8, s12
	s_lshl_b32 s14, s12, 15
	s_add_u32 s16, s64, s14
	s_addc_u32 s17, s65, 0
	global_load_dwordx4 v[112:115], v236, s[16:17]
	s_add_i32 s12, s12, s10
	s_cmp_eq_u32 s12, s11
	s_cselect_b32 s12, s8, s12
	s_lshl_b32 s14, s12, 15
	s_add_u32 s16, s64, s14
	s_addc_u32 s17, s65, 0
	global_load_dwordx4 v[116:119], v236, s[16:17]
	s_add_i32 s12, s12, s10
	s_cmp_eq_u32 s12, s11
	s_cselect_b32 s12, s8, s12
	s_lshl_b32 s14, s12, 15
	s_add_u32 s16, s64, s14
	s_addc_u32 s17, s65, 0
	global_load_dwordx4 v[120:123], v236, s[16:17]
	s_add_i32 s12, s12, s10
	s_cmp_eq_u32 s12, s11
	s_cselect_b32 s12, s8, s12
	s_lshl_b32 s14, s12, 15
	s_add_u32 s16, s64, s14
	s_addc_u32 s17, s65, 0
	global_load_dwordx4 v[124:127], v236, s[16:17]
	s_add_i32 s12, s12, s10
	s_cmp_eq_u32 s12, s11
	s_cselect_b32 s12, s8, s12
	s_lshl_b32 s14, s12, 15
	s_add_u32 s16, s64, s14
	s_addc_u32 s17, s65, 0
	global_load_dwordx4 v[130:133], v236, s[16:17]
	s_add_i32 s12, s12, s10
	s_cmp_eq_u32 s12, s11
	s_cselect_b32 s12, s8, s12
	s_lshl_b32 s14, s12, 15
	s_add_u32 s16, s64, s14
	s_addc_u32 s17, s65, 0
	global_load_dwordx4 v[134:137], v236, s[16:17]
	s_add_i32 s12, s12, s10
	s_cmp_eq_u32 s12, s11
	s_cselect_b32 s12, s8, s12
	s_lshl_b32 s14, s12, 15
	s_add_u32 s16, s64, s14
	s_addc_u32 s17, s65, 0
	global_load_dwordx4 v[138:141], v236, s[16:17]
	s_add_i32 s12, s12, s10
	s_cmp_eq_u32 s12, s11
	s_cselect_b32 s12, s8, s12
	s_lshl_b32 s14, s12, 15
	s_add_u32 s16, s64, s14
	s_addc_u32 s17, s65, 0
	global_load_dwordx4 v[142:145], v236, s[16:17]
	s_add_i32 s12, s12, s10
	s_cmp_eq_u32 s12, s11
	s_cselect_b32 s12, s8, s12
	s_lshl_b32 s14, s12, 15
	s_add_u32 s16, s64, s14
	s_addc_u32 s17, s65, 0
	global_load_dwordx4 v[146:149], v236, s[16:17]
	s_add_i32 s12, s12, s10
	s_cmp_eq_u32 s12, s11
	s_cselect_b32 s12, s8, s12
	s_lshl_b32 s14, s12, 15
	s_add_u32 s16, s64, s14
	s_addc_u32 s17, s65, 0
	global_load_dwordx4 v[150:153], v236, s[16:17]
	s_add_i32 s12, s12, s10
	s_cmp_eq_u32 s12, s11
	s_cselect_b32 s12, s8, s12
	s_lshl_b32 s14, s12, 15
	s_add_u32 s16, s64, s14
	s_addc_u32 s17, s65, 0
	global_load_dwordx4 v[154:157], v236, s[16:17]
	s_add_i32 s12, s12, s10
	s_cmp_eq_u32 s12, s11
	s_cselect_b32 s12, s8, s12
	s_lshl_b32 s14, s12, 15
	s_add_u32 s16, s64, s14
	s_addc_u32 s17, s65, 0
	global_load_dwordx4 v[158:161], v236, s[16:17]
	s_add_i32 s12, s12, s10
	s_cmp_eq_u32 s12, s11
	s_cselect_b32 s12, s8, s12
	s_lshl_b32 s14, s12, 15
	s_add_u32 s16, s64, s14
	s_addc_u32 s17, s65, 0
	global_load_dwordx4 v[188:191], v236, s[16:17]
	s_add_i32 s12, s12, s10
	s_cmp_eq_u32 s12, s11
	s_cselect_b32 s12, s8, s12
	s_lshl_b32 s14, s12, 15
	s_add_u32 s16, s64, s14
	s_addc_u32 s17, s65, 0
	global_load_dwordx4 v[192:195], v236, s[16:17]
	s_add_i32 s12, s12, s10
	s_cmp_eq_u32 s12, s11
	s_cselect_b32 s12, s8, s12
	s_lshl_b32 s14, s12, 15
	s_add_u32 s16, s64, s14
	s_addc_u32 s17, s65, 0
	global_load_dwordx4 v[196:199], v236, s[16:17]
	s_add_i32 s12, s12, s10
	s_cmp_eq_u32 s12, s11
	s_cselect_b32 s12, s8, s12
	s_lshl_b32 s14, s12, 15
	s_add_u32 s16, s64, s14
	s_addc_u32 s17, s65, 0
	global_load_dwordx4 v[200:203], v236, s[16:17]
	s_add_i32 s12, s12, s10
	s_cmp_eq_u32 s12, s11
	s_cselect_b32 s12, s8, s12
	s_lshl_b32 s14, s12, 15
	s_add_u32 s16, s64, s14
	s_addc_u32 s17, s65, 0
	global_load_dwordx4 v[204:207], v236, s[16:17]
	s_add_i32 s12, s12, s10
	s_cmp_eq_u32 s12, s11
	s_cselect_b32 s12, s8, s12
	s_lshl_b32 s14, s12, 15
	s_add_u32 s16, s64, s14
	s_addc_u32 s17, s65, 0
	global_load_dwordx4 v[208:211], v236, s[16:17]
	s_add_i32 s12, s12, s10
	s_cmp_eq_u32 s12, s11
	s_cselect_b32 s12, s8, s12
	s_waitcnt vmcnt(22)
	v_cvt_pk_bf16_f32 v216, v0, v1
	v_cvt_pk_bf16_f32 v217, v2, v3
	v_cvt_pk_bf16_f32 v218, v4, v5
	v_cvt_pk_bf16_f32 v219, v6, v7
	s_lshl_b32 s14, s13, 15
	s_add_u32 s16, s66, s14
	s_addc_u32 s17, s67, 0
	global_store_dwordx4 v236, v[216:219], s[16:17]
	v_readlane_b32 s18, v232, 0
	v_readlane_b32 s19, v233, 0
	s_nop 1
	v_add_f32_e32 v231, s18, v228
	v_max_f32_e32 v228, s19, v231
	v_sub_f32_e32 v231, v231, v228
	v_sub_f32_e32 v229, s19, v228
	v_mul_f32_e32 v231, 0x3fb8aa3b, v231
	v_mul_f32_e32 v229, 0x3fb8aa3b, v229
	v_exp_f32_e32 v230, v229
	v_exp_f32_e32 v229, v231
	s_nop 0
	v_lshlrev_b32_e32 v220, 16, v8
	v_and_b32_e32 v221, 0xffff0000, v8
	v_lshlrev_b32_e32 v222, 16, v9
	v_and_b32_e32 v223, 0xffff0000, v9
	v_lshlrev_b32_e32 v224, 16, v10
	v_and_b32_e32 v225, 0xffff0000, v10
	v_lshlrev_b32_e32 v226, 16, v11
	v_and_b32_e32 v227, 0xffff0000, v11
	v_mul_f32_e32 v220, v230, v220
	v_mul_f32_e32 v221, v230, v221
	v_mul_f32_e32 v222, v230, v222
	v_mul_f32_e32 v223, v230, v223
	v_mul_f32_e32 v224, v230, v224
	v_mul_f32_e32 v225, v230, v225
	v_mul_f32_e32 v226, v230, v226
	v_mul_f32_e32 v227, v230, v227
	v_fma_f32 v0, v229, v0, v220
	v_fma_f32 v1, v229, v1, v221
	v_fma_f32 v2, v229, v2, v222
	v_fma_f32 v3, v229, v3, v223
	v_fma_f32 v4, v229, v4, v224
	v_fma_f32 v5, v229, v5, v225
	v_fma_f32 v6, v229, v6, v226
	v_fma_f32 v7, v229, v7, v227
	s_add_i32 s13, s13, s10
	s_cmp_eq_u32 s13, s11
	s_cselect_b32 s13, s8, s13
	v_cvt_pk_bf16_f32 v216, v0, v1
	v_cvt_pk_bf16_f32 v217, v2, v3
	v_cvt_pk_bf16_f32 v218, v4, v5
	v_cvt_pk_bf16_f32 v219, v6, v7
	s_lshl_b32 s14, s13, 15
	s_add_u32 s16, s66, s14
	s_addc_u32 s17, s67, 0
	global_store_dwordx4 v236, v[216:219], s[16:17]
	v_readlane_b32 s18, v232, 1
	v_readlane_b32 s19, v233, 1
	s_nop 1
	v_add_f32_e32 v231, s18, v228
	v_max_f32_e32 v228, s19, v231
	v_sub_f32_e32 v231, v231, v228
	v_sub_f32_e32 v229, s19, v228
	v_mul_f32_e32 v231, 0x3fb8aa3b, v231
	v_mul_f32_e32 v229, 0x3fb8aa3b, v229
	v_exp_f32_e32 v230, v229
	v_exp_f32_e32 v229, v231
	s_nop 0
	v_lshlrev_b32_e32 v220, 16, v12
	v_and_b32_e32 v221, 0xffff0000, v12
	v_lshlrev_b32_e32 v222, 16, v13
	v_and_b32_e32 v223, 0xffff0000, v13
	v_lshlrev_b32_e32 v224, 16, v14
	v_and_b32_e32 v225, 0xffff0000, v14
	v_lshlrev_b32_e32 v226, 16, v15
	v_and_b32_e32 v227, 0xffff0000, v15
	v_mul_f32_e32 v220, v230, v220
	v_mul_f32_e32 v221, v230, v221
	v_mul_f32_e32 v222, v230, v222
	v_mul_f32_e32 v223, v230, v223
	v_mul_f32_e32 v224, v230, v224
	v_mul_f32_e32 v225, v230, v225
	v_mul_f32_e32 v226, v230, v226
	v_mul_f32_e32 v227, v230, v227
	v_fma_f32 v0, v229, v0, v220
	v_fma_f32 v1, v229, v1, v221
	v_fma_f32 v2, v229, v2, v222
	v_fma_f32 v3, v229, v3, v223
	v_fma_f32 v4, v229, v4, v224
	v_fma_f32 v5, v229, v5, v225
	v_fma_f32 v6, v229, v6, v226
	v_fma_f32 v7, v229, v7, v227
	s_add_i32 s13, s13, s10
	s_cmp_eq_u32 s13, s11
	s_cselect_b32 s13, s8, s13
	v_cvt_pk_bf16_f32 v216, v0, v1
	v_cvt_pk_bf16_f32 v217, v2, v3
	v_cvt_pk_bf16_f32 v218, v4, v5
	v_cvt_pk_bf16_f32 v219, v6, v7
	s_lshl_b32 s14, s13, 15
	s_add_u32 s16, s66, s14
	s_addc_u32 s17, s67, 0
	global_store_dwordx4 v236, v[216:219], s[16:17]
	v_readlane_b32 s18, v232, 2
	v_readlane_b32 s19, v233, 2
	s_nop 1
	v_add_f32_e32 v231, s18, v228
	v_max_f32_e32 v228, s19, v231
	v_sub_f32_e32 v231, v231, v228
	v_sub_f32_e32 v229, s19, v228
	v_mul_f32_e32 v231, 0x3fb8aa3b, v231
	v_mul_f32_e32 v229, 0x3fb8aa3b, v229
	v_exp_f32_e32 v230, v229
	v_exp_f32_e32 v229, v231
	s_nop 0
	v_lshlrev_b32_e32 v220, 16, v16
	v_and_b32_e32 v221, 0xffff0000, v16
	v_lshlrev_b32_e32 v222, 16, v17
	v_and_b32_e32 v223, 0xffff0000, v17
	v_lshlrev_b32_e32 v224, 16, v18
	v_and_b32_e32 v225, 0xffff0000, v18
	v_lshlrev_b32_e32 v226, 16, v19
	v_and_b32_e32 v227, 0xffff0000, v19
	v_mul_f32_e32 v220, v230, v220
	v_mul_f32_e32 v221, v230, v221
	v_mul_f32_e32 v222, v230, v222
	v_mul_f32_e32 v223, v230, v223
	v_mul_f32_e32 v224, v230, v224
	v_mul_f32_e32 v225, v230, v225
	v_mul_f32_e32 v226, v230, v226
	v_mul_f32_e32 v227, v230, v227
	v_fma_f32 v0, v229, v0, v220
	v_fma_f32 v1, v229, v1, v221
	v_fma_f32 v2, v229, v2, v222
	v_fma_f32 v3, v229, v3, v223
	v_fma_f32 v4, v229, v4, v224
	v_fma_f32 v5, v229, v5, v225
	v_fma_f32 v6, v229, v6, v226
	v_fma_f32 v7, v229, v7, v227
	s_add_i32 s13, s13, s10
	s_cmp_eq_u32 s13, s11
	s_cselect_b32 s13, s8, s13
	v_cvt_pk_bf16_f32 v216, v0, v1
	v_cvt_pk_bf16_f32 v217, v2, v3
	v_cvt_pk_bf16_f32 v218, v4, v5
	v_cvt_pk_bf16_f32 v219, v6, v7
	s_lshl_b32 s14, s13, 15
	s_add_u32 s16, s66, s14
	s_addc_u32 s17, s67, 0
	global_store_dwordx4 v236, v[216:219], s[16:17]
	v_readlane_b32 s18, v232, 3
	v_readlane_b32 s19, v233, 3
	s_nop 1
	v_add_f32_e32 v231, s18, v228
	v_max_f32_e32 v228, s19, v231
	v_sub_f32_e32 v231, v231, v228
	v_sub_f32_e32 v229, s19, v228
	v_mul_f32_e32 v231, 0x3fb8aa3b, v231
	v_mul_f32_e32 v229, 0x3fb8aa3b, v229
	v_exp_f32_e32 v230, v229
	v_exp_f32_e32 v229, v231
	s_nop 0
	v_lshlrev_b32_e32 v220, 16, v20
	v_and_b32_e32 v221, 0xffff0000, v20
	v_lshlrev_b32_e32 v222, 16, v21
	v_and_b32_e32 v223, 0xffff0000, v21
	v_lshlrev_b32_e32 v224, 16, v22
	v_and_b32_e32 v225, 0xffff0000, v22
	v_lshlrev_b32_e32 v226, 16, v23
	v_and_b32_e32 v227, 0xffff0000, v23
	v_mul_f32_e32 v220, v230, v220
	v_mul_f32_e32 v221, v230, v221
	v_mul_f32_e32 v222, v230, v222
	v_mul_f32_e32 v223, v230, v223
	v_mul_f32_e32 v224, v230, v224
	v_mul_f32_e32 v225, v230, v225
	v_mul_f32_e32 v226, v230, v226
	v_mul_f32_e32 v227, v230, v227
	v_fma_f32 v0, v229, v0, v220
	v_fma_f32 v1, v229, v1, v221
	v_fma_f32 v2, v229, v2, v222
	v_fma_f32 v3, v229, v3, v223
	v_fma_f32 v4, v229, v4, v224
	v_fma_f32 v5, v229, v5, v225
	v_fma_f32 v6, v229, v6, v226
	v_fma_f32 v7, v229, v7, v227
	s_add_i32 s13, s13, s10
	s_cmp_eq_u32 s13, s11
	s_cselect_b32 s13, s8, s13
	v_cvt_pk_bf16_f32 v216, v0, v1
	v_cvt_pk_bf16_f32 v217, v2, v3
	v_cvt_pk_bf16_f32 v218, v4, v5
	v_cvt_pk_bf16_f32 v219, v6, v7
	s_lshl_b32 s14, s13, 15
	s_add_u32 s16, s66, s14
	s_addc_u32 s17, s67, 0
	global_store_dwordx4 v236, v[216:219], s[16:17]
	v_readlane_b32 s18, v232, 4
	v_readlane_b32 s19, v233, 4
	s_nop 1
	v_add_f32_e32 v231, s18, v228
	v_max_f32_e32 v228, s19, v231
	v_sub_f32_e32 v231, v231, v228
	v_sub_f32_e32 v229, s19, v228
	v_mul_f32_e32 v231, 0x3fb8aa3b, v231
	v_mul_f32_e32 v229, 0x3fb8aa3b, v229
	v_exp_f32_e32 v230, v229
	v_exp_f32_e32 v229, v231
	s_nop 0
	v_lshlrev_b32_e32 v220, 16, v24
	v_and_b32_e32 v221, 0xffff0000, v24
	v_lshlrev_b32_e32 v222, 16, v25
	v_and_b32_e32 v223, 0xffff0000, v25
	v_lshlrev_b32_e32 v224, 16, v26
	v_and_b32_e32 v225, 0xffff0000, v26
	v_lshlrev_b32_e32 v226, 16, v27
	v_and_b32_e32 v227, 0xffff0000, v27
	v_mul_f32_e32 v220, v230, v220
	v_mul_f32_e32 v221, v230, v221
	v_mul_f32_e32 v222, v230, v222
	v_mul_f32_e32 v223, v230, v223
	v_mul_f32_e32 v224, v230, v224
	v_mul_f32_e32 v225, v230, v225
	v_mul_f32_e32 v226, v230, v226
	v_mul_f32_e32 v227, v230, v227
	v_fma_f32 v0, v229, v0, v220
	v_fma_f32 v1, v229, v1, v221
	v_fma_f32 v2, v229, v2, v222
	v_fma_f32 v3, v229, v3, v223
	v_fma_f32 v4, v229, v4, v224
	v_fma_f32 v5, v229, v5, v225
	v_fma_f32 v6, v229, v6, v226
	v_fma_f32 v7, v229, v7, v227
	s_add_i32 s13, s13, s10
	s_cmp_eq_u32 s13, s11
	s_cselect_b32 s13, s8, s13
	v_cvt_pk_bf16_f32 v216, v0, v1
	v_cvt_pk_bf16_f32 v217, v2, v3
	v_cvt_pk_bf16_f32 v218, v4, v5
	v_cvt_pk_bf16_f32 v219, v6, v7
	s_lshl_b32 s14, s13, 15
	s_add_u32 s16, s66, s14
	s_addc_u32 s17, s67, 0
	global_store_dwordx4 v236, v[216:219], s[16:17]
	v_readlane_b32 s18, v232, 5
	v_readlane_b32 s19, v233, 5
	s_nop 1
	v_add_f32_e32 v231, s18, v228
	v_max_f32_e32 v228, s19, v231
	v_sub_f32_e32 v231, v231, v228
	v_sub_f32_e32 v229, s19, v228
	v_mul_f32_e32 v231, 0x3fb8aa3b, v231
	v_mul_f32_e32 v229, 0x3fb8aa3b, v229
	v_exp_f32_e32 v230, v229
	v_exp_f32_e32 v229, v231
	s_nop 0
	v_lshlrev_b32_e32 v220, 16, v28
	v_and_b32_e32 v221, 0xffff0000, v28
	v_lshlrev_b32_e32 v222, 16, v29
	v_and_b32_e32 v223, 0xffff0000, v29
	v_lshlrev_b32_e32 v224, 16, v30
	v_and_b32_e32 v225, 0xffff0000, v30
	v_lshlrev_b32_e32 v226, 16, v31
	v_and_b32_e32 v227, 0xffff0000, v31
	v_mul_f32_e32 v220, v230, v220
	v_mul_f32_e32 v221, v230, v221
	v_mul_f32_e32 v222, v230, v222
	v_mul_f32_e32 v223, v230, v223
	v_mul_f32_e32 v224, v230, v224
	v_mul_f32_e32 v225, v230, v225
	v_mul_f32_e32 v226, v230, v226
	v_mul_f32_e32 v227, v230, v227
	v_fma_f32 v0, v229, v0, v220
	v_fma_f32 v1, v229, v1, v221
	v_fma_f32 v2, v229, v2, v222
	v_fma_f32 v3, v229, v3, v223
	v_fma_f32 v4, v229, v4, v224
	v_fma_f32 v5, v229, v5, v225
	v_fma_f32 v6, v229, v6, v226
	v_fma_f32 v7, v229, v7, v227
	s_add_i32 s13, s13, s10
	s_cmp_eq_u32 s13, s11
	s_cselect_b32 s13, s8, s13
	v_cvt_pk_bf16_f32 v216, v0, v1
	v_cvt_pk_bf16_f32 v217, v2, v3
	v_cvt_pk_bf16_f32 v218, v4, v5
	v_cvt_pk_bf16_f32 v219, v6, v7
	s_lshl_b32 s14, s13, 15
	s_add_u32 s16, s66, s14
	s_addc_u32 s17, s67, 0
	global_store_dwordx4 v236, v[216:219], s[16:17]
	v_readlane_b32 s18, v232, 6
	v_readlane_b32 s19, v233, 6
	s_nop 1
	v_add_f32_e32 v231, s18, v228
	v_max_f32_e32 v228, s19, v231
	v_sub_f32_e32 v231, v231, v228
	v_sub_f32_e32 v229, s19, v228
	v_mul_f32_e32 v231, 0x3fb8aa3b, v231
	v_mul_f32_e32 v229, 0x3fb8aa3b, v229
	v_exp_f32_e32 v230, v229
	v_exp_f32_e32 v229, v231
	s_nop 0
	v_lshlrev_b32_e32 v220, 16, v32
	v_and_b32_e32 v221, 0xffff0000, v32
	v_lshlrev_b32_e32 v222, 16, v33
	v_and_b32_e32 v223, 0xffff0000, v33
	v_lshlrev_b32_e32 v224, 16, v34
	v_and_b32_e32 v225, 0xffff0000, v34
	v_lshlrev_b32_e32 v226, 16, v35
	v_and_b32_e32 v227, 0xffff0000, v35
	v_mul_f32_e32 v220, v230, v220
	v_mul_f32_e32 v221, v230, v221
	v_mul_f32_e32 v222, v230, v222
	v_mul_f32_e32 v223, v230, v223
	v_mul_f32_e32 v224, v230, v224
	v_mul_f32_e32 v225, v230, v225
	v_mul_f32_e32 v226, v230, v226
	v_mul_f32_e32 v227, v230, v227
	v_fma_f32 v0, v229, v0, v220
	v_fma_f32 v1, v229, v1, v221
	v_fma_f32 v2, v229, v2, v222
	v_fma_f32 v3, v229, v3, v223
	v_fma_f32 v4, v229, v4, v224
	v_fma_f32 v5, v229, v5, v225
	v_fma_f32 v6, v229, v6, v226
	v_fma_f32 v7, v229, v7, v227
	s_add_i32 s13, s13, s10
	s_cmp_eq_u32 s13, s11
	s_cselect_b32 s13, s8, s13
	v_cvt_pk_bf16_f32 v216, v0, v1
	v_cvt_pk_bf16_f32 v217, v2, v3
	v_cvt_pk_bf16_f32 v218, v4, v5
	v_cvt_pk_bf16_f32 v219, v6, v7
	s_lshl_b32 s14, s13, 15
	s_add_u32 s16, s66, s14
	s_addc_u32 s17, s67, 0
	global_store_dwordx4 v236, v[216:219], s[16:17]
	v_readlane_b32 s18, v232, 7
	v_readlane_b32 s19, v233, 7
	s_nop 1
	v_add_f32_e32 v231, s18, v228
	v_max_f32_e32 v228, s19, v231
	v_sub_f32_e32 v231, v231, v228
	v_sub_f32_e32 v229, s19, v228
	v_mul_f32_e32 v231, 0x3fb8aa3b, v231
	v_mul_f32_e32 v229, 0x3fb8aa3b, v229
	v_exp_f32_e32 v230, v229
	v_exp_f32_e32 v229, v231
	s_nop 0
	v_lshlrev_b32_e32 v220, 16, v36
	v_and_b32_e32 v221, 0xffff0000, v36
	v_lshlrev_b32_e32 v222, 16, v37
	v_and_b32_e32 v223, 0xffff0000, v37
	v_lshlrev_b32_e32 v224, 16, v38
	v_and_b32_e32 v225, 0xffff0000, v38
	v_lshlrev_b32_e32 v226, 16, v39
	v_and_b32_e32 v227, 0xffff0000, v39
	v_mul_f32_e32 v220, v230, v220
	v_mul_f32_e32 v221, v230, v221
	v_mul_f32_e32 v222, v230, v222
	v_mul_f32_e32 v223, v230, v223
	v_mul_f32_e32 v224, v230, v224
	v_mul_f32_e32 v225, v230, v225
	v_mul_f32_e32 v226, v230, v226
	v_mul_f32_e32 v227, v230, v227
	v_fma_f32 v0, v229, v0, v220
	v_fma_f32 v1, v229, v1, v221
	v_fma_f32 v2, v229, v2, v222
	v_fma_f32 v3, v229, v3, v223
	v_fma_f32 v4, v229, v4, v224
	v_fma_f32 v5, v229, v5, v225
	v_fma_f32 v6, v229, v6, v226
	v_fma_f32 v7, v229, v7, v227
	s_add_i32 s13, s13, s10
	s_cmp_eq_u32 s13, s11
	s_cselect_b32 s13, s8, s13
	v_cvt_pk_bf16_f32 v216, v0, v1
	v_cvt_pk_bf16_f32 v217, v2, v3
	v_cvt_pk_bf16_f32 v218, v4, v5
	v_cvt_pk_bf16_f32 v219, v6, v7
	s_lshl_b32 s14, s13, 15
	s_add_u32 s16, s66, s14
	s_addc_u32 s17, s67, 0
	global_store_dwordx4 v236, v[216:219], s[16:17]
	v_readlane_b32 s18, v232, 8
	v_readlane_b32 s19, v233, 8
	s_nop 1
	v_add_f32_e32 v231, s18, v228
	v_max_f32_e32 v228, s19, v231
	v_sub_f32_e32 v231, v231, v228
	v_sub_f32_e32 v229, s19, v228
	v_mul_f32_e32 v231, 0x3fb8aa3b, v231
	v_mul_f32_e32 v229, 0x3fb8aa3b, v229
	v_exp_f32_e32 v230, v229
	v_exp_f32_e32 v229, v231
	s_nop 0
	v_lshlrev_b32_e32 v220, 16, v40
	v_and_b32_e32 v221, 0xffff0000, v40
	v_lshlrev_b32_e32 v222, 16, v41
	v_and_b32_e32 v223, 0xffff0000, v41
	v_lshlrev_b32_e32 v224, 16, v42
	v_and_b32_e32 v225, 0xffff0000, v42
	v_lshlrev_b32_e32 v226, 16, v43
	v_and_b32_e32 v227, 0xffff0000, v43
	v_mul_f32_e32 v220, v230, v220
	v_mul_f32_e32 v221, v230, v221
	v_mul_f32_e32 v222, v230, v222
	v_mul_f32_e32 v223, v230, v223
	v_mul_f32_e32 v224, v230, v224
	v_mul_f32_e32 v225, v230, v225
	v_mul_f32_e32 v226, v230, v226
	v_mul_f32_e32 v227, v230, v227
	v_fma_f32 v0, v229, v0, v220
	v_fma_f32 v1, v229, v1, v221
	v_fma_f32 v2, v229, v2, v222
	v_fma_f32 v3, v229, v3, v223
	v_fma_f32 v4, v229, v4, v224
	v_fma_f32 v5, v229, v5, v225
	v_fma_f32 v6, v229, v6, v226
	v_fma_f32 v7, v229, v7, v227
	s_add_i32 s13, s13, s10
	s_cmp_eq_u32 s13, s11
	s_cselect_b32 s13, s8, s13
	v_cvt_pk_bf16_f32 v216, v0, v1
	v_cvt_pk_bf16_f32 v217, v2, v3
	v_cvt_pk_bf16_f32 v218, v4, v5
	v_cvt_pk_bf16_f32 v219, v6, v7
	s_lshl_b32 s14, s13, 15
	s_add_u32 s16, s66, s14
	s_addc_u32 s17, s67, 0
	global_store_dwordx4 v236, v[216:219], s[16:17]
	v_readlane_b32 s18, v232, 9
	v_readlane_b32 s19, v233, 9
	s_nop 1
	v_add_f32_e32 v231, s18, v228
	v_max_f32_e32 v228, s19, v231
	v_sub_f32_e32 v231, v231, v228
	v_sub_f32_e32 v229, s19, v228
	v_mul_f32_e32 v231, 0x3fb8aa3b, v231
	v_mul_f32_e32 v229, 0x3fb8aa3b, v229
	v_exp_f32_e32 v230, v229
	v_exp_f32_e32 v229, v231
	s_nop 0
	v_lshlrev_b32_e32 v220, 16, v44
	v_and_b32_e32 v221, 0xffff0000, v44
	v_lshlrev_b32_e32 v222, 16, v45
	v_and_b32_e32 v223, 0xffff0000, v45
	v_lshlrev_b32_e32 v224, 16, v46
	v_and_b32_e32 v225, 0xffff0000, v46
	v_lshlrev_b32_e32 v226, 16, v47
	v_and_b32_e32 v227, 0xffff0000, v47
	v_mul_f32_e32 v220, v230, v220
	v_mul_f32_e32 v221, v230, v221
	v_mul_f32_e32 v222, v230, v222
	v_mul_f32_e32 v223, v230, v223
	v_mul_f32_e32 v224, v230, v224
	v_mul_f32_e32 v225, v230, v225
	v_mul_f32_e32 v226, v230, v226
	v_mul_f32_e32 v227, v230, v227
	v_fma_f32 v0, v229, v0, v220
	v_fma_f32 v1, v229, v1, v221
	v_fma_f32 v2, v229, v2, v222
	v_fma_f32 v3, v229, v3, v223
	v_fma_f32 v4, v229, v4, v224
	v_fma_f32 v5, v229, v5, v225
	v_fma_f32 v6, v229, v6, v226
	v_fma_f32 v7, v229, v7, v227
	s_add_i32 s13, s13, s10
	s_cmp_eq_u32 s13, s11
	s_cselect_b32 s13, s8, s13
	v_cvt_pk_bf16_f32 v216, v0, v1
	v_cvt_pk_bf16_f32 v217, v2, v3
	v_cvt_pk_bf16_f32 v218, v4, v5
	v_cvt_pk_bf16_f32 v219, v6, v7
	s_lshl_b32 s14, s13, 15
	s_add_u32 s16, s66, s14
	s_addc_u32 s17, s67, 0
	global_store_dwordx4 v236, v[216:219], s[16:17]
	v_readlane_b32 s18, v232, 10
	v_readlane_b32 s19, v233, 10
	s_nop 1
	v_add_f32_e32 v231, s18, v228
	v_max_f32_e32 v228, s19, v231
	v_sub_f32_e32 v231, v231, v228
	v_sub_f32_e32 v229, s19, v228
	v_mul_f32_e32 v231, 0x3fb8aa3b, v231
	v_mul_f32_e32 v229, 0x3fb8aa3b, v229
	v_exp_f32_e32 v230, v229
	v_exp_f32_e32 v229, v231
	s_nop 0
	v_lshlrev_b32_e32 v220, 16, v48
	v_and_b32_e32 v221, 0xffff0000, v48
	v_lshlrev_b32_e32 v222, 16, v49
	v_and_b32_e32 v223, 0xffff0000, v49
	v_lshlrev_b32_e32 v224, 16, v50
	v_and_b32_e32 v225, 0xffff0000, v50
	v_lshlrev_b32_e32 v226, 16, v51
	v_and_b32_e32 v227, 0xffff0000, v51
	v_mul_f32_e32 v220, v230, v220
	v_mul_f32_e32 v221, v230, v221
	v_mul_f32_e32 v222, v230, v222
	v_mul_f32_e32 v223, v230, v223
	v_mul_f32_e32 v224, v230, v224
	v_mul_f32_e32 v225, v230, v225
	v_mul_f32_e32 v226, v230, v226
	v_mul_f32_e32 v227, v230, v227
	v_fma_f32 v0, v229, v0, v220
	v_fma_f32 v1, v229, v1, v221
	v_fma_f32 v2, v229, v2, v222
	v_fma_f32 v3, v229, v3, v223
	v_fma_f32 v4, v229, v4, v224
	v_fma_f32 v5, v229, v5, v225
	v_fma_f32 v6, v229, v6, v226
	v_fma_f32 v7, v229, v7, v227
	s_add_i32 s13, s13, s10
	s_cmp_eq_u32 s13, s11
	s_cselect_b32 s13, s8, s13
	v_cvt_pk_bf16_f32 v216, v0, v1
	v_cvt_pk_bf16_f32 v217, v2, v3
	v_cvt_pk_bf16_f32 v218, v4, v5
	v_cvt_pk_bf16_f32 v219, v6, v7
	s_lshl_b32 s14, s13, 15
	s_add_u32 s16, s66, s14
	s_addc_u32 s17, s67, 0
	global_store_dwordx4 v236, v[216:219], s[16:17]
	v_readlane_b32 s18, v232, 11
	v_readlane_b32 s19, v233, 11
	s_nop 1
	v_add_f32_e32 v231, s18, v228
	v_max_f32_e32 v228, s19, v231
	v_sub_f32_e32 v231, v231, v228
	v_sub_f32_e32 v229, s19, v228
	v_mul_f32_e32 v231, 0x3fb8aa3b, v231
	v_mul_f32_e32 v229, 0x3fb8aa3b, v229
	v_exp_f32_e32 v230, v229
	v_exp_f32_e32 v229, v231
	s_nop 0
	v_lshlrev_b32_e32 v220, 16, v52
	v_and_b32_e32 v221, 0xffff0000, v52
	v_lshlrev_b32_e32 v222, 16, v53
	v_and_b32_e32 v223, 0xffff0000, v53
	v_lshlrev_b32_e32 v224, 16, v54
	v_and_b32_e32 v225, 0xffff0000, v54
	v_lshlrev_b32_e32 v226, 16, v55
	v_and_b32_e32 v227, 0xffff0000, v55
	v_mul_f32_e32 v220, v230, v220
	v_mul_f32_e32 v221, v230, v221
	v_mul_f32_e32 v222, v230, v222
	v_mul_f32_e32 v223, v230, v223
	v_mul_f32_e32 v224, v230, v224
	v_mul_f32_e32 v225, v230, v225
	v_mul_f32_e32 v226, v230, v226
	v_mul_f32_e32 v227, v230, v227
	v_fma_f32 v0, v229, v0, v220
	v_fma_f32 v1, v229, v1, v221
	v_fma_f32 v2, v229, v2, v222
	v_fma_f32 v3, v229, v3, v223
	v_fma_f32 v4, v229, v4, v224
	v_fma_f32 v5, v229, v5, v225
	v_fma_f32 v6, v229, v6, v226
	v_fma_f32 v7, v229, v7, v227
	s_add_i32 s13, s13, s10
	s_cmp_eq_u32 s13, s11
	s_cselect_b32 s13, s8, s13
	v_cvt_pk_bf16_f32 v216, v0, v1
	v_cvt_pk_bf16_f32 v217, v2, v3
	v_cvt_pk_bf16_f32 v218, v4, v5
	v_cvt_pk_bf16_f32 v219, v6, v7
	s_lshl_b32 s14, s13, 15
	s_add_u32 s16, s66, s14
	s_addc_u32 s17, s67, 0
	global_store_dwordx4 v236, v[216:219], s[16:17]
	v_readlane_b32 s18, v232, 12
	v_readlane_b32 s19, v233, 12
	s_nop 1
	v_add_f32_e32 v231, s18, v228
	v_max_f32_e32 v228, s19, v231
	v_sub_f32_e32 v231, v231, v228
	v_sub_f32_e32 v229, s19, v228
	v_mul_f32_e32 v231, 0x3fb8aa3b, v231
	v_mul_f32_e32 v229, 0x3fb8aa3b, v229
	v_exp_f32_e32 v230, v229
	v_exp_f32_e32 v229, v231
	s_nop 0
	v_lshlrev_b32_e32 v220, 16, v56
	v_and_b32_e32 v221, 0xffff0000, v56
	v_lshlrev_b32_e32 v222, 16, v57
	v_and_b32_e32 v223, 0xffff0000, v57
	v_lshlrev_b32_e32 v224, 16, v58
	v_and_b32_e32 v225, 0xffff0000, v58
	v_lshlrev_b32_e32 v226, 16, v59
	v_and_b32_e32 v227, 0xffff0000, v59
	v_mul_f32_e32 v220, v230, v220
	v_mul_f32_e32 v221, v230, v221
	v_mul_f32_e32 v222, v230, v222
	v_mul_f32_e32 v223, v230, v223
	v_mul_f32_e32 v224, v230, v224
	v_mul_f32_e32 v225, v230, v225
	v_mul_f32_e32 v226, v230, v226
	v_mul_f32_e32 v227, v230, v227
	v_fma_f32 v0, v229, v0, v220
	v_fma_f32 v1, v229, v1, v221
	v_fma_f32 v2, v229, v2, v222
	v_fma_f32 v3, v229, v3, v223
	v_fma_f32 v4, v229, v4, v224
	v_fma_f32 v5, v229, v5, v225
	v_fma_f32 v6, v229, v6, v226
	v_fma_f32 v7, v229, v7, v227
	s_add_i32 s13, s13, s10
	s_cmp_eq_u32 s13, s11
	s_cselect_b32 s13, s8, s13
	v_cvt_pk_bf16_f32 v216, v0, v1
	v_cvt_pk_bf16_f32 v217, v2, v3
	v_cvt_pk_bf16_f32 v218, v4, v5
	v_cvt_pk_bf16_f32 v219, v6, v7
	s_lshl_b32 s14, s13, 15
	s_add_u32 s16, s66, s14
	s_addc_u32 s17, s67, 0
	global_store_dwordx4 v236, v[216:219], s[16:17]
	v_readlane_b32 s18, v232, 13
	v_readlane_b32 s19, v233, 13
	s_nop 1
	v_add_f32_e32 v231, s18, v228
	v_max_f32_e32 v228, s19, v231
	v_sub_f32_e32 v231, v231, v228
	v_sub_f32_e32 v229, s19, v228
	v_mul_f32_e32 v231, 0x3fb8aa3b, v231
	v_mul_f32_e32 v229, 0x3fb8aa3b, v229
	v_exp_f32_e32 v230, v229
	v_exp_f32_e32 v229, v231
	s_nop 0
	v_lshlrev_b32_e32 v220, 16, v60
	v_and_b32_e32 v221, 0xffff0000, v60
	v_lshlrev_b32_e32 v222, 16, v61
	v_and_b32_e32 v223, 0xffff0000, v61
	v_lshlrev_b32_e32 v224, 16, v62
	v_and_b32_e32 v225, 0xffff0000, v62
	v_lshlrev_b32_e32 v226, 16, v63
	v_and_b32_e32 v227, 0xffff0000, v63
	v_mul_f32_e32 v220, v230, v220
	v_mul_f32_e32 v221, v230, v221
	v_mul_f32_e32 v222, v230, v222
	v_mul_f32_e32 v223, v230, v223
	v_mul_f32_e32 v224, v230, v224
	v_mul_f32_e32 v225, v230, v225
	v_mul_f32_e32 v226, v230, v226
	v_mul_f32_e32 v227, v230, v227
	v_fma_f32 v0, v229, v0, v220
	v_fma_f32 v1, v229, v1, v221
	v_fma_f32 v2, v229, v2, v222
	v_fma_f32 v3, v229, v3, v223
	v_fma_f32 v4, v229, v4, v224
	v_fma_f32 v5, v229, v5, v225
	v_fma_f32 v6, v229, v6, v226
	v_fma_f32 v7, v229, v7, v227
	s_add_i32 s13, s13, s10
	s_cmp_eq_u32 s13, s11
	s_cselect_b32 s13, s8, s13
	v_cvt_pk_bf16_f32 v216, v0, v1
	v_cvt_pk_bf16_f32 v217, v2, v3
	v_cvt_pk_bf16_f32 v218, v4, v5
	v_cvt_pk_bf16_f32 v219, v6, v7
	s_lshl_b32 s14, s13, 15
	s_add_u32 s16, s66, s14
	s_addc_u32 s17, s67, 0
	global_store_dwordx4 v236, v[216:219], s[16:17]
	v_readlane_b32 s18, v232, 14
	v_readlane_b32 s19, v233, 14
	s_nop 1
	v_add_f32_e32 v231, s18, v228
	v_max_f32_e32 v228, s19, v231
	v_sub_f32_e32 v231, v231, v228
	v_sub_f32_e32 v229, s19, v228
	v_mul_f32_e32 v231, 0x3fb8aa3b, v231
	v_mul_f32_e32 v229, 0x3fb8aa3b, v229
	v_exp_f32_e32 v230, v229
	v_exp_f32_e32 v229, v231
	s_nop 0
	v_lshlrev_b32_e32 v220, 16, v64
	v_and_b32_e32 v221, 0xffff0000, v64
	v_lshlrev_b32_e32 v222, 16, v65
	v_and_b32_e32 v223, 0xffff0000, v65
	v_lshlrev_b32_e32 v224, 16, v66
	v_and_b32_e32 v225, 0xffff0000, v66
	v_lshlrev_b32_e32 v226, 16, v67
	v_and_b32_e32 v227, 0xffff0000, v67
	v_mul_f32_e32 v220, v230, v220
	v_mul_f32_e32 v221, v230, v221
	v_mul_f32_e32 v222, v230, v222
	v_mul_f32_e32 v223, v230, v223
	v_mul_f32_e32 v224, v230, v224
	v_mul_f32_e32 v225, v230, v225
	v_mul_f32_e32 v226, v230, v226
	v_mul_f32_e32 v227, v230, v227
	v_fma_f32 v0, v229, v0, v220
	v_fma_f32 v1, v229, v1, v221
	v_fma_f32 v2, v229, v2, v222
	v_fma_f32 v3, v229, v3, v223
	v_fma_f32 v4, v229, v4, v224
	v_fma_f32 v5, v229, v5, v225
	v_fma_f32 v6, v229, v6, v226
	v_fma_f32 v7, v229, v7, v227
	s_add_i32 s13, s13, s10
	s_cmp_eq_u32 s13, s11
	s_cselect_b32 s13, s8, s13
	v_cvt_pk_bf16_f32 v216, v0, v1
	v_cvt_pk_bf16_f32 v217, v2, v3
	v_cvt_pk_bf16_f32 v218, v4, v5
	v_cvt_pk_bf16_f32 v219, v6, v7
	s_lshl_b32 s14, s13, 15
	s_add_u32 s16, s66, s14
	s_addc_u32 s17, s67, 0
	global_store_dwordx4 v236, v[216:219], s[16:17]
	v_readlane_b32 s18, v232, 15
	v_readlane_b32 s19, v233, 15
	s_nop 1
	v_add_f32_e32 v231, s18, v228
	v_max_f32_e32 v228, s19, v231
	v_sub_f32_e32 v231, v231, v228
	v_sub_f32_e32 v229, s19, v228
	v_mul_f32_e32 v231, 0x3fb8aa3b, v231
	v_mul_f32_e32 v229, 0x3fb8aa3b, v229
	v_exp_f32_e32 v230, v229
	v_exp_f32_e32 v229, v231
	s_nop 0
	v_lshlrev_b32_e32 v220, 16, v68
	v_and_b32_e32 v221, 0xffff0000, v68
	v_lshlrev_b32_e32 v222, 16, v69
	v_and_b32_e32 v223, 0xffff0000, v69
	v_lshlrev_b32_e32 v224, 16, v70
	v_and_b32_e32 v225, 0xffff0000, v70
	v_lshlrev_b32_e32 v226, 16, v71
	v_and_b32_e32 v227, 0xffff0000, v71
	v_mul_f32_e32 v220, v230, v220
	v_mul_f32_e32 v221, v230, v221
	v_mul_f32_e32 v222, v230, v222
	v_mul_f32_e32 v223, v230, v223
	v_mul_f32_e32 v224, v230, v224
	v_mul_f32_e32 v225, v230, v225
	v_mul_f32_e32 v226, v230, v226
	v_mul_f32_e32 v227, v230, v227
	v_fma_f32 v0, v229, v0, v220
	v_fma_f32 v1, v229, v1, v221
	v_fma_f32 v2, v229, v2, v222
	v_fma_f32 v3, v229, v3, v223
	v_fma_f32 v4, v229, v4, v224
	v_fma_f32 v5, v229, v5, v225
	v_fma_f32 v6, v229, v6, v226
	v_fma_f32 v7, v229, v7, v227
	s_add_i32 s13, s13, s10
	s_cmp_eq_u32 s13, s11
	s_cselect_b32 s13, s8, s13
	v_cvt_pk_bf16_f32 v216, v0, v1
	v_cvt_pk_bf16_f32 v217, v2, v3
	v_cvt_pk_bf16_f32 v218, v4, v5
	v_cvt_pk_bf16_f32 v219, v6, v7
	s_lshl_b32 s14, s13, 15
	s_add_u32 s16, s66, s14
	s_addc_u32 s17, s67, 0
	global_store_dwordx4 v236, v[216:219], s[16:17]
	v_readlane_b32 s18, v232, 16
	v_readlane_b32 s19, v233, 16
	s_nop 1
	v_add_f32_e32 v231, s18, v228
	v_max_f32_e32 v228, s19, v231
	v_sub_f32_e32 v231, v231, v228
	v_sub_f32_e32 v229, s19, v228
	v_mul_f32_e32 v231, 0x3fb8aa3b, v231
	v_mul_f32_e32 v229, 0x3fb8aa3b, v229
	v_exp_f32_e32 v230, v229
	v_exp_f32_e32 v229, v231
	s_nop 0
	v_lshlrev_b32_e32 v220, 16, v72
	v_and_b32_e32 v221, 0xffff0000, v72
	v_lshlrev_b32_e32 v222, 16, v73
	v_and_b32_e32 v223, 0xffff0000, v73
	v_lshlrev_b32_e32 v224, 16, v74
	v_and_b32_e32 v225, 0xffff0000, v74
	v_lshlrev_b32_e32 v226, 16, v75
	v_and_b32_e32 v227, 0xffff0000, v75
	v_mul_f32_e32 v220, v230, v220
	v_mul_f32_e32 v221, v230, v221
	v_mul_f32_e32 v222, v230, v222
	v_mul_f32_e32 v223, v230, v223
	v_mul_f32_e32 v224, v230, v224
	v_mul_f32_e32 v225, v230, v225
	v_mul_f32_e32 v226, v230, v226
	v_mul_f32_e32 v227, v230, v227
	v_fma_f32 v0, v229, v0, v220
	v_fma_f32 v1, v229, v1, v221
	v_fma_f32 v2, v229, v2, v222
	v_fma_f32 v3, v229, v3, v223
	v_fma_f32 v4, v229, v4, v224
	v_fma_f32 v5, v229, v5, v225
	v_fma_f32 v6, v229, v6, v226
	v_fma_f32 v7, v229, v7, v227
	s_add_i32 s13, s13, s10
	s_cmp_eq_u32 s13, s11
	s_cselect_b32 s13, s8, s13
	v_cvt_pk_bf16_f32 v216, v0, v1
	v_cvt_pk_bf16_f32 v217, v2, v3
	v_cvt_pk_bf16_f32 v218, v4, v5
	v_cvt_pk_bf16_f32 v219, v6, v7
	s_lshl_b32 s14, s13, 15
	s_add_u32 s16, s66, s14
	s_addc_u32 s17, s67, 0
	global_store_dwordx4 v236, v[216:219], s[16:17]
	v_readlane_b32 s18, v232, 17
	v_readlane_b32 s19, v233, 17
	s_nop 1
	v_add_f32_e32 v231, s18, v228
	v_max_f32_e32 v228, s19, v231
	v_sub_f32_e32 v231, v231, v228
	v_sub_f32_e32 v229, s19, v228
	v_mul_f32_e32 v231, 0x3fb8aa3b, v231
	v_mul_f32_e32 v229, 0x3fb8aa3b, v229
	v_exp_f32_e32 v230, v229
	v_exp_f32_e32 v229, v231
	s_nop 0
	v_lshlrev_b32_e32 v220, 16, v76
	v_and_b32_e32 v221, 0xffff0000, v76
	v_lshlrev_b32_e32 v222, 16, v77
	v_and_b32_e32 v223, 0xffff0000, v77
	v_lshlrev_b32_e32 v224, 16, v78
	v_and_b32_e32 v225, 0xffff0000, v78
	v_lshlrev_b32_e32 v226, 16, v79
	v_and_b32_e32 v227, 0xffff0000, v79
	v_mul_f32_e32 v220, v230, v220
	v_mul_f32_e32 v221, v230, v221
	v_mul_f32_e32 v222, v230, v222
	v_mul_f32_e32 v223, v230, v223
	v_mul_f32_e32 v224, v230, v224
	v_mul_f32_e32 v225, v230, v225
	v_mul_f32_e32 v226, v230, v226
	v_mul_f32_e32 v227, v230, v227
	v_fma_f32 v0, v229, v0, v220
	v_fma_f32 v1, v229, v1, v221
	v_fma_f32 v2, v229, v2, v222
	v_fma_f32 v3, v229, v3, v223
	v_fma_f32 v4, v229, v4, v224
	v_fma_f32 v5, v229, v5, v225
	v_fma_f32 v6, v229, v6, v226
	v_fma_f32 v7, v229, v7, v227
	s_add_i32 s13, s13, s10
	s_cmp_eq_u32 s13, s11
	s_cselect_b32 s13, s8, s13
	v_cvt_pk_bf16_f32 v216, v0, v1
	v_cvt_pk_bf16_f32 v217, v2, v3
	v_cvt_pk_bf16_f32 v218, v4, v5
	v_cvt_pk_bf16_f32 v219, v6, v7
	s_lshl_b32 s14, s13, 15
	s_add_u32 s16, s66, s14
	s_addc_u32 s17, s67, 0
	global_store_dwordx4 v236, v[216:219], s[16:17]
	v_readlane_b32 s18, v232, 18
	v_readlane_b32 s19, v233, 18
	s_nop 1
	v_add_f32_e32 v231, s18, v228
	v_max_f32_e32 v228, s19, v231
	v_sub_f32_e32 v231, v231, v228
	v_sub_f32_e32 v229, s19, v228
	v_mul_f32_e32 v231, 0x3fb8aa3b, v231
	v_mul_f32_e32 v229, 0x3fb8aa3b, v229
	v_exp_f32_e32 v230, v229
	v_exp_f32_e32 v229, v231
	s_nop 0
	v_lshlrev_b32_e32 v220, 16, v80
	v_and_b32_e32 v221, 0xffff0000, v80
	v_lshlrev_b32_e32 v222, 16, v81
	v_and_b32_e32 v223, 0xffff0000, v81
	v_lshlrev_b32_e32 v224, 16, v82
	v_and_b32_e32 v225, 0xffff0000, v82
	v_lshlrev_b32_e32 v226, 16, v83
	v_and_b32_e32 v227, 0xffff0000, v83
	v_mul_f32_e32 v220, v230, v220
	v_mul_f32_e32 v221, v230, v221
	v_mul_f32_e32 v222, v230, v222
	v_mul_f32_e32 v223, v230, v223
	v_mul_f32_e32 v224, v230, v224
	v_mul_f32_e32 v225, v230, v225
	v_mul_f32_e32 v226, v230, v226
	v_mul_f32_e32 v227, v230, v227
	v_fma_f32 v0, v229, v0, v220
	v_fma_f32 v1, v229, v1, v221
	v_fma_f32 v2, v229, v2, v222
	v_fma_f32 v3, v229, v3, v223
	v_fma_f32 v4, v229, v4, v224
	v_fma_f32 v5, v229, v5, v225
	v_fma_f32 v6, v229, v6, v226
	v_fma_f32 v7, v229, v7, v227
	s_add_i32 s13, s13, s10
	s_cmp_eq_u32 s13, s11
	s_cselect_b32 s13, s8, s13
	v_cvt_pk_bf16_f32 v216, v0, v1
	v_cvt_pk_bf16_f32 v217, v2, v3
	v_cvt_pk_bf16_f32 v218, v4, v5
	v_cvt_pk_bf16_f32 v219, v6, v7
	s_lshl_b32 s14, s13, 15
	s_add_u32 s16, s66, s14
	s_addc_u32 s17, s67, 0
	global_store_dwordx4 v236, v[216:219], s[16:17]
	v_readlane_b32 s18, v232, 19
	v_readlane_b32 s19, v233, 19
	s_nop 1
	v_add_f32_e32 v231, s18, v228
	v_max_f32_e32 v228, s19, v231
	v_sub_f32_e32 v231, v231, v228
	v_sub_f32_e32 v229, s19, v228
	v_mul_f32_e32 v231, 0x3fb8aa3b, v231
	v_mul_f32_e32 v229, 0x3fb8aa3b, v229
	v_exp_f32_e32 v230, v229
	v_exp_f32_e32 v229, v231
	s_nop 0
	v_lshlrev_b32_e32 v220, 16, v84
	v_and_b32_e32 v221, 0xffff0000, v84
	v_lshlrev_b32_e32 v222, 16, v85
	v_and_b32_e32 v223, 0xffff0000, v85
	v_lshlrev_b32_e32 v224, 16, v86
	v_and_b32_e32 v225, 0xffff0000, v86
	v_lshlrev_b32_e32 v226, 16, v87
	v_and_b32_e32 v227, 0xffff0000, v87
	v_mul_f32_e32 v220, v230, v220
	v_mul_f32_e32 v221, v230, v221
	v_mul_f32_e32 v222, v230, v222
	v_mul_f32_e32 v223, v230, v223
	v_mul_f32_e32 v224, v230, v224
	v_mul_f32_e32 v225, v230, v225
	v_mul_f32_e32 v226, v230, v226
	v_mul_f32_e32 v227, v230, v227
	v_fma_f32 v0, v229, v0, v220
	v_fma_f32 v1, v229, v1, v221
	v_fma_f32 v2, v229, v2, v222
	v_fma_f32 v3, v229, v3, v223
	v_fma_f32 v4, v229, v4, v224
	v_fma_f32 v5, v229, v5, v225
	v_fma_f32 v6, v229, v6, v226
	v_fma_f32 v7, v229, v7, v227
	s_add_i32 s13, s13, s10
	s_cmp_eq_u32 s13, s11
	s_cselect_b32 s13, s8, s13
	v_cvt_pk_bf16_f32 v216, v0, v1
	v_cvt_pk_bf16_f32 v217, v2, v3
	v_cvt_pk_bf16_f32 v218, v4, v5
	v_cvt_pk_bf16_f32 v219, v6, v7
	s_lshl_b32 s14, s13, 15
	s_add_u32 s16, s66, s14
	s_addc_u32 s17, s67, 0
	global_store_dwordx4 v236, v[216:219], s[16:17]
	v_readlane_b32 s18, v232, 20
	v_readlane_b32 s19, v233, 20
	s_nop 1
	v_add_f32_e32 v231, s18, v228
	v_max_f32_e32 v228, s19, v231
	v_sub_f32_e32 v231, v231, v228
	v_sub_f32_e32 v229, s19, v228
	v_mul_f32_e32 v231, 0x3fb8aa3b, v231
	v_mul_f32_e32 v229, 0x3fb8aa3b, v229
	v_exp_f32_e32 v230, v229
	v_exp_f32_e32 v229, v231
	s_nop 0
	v_lshlrev_b32_e32 v220, 16, v88
	v_and_b32_e32 v221, 0xffff0000, v88
	v_lshlrev_b32_e32 v222, 16, v89
	v_and_b32_e32 v223, 0xffff0000, v89
	v_lshlrev_b32_e32 v224, 16, v90
	v_and_b32_e32 v225, 0xffff0000, v90
	v_lshlrev_b32_e32 v226, 16, v91
	v_and_b32_e32 v227, 0xffff0000, v91
	v_mul_f32_e32 v220, v230, v220
	v_mul_f32_e32 v221, v230, v221
	v_mul_f32_e32 v222, v230, v222
	v_mul_f32_e32 v223, v230, v223
	v_mul_f32_e32 v224, v230, v224
	v_mul_f32_e32 v225, v230, v225
	v_mul_f32_e32 v226, v230, v226
	v_mul_f32_e32 v227, v230, v227
	v_fma_f32 v0, v229, v0, v220
	v_fma_f32 v1, v229, v1, v221
	v_fma_f32 v2, v229, v2, v222
	v_fma_f32 v3, v229, v3, v223
	v_fma_f32 v4, v229, v4, v224
	v_fma_f32 v5, v229, v5, v225
	v_fma_f32 v6, v229, v6, v226
	v_fma_f32 v7, v229, v7, v227
	s_add_i32 s13, s13, s10
	s_cmp_eq_u32 s13, s11
	s_cselect_b32 s13, s8, s13
	v_cvt_pk_bf16_f32 v216, v0, v1
	v_cvt_pk_bf16_f32 v217, v2, v3
	v_cvt_pk_bf16_f32 v218, v4, v5
	v_cvt_pk_bf16_f32 v219, v6, v7
	s_lshl_b32 s14, s13, 15
	s_add_u32 s16, s66, s14
	s_addc_u32 s17, s67, 0
	global_store_dwordx4 v236, v[216:219], s[16:17]
	v_readlane_b32 s18, v232, 21
	v_readlane_b32 s19, v233, 21
	s_nop 1
	v_add_f32_e32 v231, s18, v228
	v_max_f32_e32 v228, s19, v231
	v_sub_f32_e32 v231, v231, v228
	v_sub_f32_e32 v229, s19, v228
	v_mul_f32_e32 v231, 0x3fb8aa3b, v231
	v_mul_f32_e32 v229, 0x3fb8aa3b, v229
	v_exp_f32_e32 v230, v229
	v_exp_f32_e32 v229, v231
	s_nop 0
	v_lshlrev_b32_e32 v220, 16, v92
	v_and_b32_e32 v221, 0xffff0000, v92
	v_lshlrev_b32_e32 v222, 16, v93
	v_and_b32_e32 v223, 0xffff0000, v93
	v_lshlrev_b32_e32 v224, 16, v94
	v_and_b32_e32 v225, 0xffff0000, v94
	v_lshlrev_b32_e32 v226, 16, v95
	v_and_b32_e32 v227, 0xffff0000, v95
	v_mul_f32_e32 v220, v230, v220
	v_mul_f32_e32 v221, v230, v221
	v_mul_f32_e32 v222, v230, v222
	v_mul_f32_e32 v223, v230, v223
	v_mul_f32_e32 v224, v230, v224
	v_mul_f32_e32 v225, v230, v225
	v_mul_f32_e32 v226, v230, v226
	v_mul_f32_e32 v227, v230, v227
	v_fma_f32 v0, v229, v0, v220
	v_fma_f32 v1, v229, v1, v221
	v_fma_f32 v2, v229, v2, v222
	v_fma_f32 v3, v229, v3, v223
	v_fma_f32 v4, v229, v4, v224
	v_fma_f32 v5, v229, v5, v225
	v_fma_f32 v6, v229, v6, v226
	v_fma_f32 v7, v229, v7, v227
	s_add_i32 s13, s13, s10
	s_cmp_eq_u32 s13, s11
	s_cselect_b32 s13, s8, s13
	s_lshl_b32 s14, s12, 15
	s_add_u32 s16, s64, s14
	s_addc_u32 s17, s65, 0
	global_load_dwordx4 v[8:11], v236, s[16:17]
	s_add_i32 s12, s12, s10
	s_cmp_eq_u32 s12, s11
	s_cselect_b32 s12, s8, s12
	s_lshl_b32 s14, s12, 15
	s_add_u32 s16, s64, s14
	s_addc_u32 s17, s65, 0
	global_load_dwordx4 v[12:15], v236, s[16:17]
	s_add_i32 s12, s12, s10
	s_cmp_eq_u32 s12, s11
	s_cselect_b32 s12, s8, s12
	s_lshl_b32 s14, s12, 15
	s_add_u32 s16, s64, s14
	s_addc_u32 s17, s65, 0
	global_load_dwordx4 v[16:19], v236, s[16:17]
	s_add_i32 s12, s12, s10
	s_cmp_eq_u32 s12, s11
	s_cselect_b32 s12, s8, s12
	s_lshl_b32 s14, s12, 15
	s_add_u32 s16, s64, s14
	s_addc_u32 s17, s65, 0
	global_load_dwordx4 v[20:23], v236, s[16:17]
	s_add_i32 s12, s12, s10
	s_cmp_eq_u32 s12, s11
	s_cselect_b32 s12, s8, s12
	s_lshl_b32 s14, s12, 15
	s_add_u32 s16, s64, s14
	s_addc_u32 s17, s65, 0
	global_load_dwordx4 v[24:27], v236, s[16:17]
	s_add_i32 s12, s12, s10
	s_cmp_eq_u32 s12, s11
	s_cselect_b32 s12, s8, s12
	s_lshl_b32 s14, s12, 15
	s_add_u32 s16, s64, s14
	s_addc_u32 s17, s65, 0
	global_load_dwordx4 v[28:31], v236, s[16:17]
	s_add_i32 s12, s12, s10
	s_cmp_eq_u32 s12, s11
	s_cselect_b32 s12, s8, s12
	s_lshl_b32 s14, s12, 15
	s_add_u32 s16, s64, s14
	s_addc_u32 s17, s65, 0
	global_load_dwordx4 v[32:35], v236, s[16:17]
	s_add_i32 s12, s12, s10
	s_cmp_eq_u32 s12, s11
	s_cselect_b32 s12, s8, s12
	s_lshl_b32 s14, s12, 15
	s_add_u32 s16, s64, s14
	s_addc_u32 s17, s65, 0
	global_load_dwordx4 v[36:39], v236, s[16:17]
	s_add_i32 s12, s12, s10
	s_cmp_eq_u32 s12, s11
	s_cselect_b32 s12, s8, s12
	s_lshl_b32 s14, s12, 15
	s_add_u32 s16, s64, s14
	s_addc_u32 s17, s65, 0
	global_load_dwordx4 v[40:43], v236, s[16:17]
	s_add_i32 s12, s12, s10
	s_cmp_eq_u32 s12, s11
	s_cselect_b32 s12, s8, s12
	s_lshl_b32 s14, s12, 15
	s_add_u32 s16, s64, s14
	s_addc_u32 s17, s65, 0
	global_load_dwordx4 v[44:47], v236, s[16:17]
	s_add_i32 s12, s12, s10
	s_cmp_eq_u32 s12, s11
	s_cselect_b32 s12, s8, s12
	s_lshl_b32 s14, s12, 15
	s_add_u32 s16, s64, s14
	s_addc_u32 s17, s65, 0
	global_load_dwordx4 v[48:51], v236, s[16:17]
	s_add_i32 s12, s12, s10
	s_cmp_eq_u32 s12, s11
	s_cselect_b32 s12, s8, s12
	s_lshl_b32 s14, s12, 15
	s_add_u32 s16, s64, s14
	s_addc_u32 s17, s65, 0
	global_load_dwordx4 v[52:55], v236, s[16:17]
	s_add_i32 s12, s12, s10
	s_cmp_eq_u32 s12, s11
	s_cselect_b32 s12, s8, s12
	s_lshl_b32 s14, s12, 15
	s_add_u32 s16, s64, s14
	s_addc_u32 s17, s65, 0
	global_load_dwordx4 v[56:59], v236, s[16:17]
	s_add_i32 s12, s12, s10
	s_cmp_eq_u32 s12, s11
	s_cselect_b32 s12, s8, s12
	s_lshl_b32 s14, s12, 15
	s_add_u32 s16, s64, s14
	s_addc_u32 s17, s65, 0
	global_load_dwordx4 v[60:63], v236, s[16:17]
	s_add_i32 s12, s12, s10
	s_cmp_eq_u32 s12, s11
	s_cselect_b32 s12, s8, s12
	s_lshl_b32 s14, s12, 15
	s_add_u32 s16, s64, s14
	s_addc_u32 s17, s65, 0
	global_load_dwordx4 v[64:67], v236, s[16:17]
	s_add_i32 s12, s12, s10
	s_cmp_eq_u32 s12, s11
	s_cselect_b32 s12, s8, s12
	s_lshl_b32 s14, s12, 15
	s_add_u32 s16, s64, s14
	s_addc_u32 s17, s65, 0
	global_load_dwordx4 v[68:71], v236, s[16:17]
	s_add_i32 s12, s12, s10
	s_cmp_eq_u32 s12, s11
	s_cselect_b32 s12, s8, s12
	s_lshl_b32 s14, s12, 15
	s_add_u32 s16, s64, s14
	s_addc_u32 s17, s65, 0
	global_load_dwordx4 v[72:75], v236, s[16:17]
	s_add_i32 s12, s12, s10
	s_cmp_eq_u32 s12, s11
	s_cselect_b32 s12, s8, s12
	s_lshl_b32 s14, s12, 15
	s_add_u32 s16, s64, s14
	s_addc_u32 s17, s65, 0
	global_load_dwordx4 v[76:79], v236, s[16:17]
	s_add_i32 s12, s12, s10
	s_cmp_eq_u32 s12, s11
	s_cselect_b32 s12, s8, s12
	s_lshl_b32 s14, s12, 15
	s_add_u32 s16, s64, s14
	s_addc_u32 s17, s65, 0
	global_load_dwordx4 v[80:83], v236, s[16:17]
	s_add_i32 s12, s12, s10
	s_cmp_eq_u32 s12, s11
	s_cselect_b32 s12, s8, s12
	s_lshl_b32 s14, s12, 15
	s_add_u32 s16, s64, s14
	s_addc_u32 s17, s65, 0
	global_load_dwordx4 v[84:87], v236, s[16:17]
	s_add_i32 s12, s12, s10
	s_cmp_eq_u32 s12, s11
	s_cselect_b32 s12, s8, s12
	s_lshl_b32 s14, s12, 15
	s_add_u32 s16, s64, s14
	s_addc_u32 s17, s65, 0
	global_load_dwordx4 v[88:91], v236, s[16:17]
	s_add_i32 s12, s12, s10
	s_cmp_eq_u32 s12, s11
	s_cselect_b32 s12, s8, s12
	s_lshl_b32 s14, s12, 15
	s_add_u32 s16, s64, s14
	s_addc_u32 s17, s65, 0
	global_load_dwordx4 v[92:95], v236, s[16:17]
	s_add_i32 s12, s12, s10
	s_cmp_eq_u32 s12, s11
	s_cselect_b32 s12, s8, s12
	s_waitcnt vmcnt(22)
	v_cvt_pk_bf16_f32 v216, v0, v1
	v_cvt_pk_bf16_f32 v217, v2, v3
	v_cvt_pk_bf16_f32 v218, v4, v5
	v_cvt_pk_bf16_f32 v219, v6, v7
	s_lshl_b32 s14, s13, 15
	s_add_u32 s16, s66, s14
	s_addc_u32 s17, s67, 0
	global_store_dwordx4 v236, v[216:219], s[16:17]
	v_readlane_b32 s18, v232, 22
	v_readlane_b32 s19, v233, 22
	s_nop 1
	v_add_f32_e32 v231, s18, v228
	v_max_f32_e32 v228, s19, v231
	v_sub_f32_e32 v231, v231, v228
	v_sub_f32_e32 v229, s19, v228
	v_mul_f32_e32 v231, 0x3fb8aa3b, v231
	v_mul_f32_e32 v229, 0x3fb8aa3b, v229
	v_exp_f32_e32 v230, v229
	v_exp_f32_e32 v229, v231
	s_nop 0
	v_lshlrev_b32_e32 v220, 16, v96
	v_and_b32_e32 v221, 0xffff0000, v96
	v_lshlrev_b32_e32 v222, 16, v97
	v_and_b32_e32 v223, 0xffff0000, v97
	v_lshlrev_b32_e32 v224, 16, v98
	v_and_b32_e32 v225, 0xffff0000, v98
	v_lshlrev_b32_e32 v226, 16, v99
	v_and_b32_e32 v227, 0xffff0000, v99
	v_mul_f32_e32 v220, v230, v220
	v_mul_f32_e32 v221, v230, v221
	v_mul_f32_e32 v222, v230, v222
	v_mul_f32_e32 v223, v230, v223
	v_mul_f32_e32 v224, v230, v224
	v_mul_f32_e32 v225, v230, v225
	v_mul_f32_e32 v226, v230, v226
	v_mul_f32_e32 v227, v230, v227
	v_fma_f32 v0, v229, v0, v220
	v_fma_f32 v1, v229, v1, v221
	v_fma_f32 v2, v229, v2, v222
	v_fma_f32 v3, v229, v3, v223
	v_fma_f32 v4, v229, v4, v224
	v_fma_f32 v5, v229, v5, v225
	v_fma_f32 v6, v229, v6, v226
	v_fma_f32 v7, v229, v7, v227
	s_add_i32 s13, s13, s10
	s_cmp_eq_u32 s13, s11
	s_cselect_b32 s13, s8, s13
	v_cvt_pk_bf16_f32 v216, v0, v1
	v_cvt_pk_bf16_f32 v217, v2, v3
	v_cvt_pk_bf16_f32 v218, v4, v5
	v_cvt_pk_bf16_f32 v219, v6, v7
	s_lshl_b32 s14, s13, 15
	s_add_u32 s16, s66, s14
	s_addc_u32 s17, s67, 0
	global_store_dwordx4 v236, v[216:219], s[16:17]
	v_readlane_b32 s18, v232, 23
	v_readlane_b32 s19, v233, 23
	s_nop 1
	v_add_f32_e32 v231, s18, v228
	v_max_f32_e32 v228, s19, v231
	v_sub_f32_e32 v231, v231, v228
	v_sub_f32_e32 v229, s19, v228
	v_mul_f32_e32 v231, 0x3fb8aa3b, v231
	v_mul_f32_e32 v229, 0x3fb8aa3b, v229
	v_exp_f32_e32 v230, v229
	v_exp_f32_e32 v229, v231
	s_nop 0
	v_lshlrev_b32_e32 v220, 16, v100
	v_and_b32_e32 v221, 0xffff0000, v100
	v_lshlrev_b32_e32 v222, 16, v101
	v_and_b32_e32 v223, 0xffff0000, v101
	v_lshlrev_b32_e32 v224, 16, v102
	v_and_b32_e32 v225, 0xffff0000, v102
	v_lshlrev_b32_e32 v226, 16, v103
	v_and_b32_e32 v227, 0xffff0000, v103
	v_mul_f32_e32 v220, v230, v220
	v_mul_f32_e32 v221, v230, v221
	v_mul_f32_e32 v222, v230, v222
	v_mul_f32_e32 v223, v230, v223
	v_mul_f32_e32 v224, v230, v224
	v_mul_f32_e32 v225, v230, v225
	v_mul_f32_e32 v226, v230, v226
	v_mul_f32_e32 v227, v230, v227
	v_fma_f32 v0, v229, v0, v220
	v_fma_f32 v1, v229, v1, v221
	v_fma_f32 v2, v229, v2, v222
	v_fma_f32 v3, v229, v3, v223
	v_fma_f32 v4, v229, v4, v224
	v_fma_f32 v5, v229, v5, v225
	v_fma_f32 v6, v229, v6, v226
	v_fma_f32 v7, v229, v7, v227
	s_add_i32 s13, s13, s10
	s_cmp_eq_u32 s13, s11
	s_cselect_b32 s13, s8, s13
	v_cvt_pk_bf16_f32 v216, v0, v1
	v_cvt_pk_bf16_f32 v217, v2, v3
	v_cvt_pk_bf16_f32 v218, v4, v5
	v_cvt_pk_bf16_f32 v219, v6, v7
	s_lshl_b32 s14, s13, 15
	s_add_u32 s16, s66, s14
	s_addc_u32 s17, s67, 0
	global_store_dwordx4 v236, v[216:219], s[16:17]
	v_readlane_b32 s18, v232, 24
	v_readlane_b32 s19, v233, 24
	s_nop 1
	v_add_f32_e32 v231, s18, v228
	v_max_f32_e32 v228, s19, v231
	v_sub_f32_e32 v231, v231, v228
	v_sub_f32_e32 v229, s19, v228
	v_mul_f32_e32 v231, 0x3fb8aa3b, v231
	v_mul_f32_e32 v229, 0x3fb8aa3b, v229
	v_exp_f32_e32 v230, v229
	v_exp_f32_e32 v229, v231
	s_nop 0
	v_lshlrev_b32_e32 v220, 16, v104
	v_and_b32_e32 v221, 0xffff0000, v104
	v_lshlrev_b32_e32 v222, 16, v105
	v_and_b32_e32 v223, 0xffff0000, v105
	v_lshlrev_b32_e32 v224, 16, v106
	v_and_b32_e32 v225, 0xffff0000, v106
	v_lshlrev_b32_e32 v226, 16, v107
	v_and_b32_e32 v227, 0xffff0000, v107
	v_mul_f32_e32 v220, v230, v220
	v_mul_f32_e32 v221, v230, v221
	v_mul_f32_e32 v222, v230, v222
	v_mul_f32_e32 v223, v230, v223
	v_mul_f32_e32 v224, v230, v224
	v_mul_f32_e32 v225, v230, v225
	v_mul_f32_e32 v226, v230, v226
	v_mul_f32_e32 v227, v230, v227
	v_fma_f32 v0, v229, v0, v220
	v_fma_f32 v1, v229, v1, v221
	v_fma_f32 v2, v229, v2, v222
	v_fma_f32 v3, v229, v3, v223
	v_fma_f32 v4, v229, v4, v224
	v_fma_f32 v5, v229, v5, v225
	v_fma_f32 v6, v229, v6, v226
	v_fma_f32 v7, v229, v7, v227
	s_add_i32 s13, s13, s10
	s_cmp_eq_u32 s13, s11
	s_cselect_b32 s13, s8, s13
	v_cvt_pk_bf16_f32 v216, v0, v1
	v_cvt_pk_bf16_f32 v217, v2, v3
	v_cvt_pk_bf16_f32 v218, v4, v5
	v_cvt_pk_bf16_f32 v219, v6, v7
	s_lshl_b32 s14, s13, 15
	s_add_u32 s16, s66, s14
	s_addc_u32 s17, s67, 0
	global_store_dwordx4 v236, v[216:219], s[16:17]
	v_readlane_b32 s18, v232, 25
	v_readlane_b32 s19, v233, 25
	s_nop 1
	v_add_f32_e32 v231, s18, v228
	v_max_f32_e32 v228, s19, v231
	v_sub_f32_e32 v231, v231, v228
	v_sub_f32_e32 v229, s19, v228
	v_mul_f32_e32 v231, 0x3fb8aa3b, v231
	v_mul_f32_e32 v229, 0x3fb8aa3b, v229
	v_exp_f32_e32 v230, v229
	v_exp_f32_e32 v229, v231
	s_nop 0
	v_lshlrev_b32_e32 v220, 16, v108
	v_and_b32_e32 v221, 0xffff0000, v108
	v_lshlrev_b32_e32 v222, 16, v109
	v_and_b32_e32 v223, 0xffff0000, v109
	v_lshlrev_b32_e32 v224, 16, v110
	v_and_b32_e32 v225, 0xffff0000, v110
	v_lshlrev_b32_e32 v226, 16, v111
	v_and_b32_e32 v227, 0xffff0000, v111
	v_mul_f32_e32 v220, v230, v220
	v_mul_f32_e32 v221, v230, v221
	v_mul_f32_e32 v222, v230, v222
	v_mul_f32_e32 v223, v230, v223
	v_mul_f32_e32 v224, v230, v224
	v_mul_f32_e32 v225, v230, v225
	v_mul_f32_e32 v226, v230, v226
	v_mul_f32_e32 v227, v230, v227
	v_fma_f32 v0, v229, v0, v220
	v_fma_f32 v1, v229, v1, v221
	v_fma_f32 v2, v229, v2, v222
	v_fma_f32 v3, v229, v3, v223
	v_fma_f32 v4, v229, v4, v224
	v_fma_f32 v5, v229, v5, v225
	v_fma_f32 v6, v229, v6, v226
	v_fma_f32 v7, v229, v7, v227
	s_add_i32 s13, s13, s10
	s_cmp_eq_u32 s13, s11
	s_cselect_b32 s13, s8, s13
	v_cvt_pk_bf16_f32 v216, v0, v1
	v_cvt_pk_bf16_f32 v217, v2, v3
	v_cvt_pk_bf16_f32 v218, v4, v5
	v_cvt_pk_bf16_f32 v219, v6, v7
	s_lshl_b32 s14, s13, 15
	s_add_u32 s16, s66, s14
	s_addc_u32 s17, s67, 0
	global_store_dwordx4 v236, v[216:219], s[16:17]
	v_readlane_b32 s18, v232, 26
	v_readlane_b32 s19, v233, 26
	s_nop 1
	v_add_f32_e32 v231, s18, v228
	v_max_f32_e32 v228, s19, v231
	v_sub_f32_e32 v231, v231, v228
	v_sub_f32_e32 v229, s19, v228
	v_mul_f32_e32 v231, 0x3fb8aa3b, v231
	v_mul_f32_e32 v229, 0x3fb8aa3b, v229
	v_exp_f32_e32 v230, v229
	v_exp_f32_e32 v229, v231
	s_nop 0
	v_lshlrev_b32_e32 v220, 16, v112
	v_and_b32_e32 v221, 0xffff0000, v112
	v_lshlrev_b32_e32 v222, 16, v113
	v_and_b32_e32 v223, 0xffff0000, v113
	v_lshlrev_b32_e32 v224, 16, v114
	v_and_b32_e32 v225, 0xffff0000, v114
	v_lshlrev_b32_e32 v226, 16, v115
	v_and_b32_e32 v227, 0xffff0000, v115
	v_mul_f32_e32 v220, v230, v220
	v_mul_f32_e32 v221, v230, v221
	v_mul_f32_e32 v222, v230, v222
	v_mul_f32_e32 v223, v230, v223
	v_mul_f32_e32 v224, v230, v224
	v_mul_f32_e32 v225, v230, v225
	v_mul_f32_e32 v226, v230, v226
	v_mul_f32_e32 v227, v230, v227
	v_fma_f32 v0, v229, v0, v220
	v_fma_f32 v1, v229, v1, v221
	v_fma_f32 v2, v229, v2, v222
	v_fma_f32 v3, v229, v3, v223
	v_fma_f32 v4, v229, v4, v224
	v_fma_f32 v5, v229, v5, v225
	v_fma_f32 v6, v229, v6, v226
	v_fma_f32 v7, v229, v7, v227
	s_add_i32 s13, s13, s10
	s_cmp_eq_u32 s13, s11
	s_cselect_b32 s13, s8, s13
	v_cvt_pk_bf16_f32 v216, v0, v1
	v_cvt_pk_bf16_f32 v217, v2, v3
	v_cvt_pk_bf16_f32 v218, v4, v5
	v_cvt_pk_bf16_f32 v219, v6, v7
	s_lshl_b32 s14, s13, 15
	s_add_u32 s16, s66, s14
	s_addc_u32 s17, s67, 0
	global_store_dwordx4 v236, v[216:219], s[16:17]
	v_readlane_b32 s18, v232, 27
	v_readlane_b32 s19, v233, 27
	s_nop 1
	v_add_f32_e32 v231, s18, v228
	v_max_f32_e32 v228, s19, v231
	v_sub_f32_e32 v231, v231, v228
	v_sub_f32_e32 v229, s19, v228
	v_mul_f32_e32 v231, 0x3fb8aa3b, v231
	v_mul_f32_e32 v229, 0x3fb8aa3b, v229
	v_exp_f32_e32 v230, v229
	v_exp_f32_e32 v229, v231
	s_nop 0
	v_lshlrev_b32_e32 v220, 16, v116
	v_and_b32_e32 v221, 0xffff0000, v116
	v_lshlrev_b32_e32 v222, 16, v117
	v_and_b32_e32 v223, 0xffff0000, v117
	v_lshlrev_b32_e32 v224, 16, v118
	v_and_b32_e32 v225, 0xffff0000, v118
	v_lshlrev_b32_e32 v226, 16, v119
	v_and_b32_e32 v227, 0xffff0000, v119
	v_mul_f32_e32 v220, v230, v220
	v_mul_f32_e32 v221, v230, v221
	v_mul_f32_e32 v222, v230, v222
	v_mul_f32_e32 v223, v230, v223
	v_mul_f32_e32 v224, v230, v224
	v_mul_f32_e32 v225, v230, v225
	v_mul_f32_e32 v226, v230, v226
	v_mul_f32_e32 v227, v230, v227
	v_fma_f32 v0, v229, v0, v220
	v_fma_f32 v1, v229, v1, v221
	v_fma_f32 v2, v229, v2, v222
	v_fma_f32 v3, v229, v3, v223
	v_fma_f32 v4, v229, v4, v224
	v_fma_f32 v5, v229, v5, v225
	v_fma_f32 v6, v229, v6, v226
	v_fma_f32 v7, v229, v7, v227
	s_add_i32 s13, s13, s10
	s_cmp_eq_u32 s13, s11
	s_cselect_b32 s13, s8, s13
	v_cvt_pk_bf16_f32 v216, v0, v1
	v_cvt_pk_bf16_f32 v217, v2, v3
	v_cvt_pk_bf16_f32 v218, v4, v5
	v_cvt_pk_bf16_f32 v219, v6, v7
	s_lshl_b32 s14, s13, 15
	s_add_u32 s16, s66, s14
	s_addc_u32 s17, s67, 0
	global_store_dwordx4 v236, v[216:219], s[16:17]
	v_readlane_b32 s18, v232, 28
	v_readlane_b32 s19, v233, 28
	s_nop 1
	v_add_f32_e32 v231, s18, v228
	v_max_f32_e32 v228, s19, v231
	v_sub_f32_e32 v231, v231, v228
	v_sub_f32_e32 v229, s19, v228
	v_mul_f32_e32 v231, 0x3fb8aa3b, v231
	v_mul_f32_e32 v229, 0x3fb8aa3b, v229
	v_exp_f32_e32 v230, v229
	v_exp_f32_e32 v229, v231
	s_nop 0
	v_lshlrev_b32_e32 v220, 16, v120
	v_and_b32_e32 v221, 0xffff0000, v120
	v_lshlrev_b32_e32 v222, 16, v121
	v_and_b32_e32 v223, 0xffff0000, v121
	v_lshlrev_b32_e32 v224, 16, v122
	v_and_b32_e32 v225, 0xffff0000, v122
	v_lshlrev_b32_e32 v226, 16, v123
	v_and_b32_e32 v227, 0xffff0000, v123
	v_mul_f32_e32 v220, v230, v220
	v_mul_f32_e32 v221, v230, v221
	v_mul_f32_e32 v222, v230, v222
	v_mul_f32_e32 v223, v230, v223
	v_mul_f32_e32 v224, v230, v224
	v_mul_f32_e32 v225, v230, v225
	v_mul_f32_e32 v226, v230, v226
	v_mul_f32_e32 v227, v230, v227
	v_fma_f32 v0, v229, v0, v220
	v_fma_f32 v1, v229, v1, v221
	v_fma_f32 v2, v229, v2, v222
	v_fma_f32 v3, v229, v3, v223
	v_fma_f32 v4, v229, v4, v224
	v_fma_f32 v5, v229, v5, v225
	v_fma_f32 v6, v229, v6, v226
	v_fma_f32 v7, v229, v7, v227
	s_add_i32 s13, s13, s10
	s_cmp_eq_u32 s13, s11
	s_cselect_b32 s13, s8, s13
	v_cvt_pk_bf16_f32 v216, v0, v1
	v_cvt_pk_bf16_f32 v217, v2, v3
	v_cvt_pk_bf16_f32 v218, v4, v5
	v_cvt_pk_bf16_f32 v219, v6, v7
	s_lshl_b32 s14, s13, 15
	s_add_u32 s16, s66, s14
	s_addc_u32 s17, s67, 0
	global_store_dwordx4 v236, v[216:219], s[16:17]
	v_readlane_b32 s18, v232, 29
	v_readlane_b32 s19, v233, 29
	s_nop 1
	v_add_f32_e32 v231, s18, v228
	v_max_f32_e32 v228, s19, v231
	v_sub_f32_e32 v231, v231, v228
	v_sub_f32_e32 v229, s19, v228
	v_mul_f32_e32 v231, 0x3fb8aa3b, v231
	v_mul_f32_e32 v229, 0x3fb8aa3b, v229
	v_exp_f32_e32 v230, v229
	v_exp_f32_e32 v229, v231
	s_nop 0
	v_lshlrev_b32_e32 v220, 16, v124
	v_and_b32_e32 v221, 0xffff0000, v124
	v_lshlrev_b32_e32 v222, 16, v125
	v_and_b32_e32 v223, 0xffff0000, v125
	v_lshlrev_b32_e32 v224, 16, v126
	v_and_b32_e32 v225, 0xffff0000, v126
	v_lshlrev_b32_e32 v226, 16, v127
	v_and_b32_e32 v227, 0xffff0000, v127
	v_mul_f32_e32 v220, v230, v220
	v_mul_f32_e32 v221, v230, v221
	v_mul_f32_e32 v222, v230, v222
	v_mul_f32_e32 v223, v230, v223
	v_mul_f32_e32 v224, v230, v224
	v_mul_f32_e32 v225, v230, v225
	v_mul_f32_e32 v226, v230, v226
	v_mul_f32_e32 v227, v230, v227
	v_fma_f32 v0, v229, v0, v220
	v_fma_f32 v1, v229, v1, v221
	v_fma_f32 v2, v229, v2, v222
	v_fma_f32 v3, v229, v3, v223
	v_fma_f32 v4, v229, v4, v224
	v_fma_f32 v5, v229, v5, v225
	v_fma_f32 v6, v229, v6, v226
	v_fma_f32 v7, v229, v7, v227
	s_add_i32 s13, s13, s10
	s_cmp_eq_u32 s13, s11
	s_cselect_b32 s13, s8, s13
	v_cvt_pk_bf16_f32 v216, v0, v1
	v_cvt_pk_bf16_f32 v217, v2, v3
	v_cvt_pk_bf16_f32 v218, v4, v5
	v_cvt_pk_bf16_f32 v219, v6, v7
	s_lshl_b32 s14, s13, 15
	s_add_u32 s16, s66, s14
	s_addc_u32 s17, s67, 0
	global_store_dwordx4 v236, v[216:219], s[16:17]
	v_readlane_b32 s18, v232, 30
	v_readlane_b32 s19, v233, 30
	s_nop 1
	v_add_f32_e32 v231, s18, v228
	v_max_f32_e32 v228, s19, v231
	v_sub_f32_e32 v231, v231, v228
	v_sub_f32_e32 v229, s19, v228
	v_mul_f32_e32 v231, 0x3fb8aa3b, v231
	v_mul_f32_e32 v229, 0x3fb8aa3b, v229
	v_exp_f32_e32 v230, v229
	v_exp_f32_e32 v229, v231
	s_nop 0
	v_lshlrev_b32_e32 v220, 16, v130
	v_and_b32_e32 v221, 0xffff0000, v130
	v_lshlrev_b32_e32 v222, 16, v131
	v_and_b32_e32 v223, 0xffff0000, v131
	v_lshlrev_b32_e32 v224, 16, v132
	v_and_b32_e32 v225, 0xffff0000, v132
	v_lshlrev_b32_e32 v226, 16, v133
	v_and_b32_e32 v227, 0xffff0000, v133
	v_mul_f32_e32 v220, v230, v220
	v_mul_f32_e32 v221, v230, v221
	v_mul_f32_e32 v222, v230, v222
	v_mul_f32_e32 v223, v230, v223
	v_mul_f32_e32 v224, v230, v224
	v_mul_f32_e32 v225, v230, v225
	v_mul_f32_e32 v226, v230, v226
	v_mul_f32_e32 v227, v230, v227
	v_fma_f32 v0, v229, v0, v220
	v_fma_f32 v1, v229, v1, v221
	v_fma_f32 v2, v229, v2, v222
	v_fma_f32 v3, v229, v3, v223
	v_fma_f32 v4, v229, v4, v224
	v_fma_f32 v5, v229, v5, v225
	v_fma_f32 v6, v229, v6, v226
	v_fma_f32 v7, v229, v7, v227
	s_add_i32 s13, s13, s10
	s_cmp_eq_u32 s13, s11
	s_cselect_b32 s13, s8, s13
	v_cvt_pk_bf16_f32 v216, v0, v1
	v_cvt_pk_bf16_f32 v217, v2, v3
	v_cvt_pk_bf16_f32 v218, v4, v5
	v_cvt_pk_bf16_f32 v219, v6, v7
	s_lshl_b32 s14, s13, 15
	s_add_u32 s16, s66, s14
	s_addc_u32 s17, s67, 0
	global_store_dwordx4 v236, v[216:219], s[16:17]
	v_readlane_b32 s18, v232, 31
	v_readlane_b32 s19, v233, 31
	s_nop 1
	v_add_f32_e32 v231, s18, v228
	v_max_f32_e32 v228, s19, v231
	v_sub_f32_e32 v231, v231, v228
	v_sub_f32_e32 v229, s19, v228
	v_mul_f32_e32 v231, 0x3fb8aa3b, v231
	v_mul_f32_e32 v229, 0x3fb8aa3b, v229
	v_exp_f32_e32 v230, v229
	v_exp_f32_e32 v229, v231
	s_nop 0
	v_lshlrev_b32_e32 v220, 16, v134
	v_and_b32_e32 v221, 0xffff0000, v134
	v_lshlrev_b32_e32 v222, 16, v135
	v_and_b32_e32 v223, 0xffff0000, v135
	v_lshlrev_b32_e32 v224, 16, v136
	v_and_b32_e32 v225, 0xffff0000, v136
	v_lshlrev_b32_e32 v226, 16, v137
	v_and_b32_e32 v227, 0xffff0000, v137
	v_mul_f32_e32 v220, v230, v220
	v_mul_f32_e32 v221, v230, v221
	v_mul_f32_e32 v222, v230, v222
	v_mul_f32_e32 v223, v230, v223
	v_mul_f32_e32 v224, v230, v224
	v_mul_f32_e32 v225, v230, v225
	v_mul_f32_e32 v226, v230, v226
	v_mul_f32_e32 v227, v230, v227
	v_fma_f32 v0, v229, v0, v220
	v_fma_f32 v1, v229, v1, v221
	v_fma_f32 v2, v229, v2, v222
	v_fma_f32 v3, v229, v3, v223
	v_fma_f32 v4, v229, v4, v224
	v_fma_f32 v5, v229, v5, v225
	v_fma_f32 v6, v229, v6, v226
	v_fma_f32 v7, v229, v7, v227
	s_add_i32 s13, s13, s10
	s_cmp_eq_u32 s13, s11
	s_cselect_b32 s13, s8, s13
	v_cvt_pk_bf16_f32 v216, v0, v1
	v_cvt_pk_bf16_f32 v217, v2, v3
	v_cvt_pk_bf16_f32 v218, v4, v5
	v_cvt_pk_bf16_f32 v219, v6, v7
	s_lshl_b32 s14, s13, 15
	s_add_u32 s16, s66, s14
	s_addc_u32 s17, s67, 0
	global_store_dwordx4 v236, v[216:219], s[16:17]
	v_readlane_b32 s18, v232, 32
	v_readlane_b32 s19, v233, 32
	s_nop 1
	v_add_f32_e32 v231, s18, v228
	v_max_f32_e32 v228, s19, v231
	v_sub_f32_e32 v231, v231, v228
	v_sub_f32_e32 v229, s19, v228
	v_mul_f32_e32 v231, 0x3fb8aa3b, v231
	v_mul_f32_e32 v229, 0x3fb8aa3b, v229
	v_exp_f32_e32 v230, v229
	v_exp_f32_e32 v229, v231
	s_nop 0
	v_lshlrev_b32_e32 v220, 16, v138
	v_and_b32_e32 v221, 0xffff0000, v138
	v_lshlrev_b32_e32 v222, 16, v139
	v_and_b32_e32 v223, 0xffff0000, v139
	v_lshlrev_b32_e32 v224, 16, v140
	v_and_b32_e32 v225, 0xffff0000, v140
	v_lshlrev_b32_e32 v226, 16, v141
	v_and_b32_e32 v227, 0xffff0000, v141
	v_mul_f32_e32 v220, v230, v220
	v_mul_f32_e32 v221, v230, v221
	v_mul_f32_e32 v222, v230, v222
	v_mul_f32_e32 v223, v230, v223
	v_mul_f32_e32 v224, v230, v224
	v_mul_f32_e32 v225, v230, v225
	v_mul_f32_e32 v226, v230, v226
	v_mul_f32_e32 v227, v230, v227
	v_fma_f32 v0, v229, v0, v220
	v_fma_f32 v1, v229, v1, v221
	v_fma_f32 v2, v229, v2, v222
	v_fma_f32 v3, v229, v3, v223
	v_fma_f32 v4, v229, v4, v224
	v_fma_f32 v5, v229, v5, v225
	v_fma_f32 v6, v229, v6, v226
	v_fma_f32 v7, v229, v7, v227
	s_add_i32 s13, s13, s10
	s_cmp_eq_u32 s13, s11
	s_cselect_b32 s13, s8, s13
	v_cvt_pk_bf16_f32 v216, v0, v1
	v_cvt_pk_bf16_f32 v217, v2, v3
	v_cvt_pk_bf16_f32 v218, v4, v5
	v_cvt_pk_bf16_f32 v219, v6, v7
	s_lshl_b32 s14, s13, 15
	s_add_u32 s16, s66, s14
	s_addc_u32 s17, s67, 0
	global_store_dwordx4 v236, v[216:219], s[16:17]
	v_readlane_b32 s18, v232, 33
	v_readlane_b32 s19, v233, 33
	s_nop 1
	v_add_f32_e32 v231, s18, v228
	v_max_f32_e32 v228, s19, v231
	v_sub_f32_e32 v231, v231, v228
	v_sub_f32_e32 v229, s19, v228
	v_mul_f32_e32 v231, 0x3fb8aa3b, v231
	v_mul_f32_e32 v229, 0x3fb8aa3b, v229
	v_exp_f32_e32 v230, v229
	v_exp_f32_e32 v229, v231
	s_nop 0
	v_lshlrev_b32_e32 v220, 16, v142
	v_and_b32_e32 v221, 0xffff0000, v142
	v_lshlrev_b32_e32 v222, 16, v143
	v_and_b32_e32 v223, 0xffff0000, v143
	v_lshlrev_b32_e32 v224, 16, v144
	v_and_b32_e32 v225, 0xffff0000, v144
	v_lshlrev_b32_e32 v226, 16, v145
	v_and_b32_e32 v227, 0xffff0000, v145
	v_mul_f32_e32 v220, v230, v220
	v_mul_f32_e32 v221, v230, v221
	v_mul_f32_e32 v222, v230, v222
	v_mul_f32_e32 v223, v230, v223
	v_mul_f32_e32 v224, v230, v224
	v_mul_f32_e32 v225, v230, v225
	v_mul_f32_e32 v226, v230, v226
	v_mul_f32_e32 v227, v230, v227
	v_fma_f32 v0, v229, v0, v220
	v_fma_f32 v1, v229, v1, v221
	v_fma_f32 v2, v229, v2, v222
	v_fma_f32 v3, v229, v3, v223
	v_fma_f32 v4, v229, v4, v224
	v_fma_f32 v5, v229, v5, v225
	v_fma_f32 v6, v229, v6, v226
	v_fma_f32 v7, v229, v7, v227
	s_add_i32 s13, s13, s10
	s_cmp_eq_u32 s13, s11
	s_cselect_b32 s13, s8, s13
	v_cvt_pk_bf16_f32 v216, v0, v1
	v_cvt_pk_bf16_f32 v217, v2, v3
	v_cvt_pk_bf16_f32 v218, v4, v5
	v_cvt_pk_bf16_f32 v219, v6, v7
	s_lshl_b32 s14, s13, 15
	s_add_u32 s16, s66, s14
	s_addc_u32 s17, s67, 0
	global_store_dwordx4 v236, v[216:219], s[16:17]
	v_readlane_b32 s18, v232, 34
	v_readlane_b32 s19, v233, 34
	s_nop 1
	v_add_f32_e32 v231, s18, v228
	v_max_f32_e32 v228, s19, v231
	v_sub_f32_e32 v231, v231, v228
	v_sub_f32_e32 v229, s19, v228
	v_mul_f32_e32 v231, 0x3fb8aa3b, v231
	v_mul_f32_e32 v229, 0x3fb8aa3b, v229
	v_exp_f32_e32 v230, v229
	v_exp_f32_e32 v229, v231
	s_nop 0
	v_lshlrev_b32_e32 v220, 16, v146
	v_and_b32_e32 v221, 0xffff0000, v146
	v_lshlrev_b32_e32 v222, 16, v147
	v_and_b32_e32 v223, 0xffff0000, v147
	v_lshlrev_b32_e32 v224, 16, v148
	v_and_b32_e32 v225, 0xffff0000, v148
	v_lshlrev_b32_e32 v226, 16, v149
	v_and_b32_e32 v227, 0xffff0000, v149
	v_mul_f32_e32 v220, v230, v220
	v_mul_f32_e32 v221, v230, v221
	v_mul_f32_e32 v222, v230, v222
	v_mul_f32_e32 v223, v230, v223
	v_mul_f32_e32 v224, v230, v224
	v_mul_f32_e32 v225, v230, v225
	v_mul_f32_e32 v226, v230, v226
	v_mul_f32_e32 v227, v230, v227
	v_fma_f32 v0, v229, v0, v220
	v_fma_f32 v1, v229, v1, v221
	v_fma_f32 v2, v229, v2, v222
	v_fma_f32 v3, v229, v3, v223
	v_fma_f32 v4, v229, v4, v224
	v_fma_f32 v5, v229, v5, v225
	v_fma_f32 v6, v229, v6, v226
	v_fma_f32 v7, v229, v7, v227
	s_add_i32 s13, s13, s10
	s_cmp_eq_u32 s13, s11
	s_cselect_b32 s13, s8, s13
	v_cvt_pk_bf16_f32 v216, v0, v1
	v_cvt_pk_bf16_f32 v217, v2, v3
	v_cvt_pk_bf16_f32 v218, v4, v5
	v_cvt_pk_bf16_f32 v219, v6, v7
	s_lshl_b32 s14, s13, 15
	s_add_u32 s16, s66, s14
	s_addc_u32 s17, s67, 0
	global_store_dwordx4 v236, v[216:219], s[16:17]
	v_readlane_b32 s18, v232, 35
	v_readlane_b32 s19, v233, 35
	s_nop 1
	v_add_f32_e32 v231, s18, v228
	v_max_f32_e32 v228, s19, v231
	v_sub_f32_e32 v231, v231, v228
	v_sub_f32_e32 v229, s19, v228
	v_mul_f32_e32 v231, 0x3fb8aa3b, v231
	v_mul_f32_e32 v229, 0x3fb8aa3b, v229
	v_exp_f32_e32 v230, v229
	v_exp_f32_e32 v229, v231
	s_nop 0
	v_lshlrev_b32_e32 v220, 16, v150
	v_and_b32_e32 v221, 0xffff0000, v150
	v_lshlrev_b32_e32 v222, 16, v151
	v_and_b32_e32 v223, 0xffff0000, v151
	v_lshlrev_b32_e32 v224, 16, v152
	v_and_b32_e32 v225, 0xffff0000, v152
	v_lshlrev_b32_e32 v226, 16, v153
	v_and_b32_e32 v227, 0xffff0000, v153
	v_mul_f32_e32 v220, v230, v220
	v_mul_f32_e32 v221, v230, v221
	v_mul_f32_e32 v222, v230, v222
	v_mul_f32_e32 v223, v230, v223
	v_mul_f32_e32 v224, v230, v224
	v_mul_f32_e32 v225, v230, v225
	v_mul_f32_e32 v226, v230, v226
	v_mul_f32_e32 v227, v230, v227
	v_fma_f32 v0, v229, v0, v220
	v_fma_f32 v1, v229, v1, v221
	v_fma_f32 v2, v229, v2, v222
	v_fma_f32 v3, v229, v3, v223
	v_fma_f32 v4, v229, v4, v224
	v_fma_f32 v5, v229, v5, v225
	v_fma_f32 v6, v229, v6, v226
	v_fma_f32 v7, v229, v7, v227
	s_add_i32 s13, s13, s10
	s_cmp_eq_u32 s13, s11
	s_cselect_b32 s13, s8, s13
	v_cvt_pk_bf16_f32 v216, v0, v1
	v_cvt_pk_bf16_f32 v217, v2, v3
	v_cvt_pk_bf16_f32 v218, v4, v5
	v_cvt_pk_bf16_f32 v219, v6, v7
	s_lshl_b32 s14, s13, 15
	s_add_u32 s16, s66, s14
	s_addc_u32 s17, s67, 0
	global_store_dwordx4 v236, v[216:219], s[16:17]
	v_readlane_b32 s18, v232, 36
	v_readlane_b32 s19, v233, 36
	s_nop 1
	v_add_f32_e32 v231, s18, v228
	v_max_f32_e32 v228, s19, v231
	v_sub_f32_e32 v231, v231, v228
	v_sub_f32_e32 v229, s19, v228
	v_mul_f32_e32 v231, 0x3fb8aa3b, v231
	v_mul_f32_e32 v229, 0x3fb8aa3b, v229
	v_exp_f32_e32 v230, v229
	v_exp_f32_e32 v229, v231
	s_nop 0
	v_lshlrev_b32_e32 v220, 16, v154
	v_and_b32_e32 v221, 0xffff0000, v154
	v_lshlrev_b32_e32 v222, 16, v155
	v_and_b32_e32 v223, 0xffff0000, v155
	v_lshlrev_b32_e32 v224, 16, v156
	v_and_b32_e32 v225, 0xffff0000, v156
	v_lshlrev_b32_e32 v226, 16, v157
	v_and_b32_e32 v227, 0xffff0000, v157
	v_mul_f32_e32 v220, v230, v220
	v_mul_f32_e32 v221, v230, v221
	v_mul_f32_e32 v222, v230, v222
	v_mul_f32_e32 v223, v230, v223
	v_mul_f32_e32 v224, v230, v224
	v_mul_f32_e32 v225, v230, v225
	v_mul_f32_e32 v226, v230, v226
	v_mul_f32_e32 v227, v230, v227
	v_fma_f32 v0, v229, v0, v220
	v_fma_f32 v1, v229, v1, v221
	v_fma_f32 v2, v229, v2, v222
	v_fma_f32 v3, v229, v3, v223
	v_fma_f32 v4, v229, v4, v224
	v_fma_f32 v5, v229, v5, v225
	v_fma_f32 v6, v229, v6, v226
	v_fma_f32 v7, v229, v7, v227
	s_add_i32 s13, s13, s10
	s_cmp_eq_u32 s13, s11
	s_cselect_b32 s13, s8, s13
	v_cvt_pk_bf16_f32 v216, v0, v1
	v_cvt_pk_bf16_f32 v217, v2, v3
	v_cvt_pk_bf16_f32 v218, v4, v5
	v_cvt_pk_bf16_f32 v219, v6, v7
	s_lshl_b32 s14, s13, 15
	s_add_u32 s16, s66, s14
	s_addc_u32 s17, s67, 0
	global_store_dwordx4 v236, v[216:219], s[16:17]
	v_readlane_b32 s18, v232, 37
	v_readlane_b32 s19, v233, 37
	s_nop 1
	v_add_f32_e32 v231, s18, v228
	v_max_f32_e32 v228, s19, v231
	v_sub_f32_e32 v231, v231, v228
	v_sub_f32_e32 v229, s19, v228
	v_mul_f32_e32 v231, 0x3fb8aa3b, v231
	v_mul_f32_e32 v229, 0x3fb8aa3b, v229
	v_exp_f32_e32 v230, v229
	v_exp_f32_e32 v229, v231
	s_nop 0
	v_lshlrev_b32_e32 v220, 16, v158
	v_and_b32_e32 v221, 0xffff0000, v158
	v_lshlrev_b32_e32 v222, 16, v159
	v_and_b32_e32 v223, 0xffff0000, v159
	v_lshlrev_b32_e32 v224, 16, v160
	v_and_b32_e32 v225, 0xffff0000, v160
	v_lshlrev_b32_e32 v226, 16, v161
	v_and_b32_e32 v227, 0xffff0000, v161
	v_mul_f32_e32 v220, v230, v220
	v_mul_f32_e32 v221, v230, v221
	v_mul_f32_e32 v222, v230, v222
	v_mul_f32_e32 v223, v230, v223
	v_mul_f32_e32 v224, v230, v224
	v_mul_f32_e32 v225, v230, v225
	v_mul_f32_e32 v226, v230, v226
	v_mul_f32_e32 v227, v230, v227
	v_fma_f32 v0, v229, v0, v220
	v_fma_f32 v1, v229, v1, v221
	v_fma_f32 v2, v229, v2, v222
	v_fma_f32 v3, v229, v3, v223
	v_fma_f32 v4, v229, v4, v224
	v_fma_f32 v5, v229, v5, v225
	v_fma_f32 v6, v229, v6, v226
	v_fma_f32 v7, v229, v7, v227
	s_add_i32 s13, s13, s10
	s_cmp_eq_u32 s13, s11
	s_cselect_b32 s13, s8, s13
	v_cvt_pk_bf16_f32 v216, v0, v1
	v_cvt_pk_bf16_f32 v217, v2, v3
	v_cvt_pk_bf16_f32 v218, v4, v5
	v_cvt_pk_bf16_f32 v219, v6, v7
	s_lshl_b32 s14, s13, 15
	s_add_u32 s16, s66, s14
	s_addc_u32 s17, s67, 0
	global_store_dwordx4 v236, v[216:219], s[16:17]
	v_readlane_b32 s18, v232, 38
	v_readlane_b32 s19, v233, 38
	s_nop 1
	v_add_f32_e32 v231, s18, v228
	v_max_f32_e32 v228, s19, v231
	v_sub_f32_e32 v231, v231, v228
	v_sub_f32_e32 v229, s19, v228
	v_mul_f32_e32 v231, 0x3fb8aa3b, v231
	v_mul_f32_e32 v229, 0x3fb8aa3b, v229
	v_exp_f32_e32 v230, v229
	v_exp_f32_e32 v229, v231
	s_nop 0
	v_lshlrev_b32_e32 v220, 16, v188
	v_and_b32_e32 v221, 0xffff0000, v188
	v_lshlrev_b32_e32 v222, 16, v189
	v_and_b32_e32 v223, 0xffff0000, v189
	v_lshlrev_b32_e32 v224, 16, v190
	v_and_b32_e32 v225, 0xffff0000, v190
	v_lshlrev_b32_e32 v226, 16, v191
	v_and_b32_e32 v227, 0xffff0000, v191
	v_mul_f32_e32 v220, v230, v220
	v_mul_f32_e32 v221, v230, v221
	v_mul_f32_e32 v222, v230, v222
	v_mul_f32_e32 v223, v230, v223
	v_mul_f32_e32 v224, v230, v224
	v_mul_f32_e32 v225, v230, v225
	v_mul_f32_e32 v226, v230, v226
	v_mul_f32_e32 v227, v230, v227
	v_fma_f32 v0, v229, v0, v220
	v_fma_f32 v1, v229, v1, v221
	v_fma_f32 v2, v229, v2, v222
	v_fma_f32 v3, v229, v3, v223
	v_fma_f32 v4, v229, v4, v224
	v_fma_f32 v5, v229, v5, v225
	v_fma_f32 v6, v229, v6, v226
	v_fma_f32 v7, v229, v7, v227
	s_add_i32 s13, s13, s10
	s_cmp_eq_u32 s13, s11
	s_cselect_b32 s13, s8, s13
	v_cvt_pk_bf16_f32 v216, v0, v1
	v_cvt_pk_bf16_f32 v217, v2, v3
	v_cvt_pk_bf16_f32 v218, v4, v5
	v_cvt_pk_bf16_f32 v219, v6, v7
	s_lshl_b32 s14, s13, 15
	s_add_u32 s16, s66, s14
	s_addc_u32 s17, s67, 0
	global_store_dwordx4 v236, v[216:219], s[16:17]
	v_readlane_b32 s18, v232, 39
	v_readlane_b32 s19, v233, 39
	s_nop 1
	v_add_f32_e32 v231, s18, v228
	v_max_f32_e32 v228, s19, v231
	v_sub_f32_e32 v231, v231, v228
	v_sub_f32_e32 v229, s19, v228
	v_mul_f32_e32 v231, 0x3fb8aa3b, v231
	v_mul_f32_e32 v229, 0x3fb8aa3b, v229
	v_exp_f32_e32 v230, v229
	v_exp_f32_e32 v229, v231
	s_nop 0
	v_lshlrev_b32_e32 v220, 16, v192
	v_and_b32_e32 v221, 0xffff0000, v192
	v_lshlrev_b32_e32 v222, 16, v193
	v_and_b32_e32 v223, 0xffff0000, v193
	v_lshlrev_b32_e32 v224, 16, v194
	v_and_b32_e32 v225, 0xffff0000, v194
	v_lshlrev_b32_e32 v226, 16, v195
	v_and_b32_e32 v227, 0xffff0000, v195
	v_mul_f32_e32 v220, v230, v220
	v_mul_f32_e32 v221, v230, v221
	v_mul_f32_e32 v222, v230, v222
	v_mul_f32_e32 v223, v230, v223
	v_mul_f32_e32 v224, v230, v224
	v_mul_f32_e32 v225, v230, v225
	v_mul_f32_e32 v226, v230, v226
	v_mul_f32_e32 v227, v230, v227
	v_fma_f32 v0, v229, v0, v220
	v_fma_f32 v1, v229, v1, v221
	v_fma_f32 v2, v229, v2, v222
	v_fma_f32 v3, v229, v3, v223
	v_fma_f32 v4, v229, v4, v224
	v_fma_f32 v5, v229, v5, v225
	v_fma_f32 v6, v229, v6, v226
	v_fma_f32 v7, v229, v7, v227
	s_add_i32 s13, s13, s10
	s_cmp_eq_u32 s13, s11
	s_cselect_b32 s13, s8, s13
	v_cvt_pk_bf16_f32 v216, v0, v1
	v_cvt_pk_bf16_f32 v217, v2, v3
	v_cvt_pk_bf16_f32 v218, v4, v5
	v_cvt_pk_bf16_f32 v219, v6, v7
	s_lshl_b32 s14, s13, 15
	s_add_u32 s16, s66, s14
	s_addc_u32 s17, s67, 0
	global_store_dwordx4 v236, v[216:219], s[16:17]
	v_readlane_b32 s18, v232, 40
	v_readlane_b32 s19, v233, 40
	s_nop 1
	v_add_f32_e32 v231, s18, v228
	v_max_f32_e32 v228, s19, v231
	v_sub_f32_e32 v231, v231, v228
	v_sub_f32_e32 v229, s19, v228
	v_mul_f32_e32 v231, 0x3fb8aa3b, v231
	v_mul_f32_e32 v229, 0x3fb8aa3b, v229
	v_exp_f32_e32 v230, v229
	v_exp_f32_e32 v229, v231
	s_nop 0
	v_lshlrev_b32_e32 v220, 16, v196
	v_and_b32_e32 v221, 0xffff0000, v196
	v_lshlrev_b32_e32 v222, 16, v197
	v_and_b32_e32 v223, 0xffff0000, v197
	v_lshlrev_b32_e32 v224, 16, v198
	v_and_b32_e32 v225, 0xffff0000, v198
	v_lshlrev_b32_e32 v226, 16, v199
	v_and_b32_e32 v227, 0xffff0000, v199
	v_mul_f32_e32 v220, v230, v220
	v_mul_f32_e32 v221, v230, v221
	v_mul_f32_e32 v222, v230, v222
	v_mul_f32_e32 v223, v230, v223
	v_mul_f32_e32 v224, v230, v224
	v_mul_f32_e32 v225, v230, v225
	v_mul_f32_e32 v226, v230, v226
	v_mul_f32_e32 v227, v230, v227
	v_fma_f32 v0, v229, v0, v220
	v_fma_f32 v1, v229, v1, v221
	v_fma_f32 v2, v229, v2, v222
	v_fma_f32 v3, v229, v3, v223
	v_fma_f32 v4, v229, v4, v224
	v_fma_f32 v5, v229, v5, v225
	v_fma_f32 v6, v229, v6, v226
	v_fma_f32 v7, v229, v7, v227
	s_add_i32 s13, s13, s10
	s_cmp_eq_u32 s13, s11
	s_cselect_b32 s13, s8, s13
	v_cvt_pk_bf16_f32 v216, v0, v1
	v_cvt_pk_bf16_f32 v217, v2, v3
	v_cvt_pk_bf16_f32 v218, v4, v5
	v_cvt_pk_bf16_f32 v219, v6, v7
	s_lshl_b32 s14, s13, 15
	s_add_u32 s16, s66, s14
	s_addc_u32 s17, s67, 0
	global_store_dwordx4 v236, v[216:219], s[16:17]
	v_readlane_b32 s18, v232, 41
	v_readlane_b32 s19, v233, 41
	s_nop 1
	v_add_f32_e32 v231, s18, v228
	v_max_f32_e32 v228, s19, v231
	v_sub_f32_e32 v231, v231, v228
	v_sub_f32_e32 v229, s19, v228
	v_mul_f32_e32 v231, 0x3fb8aa3b, v231
	v_mul_f32_e32 v229, 0x3fb8aa3b, v229
	v_exp_f32_e32 v230, v229
	v_exp_f32_e32 v229, v231
	s_nop 0
	v_lshlrev_b32_e32 v220, 16, v200
	v_and_b32_e32 v221, 0xffff0000, v200
	v_lshlrev_b32_e32 v222, 16, v201
	v_and_b32_e32 v223, 0xffff0000, v201
	v_lshlrev_b32_e32 v224, 16, v202
	v_and_b32_e32 v225, 0xffff0000, v202
	v_lshlrev_b32_e32 v226, 16, v203
	v_and_b32_e32 v227, 0xffff0000, v203
	v_mul_f32_e32 v220, v230, v220
	v_mul_f32_e32 v221, v230, v221
	v_mul_f32_e32 v222, v230, v222
	v_mul_f32_e32 v223, v230, v223
	v_mul_f32_e32 v224, v230, v224
	v_mul_f32_e32 v225, v230, v225
	v_mul_f32_e32 v226, v230, v226
	v_mul_f32_e32 v227, v230, v227
	v_fma_f32 v0, v229, v0, v220
	v_fma_f32 v1, v229, v1, v221
	v_fma_f32 v2, v229, v2, v222
	v_fma_f32 v3, v229, v3, v223
	v_fma_f32 v4, v229, v4, v224
	v_fma_f32 v5, v229, v5, v225
	v_fma_f32 v6, v229, v6, v226
	v_fma_f32 v7, v229, v7, v227
	s_add_i32 s13, s13, s10
	s_cmp_eq_u32 s13, s11
	s_cselect_b32 s13, s8, s13
	v_cvt_pk_bf16_f32 v216, v0, v1
	v_cvt_pk_bf16_f32 v217, v2, v3
	v_cvt_pk_bf16_f32 v218, v4, v5
	v_cvt_pk_bf16_f32 v219, v6, v7
	s_lshl_b32 s14, s13, 15
	s_add_u32 s16, s66, s14
	s_addc_u32 s17, s67, 0
	global_store_dwordx4 v236, v[216:219], s[16:17]
	v_readlane_b32 s18, v232, 42
	v_readlane_b32 s19, v233, 42
	s_nop 1
	v_add_f32_e32 v231, s18, v228
	v_max_f32_e32 v228, s19, v231
	v_sub_f32_e32 v231, v231, v228
	v_sub_f32_e32 v229, s19, v228
	v_mul_f32_e32 v231, 0x3fb8aa3b, v231
	v_mul_f32_e32 v229, 0x3fb8aa3b, v229
	v_exp_f32_e32 v230, v229
	v_exp_f32_e32 v229, v231
	s_nop 0
	v_lshlrev_b32_e32 v220, 16, v204
	v_and_b32_e32 v221, 0xffff0000, v204
	v_lshlrev_b32_e32 v222, 16, v205
	v_and_b32_e32 v223, 0xffff0000, v205
	v_lshlrev_b32_e32 v224, 16, v206
	v_and_b32_e32 v225, 0xffff0000, v206
	v_lshlrev_b32_e32 v226, 16, v207
	v_and_b32_e32 v227, 0xffff0000, v207
	v_mul_f32_e32 v220, v230, v220
	v_mul_f32_e32 v221, v230, v221
	v_mul_f32_e32 v222, v230, v222
	v_mul_f32_e32 v223, v230, v223
	v_mul_f32_e32 v224, v230, v224
	v_mul_f32_e32 v225, v230, v225
	v_mul_f32_e32 v226, v230, v226
	v_mul_f32_e32 v227, v230, v227
	v_fma_f32 v0, v229, v0, v220
	v_fma_f32 v1, v229, v1, v221
	v_fma_f32 v2, v229, v2, v222
	v_fma_f32 v3, v229, v3, v223
	v_fma_f32 v4, v229, v4, v224
	v_fma_f32 v5, v229, v5, v225
	v_fma_f32 v6, v229, v6, v226
	v_fma_f32 v7, v229, v7, v227
	s_add_i32 s13, s13, s10
	s_cmp_eq_u32 s13, s11
	s_cselect_b32 s13, s8, s13
	v_cvt_pk_bf16_f32 v216, v0, v1
	v_cvt_pk_bf16_f32 v217, v2, v3
	v_cvt_pk_bf16_f32 v218, v4, v5
	v_cvt_pk_bf16_f32 v219, v6, v7
	s_lshl_b32 s14, s13, 15
	s_add_u32 s16, s66, s14
	s_addc_u32 s17, s67, 0
	global_store_dwordx4 v236, v[216:219], s[16:17]
	v_readlane_b32 s18, v232, 43
	v_readlane_b32 s19, v233, 43
	s_nop 1
	v_add_f32_e32 v231, s18, v228
	v_max_f32_e32 v228, s19, v231
	v_sub_f32_e32 v231, v231, v228
	v_sub_f32_e32 v229, s19, v228
	v_mul_f32_e32 v231, 0x3fb8aa3b, v231
	v_mul_f32_e32 v229, 0x3fb8aa3b, v229
	v_exp_f32_e32 v230, v229
	v_exp_f32_e32 v229, v231
	s_nop 0
	v_lshlrev_b32_e32 v220, 16, v208
	v_and_b32_e32 v221, 0xffff0000, v208
	v_lshlrev_b32_e32 v222, 16, v209
	v_and_b32_e32 v223, 0xffff0000, v209
	v_lshlrev_b32_e32 v224, 16, v210
	v_and_b32_e32 v225, 0xffff0000, v210
	v_lshlrev_b32_e32 v226, 16, v211
	v_and_b32_e32 v227, 0xffff0000, v211
	v_mul_f32_e32 v220, v230, v220
	v_mul_f32_e32 v221, v230, v221
	v_mul_f32_e32 v222, v230, v222
	v_mul_f32_e32 v223, v230, v223
	v_mul_f32_e32 v224, v230, v224
	v_mul_f32_e32 v225, v230, v225
	v_mul_f32_e32 v226, v230, v226
	v_mul_f32_e32 v227, v230, v227
	v_fma_f32 v0, v229, v0, v220
	v_fma_f32 v1, v229, v1, v221
	v_fma_f32 v2, v229, v2, v222
	v_fma_f32 v3, v229, v3, v223
	v_fma_f32 v4, v229, v4, v224
	v_fma_f32 v5, v229, v5, v225
	v_fma_f32 v6, v229, v6, v226
	v_fma_f32 v7, v229, v7, v227
	s_add_i32 s13, s13, s10
	s_cmp_eq_u32 s13, s11
	s_cselect_b32 s13, s8, s13
	s_waitcnt vmcnt(0)
	v_cvt_pk_bf16_f32 v216, v0, v1
	v_cvt_pk_bf16_f32 v217, v2, v3
	v_cvt_pk_bf16_f32 v218, v4, v5
	v_cvt_pk_bf16_f32 v219, v6, v7
	s_lshl_b32 s14, s13, 15
	s_add_u32 s16, s66, s14
	s_addc_u32 s17, s67, 0
	global_store_dwordx4 v236, v[216:219], s[16:17]
	v_readlane_b32 s18, v232, 44
	v_readlane_b32 s19, v233, 44
	s_nop 1
	v_add_f32_e32 v231, s18, v228
	v_max_f32_e32 v228, s19, v231
	v_sub_f32_e32 v231, v231, v228
	v_sub_f32_e32 v229, s19, v228
	v_mul_f32_e32 v231, 0x3fb8aa3b, v231
	v_mul_f32_e32 v229, 0x3fb8aa3b, v229
	v_exp_f32_e32 v230, v229
	v_exp_f32_e32 v229, v231
	s_nop 0
	v_lshlrev_b32_e32 v220, 16, v8
	v_and_b32_e32 v221, 0xffff0000, v8
	v_lshlrev_b32_e32 v222, 16, v9
	v_and_b32_e32 v223, 0xffff0000, v9
	v_lshlrev_b32_e32 v224, 16, v10
	v_and_b32_e32 v225, 0xffff0000, v10
	v_lshlrev_b32_e32 v226, 16, v11
	v_and_b32_e32 v227, 0xffff0000, v11
	v_mul_f32_e32 v220, v230, v220
	v_mul_f32_e32 v221, v230, v221
	v_mul_f32_e32 v222, v230, v222
	v_mul_f32_e32 v223, v230, v223
	v_mul_f32_e32 v224, v230, v224
	v_mul_f32_e32 v225, v230, v225
	v_mul_f32_e32 v226, v230, v226
	v_mul_f32_e32 v227, v230, v227
	v_fma_f32 v0, v229, v0, v220
	v_fma_f32 v1, v229, v1, v221
	v_fma_f32 v2, v229, v2, v222
	v_fma_f32 v3, v229, v3, v223
	v_fma_f32 v4, v229, v4, v224
	v_fma_f32 v5, v229, v5, v225
	v_fma_f32 v6, v229, v6, v226
	v_fma_f32 v7, v229, v7, v227
	s_add_i32 s13, s13, s10
	s_cmp_eq_u32 s13, s11
	s_cselect_b32 s13, s8, s13
	v_cvt_pk_bf16_f32 v216, v0, v1
	v_cvt_pk_bf16_f32 v217, v2, v3
	v_cvt_pk_bf16_f32 v218, v4, v5
	v_cvt_pk_bf16_f32 v219, v6, v7
	s_lshl_b32 s14, s13, 15
	s_add_u32 s16, s66, s14
	s_addc_u32 s17, s67, 0
	global_store_dwordx4 v236, v[216:219], s[16:17]
	v_readlane_b32 s18, v232, 45
	v_readlane_b32 s19, v233, 45
	s_nop 1
	v_add_f32_e32 v231, s18, v228
	v_max_f32_e32 v228, s19, v231
	v_sub_f32_e32 v231, v231, v228
	v_sub_f32_e32 v229, s19, v228
	v_mul_f32_e32 v231, 0x3fb8aa3b, v231
	v_mul_f32_e32 v229, 0x3fb8aa3b, v229
	v_exp_f32_e32 v230, v229
	v_exp_f32_e32 v229, v231
	s_nop 0
	v_lshlrev_b32_e32 v220, 16, v12
	v_and_b32_e32 v221, 0xffff0000, v12
	v_lshlrev_b32_e32 v222, 16, v13
	v_and_b32_e32 v223, 0xffff0000, v13
	v_lshlrev_b32_e32 v224, 16, v14
	v_and_b32_e32 v225, 0xffff0000, v14
	v_lshlrev_b32_e32 v226, 16, v15
	v_and_b32_e32 v227, 0xffff0000, v15
	v_mul_f32_e32 v220, v230, v220
	v_mul_f32_e32 v221, v230, v221
	v_mul_f32_e32 v222, v230, v222
	v_mul_f32_e32 v223, v230, v223
	v_mul_f32_e32 v224, v230, v224
	v_mul_f32_e32 v225, v230, v225
	v_mul_f32_e32 v226, v230, v226
	v_mul_f32_e32 v227, v230, v227
	v_fma_f32 v0, v229, v0, v220
	v_fma_f32 v1, v229, v1, v221
	v_fma_f32 v2, v229, v2, v222
	v_fma_f32 v3, v229, v3, v223
	v_fma_f32 v4, v229, v4, v224
	v_fma_f32 v5, v229, v5, v225
	v_fma_f32 v6, v229, v6, v226
	v_fma_f32 v7, v229, v7, v227
	s_add_i32 s13, s13, s10
	s_cmp_eq_u32 s13, s11
	s_cselect_b32 s13, s8, s13
	v_cvt_pk_bf16_f32 v216, v0, v1
	v_cvt_pk_bf16_f32 v217, v2, v3
	v_cvt_pk_bf16_f32 v218, v4, v5
	v_cvt_pk_bf16_f32 v219, v6, v7
	s_lshl_b32 s14, s13, 15
	s_add_u32 s16, s66, s14
	s_addc_u32 s17, s67, 0
	global_store_dwordx4 v236, v[216:219], s[16:17]
	v_readlane_b32 s18, v232, 46
	v_readlane_b32 s19, v233, 46
	s_nop 1
	v_add_f32_e32 v231, s18, v228
	v_max_f32_e32 v228, s19, v231
	v_sub_f32_e32 v231, v231, v228
	v_sub_f32_e32 v229, s19, v228
	v_mul_f32_e32 v231, 0x3fb8aa3b, v231
	v_mul_f32_e32 v229, 0x3fb8aa3b, v229
	v_exp_f32_e32 v230, v229
	v_exp_f32_e32 v229, v231
	s_nop 0
	v_lshlrev_b32_e32 v220, 16, v16
	v_and_b32_e32 v221, 0xffff0000, v16
	v_lshlrev_b32_e32 v222, 16, v17
	v_and_b32_e32 v223, 0xffff0000, v17
	v_lshlrev_b32_e32 v224, 16, v18
	v_and_b32_e32 v225, 0xffff0000, v18
	v_lshlrev_b32_e32 v226, 16, v19
	v_and_b32_e32 v227, 0xffff0000, v19
	v_mul_f32_e32 v220, v230, v220
	v_mul_f32_e32 v221, v230, v221
	v_mul_f32_e32 v222, v230, v222
	v_mul_f32_e32 v223, v230, v223
	v_mul_f32_e32 v224, v230, v224
	v_mul_f32_e32 v225, v230, v225
	v_mul_f32_e32 v226, v230, v226
	v_mul_f32_e32 v227, v230, v227
	v_fma_f32 v0, v229, v0, v220
	v_fma_f32 v1, v229, v1, v221
	v_fma_f32 v2, v229, v2, v222
	v_fma_f32 v3, v229, v3, v223
	v_fma_f32 v4, v229, v4, v224
	v_fma_f32 v5, v229, v5, v225
	v_fma_f32 v6, v229, v6, v226
	v_fma_f32 v7, v229, v7, v227
	s_add_i32 s13, s13, s10
	s_cmp_eq_u32 s13, s11
	s_cselect_b32 s13, s8, s13
	v_cvt_pk_bf16_f32 v216, v0, v1
	v_cvt_pk_bf16_f32 v217, v2, v3
	v_cvt_pk_bf16_f32 v218, v4, v5
	v_cvt_pk_bf16_f32 v219, v6, v7
	s_lshl_b32 s14, s13, 15
	s_add_u32 s16, s66, s14
	s_addc_u32 s17, s67, 0
	global_store_dwordx4 v236, v[216:219], s[16:17]
	v_readlane_b32 s18, v232, 47
	v_readlane_b32 s19, v233, 47
	s_nop 1
	v_add_f32_e32 v231, s18, v228
	v_max_f32_e32 v228, s19, v231
	v_sub_f32_e32 v231, v231, v228
	v_sub_f32_e32 v229, s19, v228
	v_mul_f32_e32 v231, 0x3fb8aa3b, v231
	v_mul_f32_e32 v229, 0x3fb8aa3b, v229
	v_exp_f32_e32 v230, v229
	v_exp_f32_e32 v229, v231
	s_nop 0
	v_lshlrev_b32_e32 v220, 16, v20
	v_and_b32_e32 v221, 0xffff0000, v20
	v_lshlrev_b32_e32 v222, 16, v21
	v_and_b32_e32 v223, 0xffff0000, v21
	v_lshlrev_b32_e32 v224, 16, v22
	v_and_b32_e32 v225, 0xffff0000, v22
	v_lshlrev_b32_e32 v226, 16, v23
	v_and_b32_e32 v227, 0xffff0000, v23
	v_mul_f32_e32 v220, v230, v220
	v_mul_f32_e32 v221, v230, v221
	v_mul_f32_e32 v222, v230, v222
	v_mul_f32_e32 v223, v230, v223
	v_mul_f32_e32 v224, v230, v224
	v_mul_f32_e32 v225, v230, v225
	v_mul_f32_e32 v226, v230, v226
	v_mul_f32_e32 v227, v230, v227
	v_fma_f32 v0, v229, v0, v220
	v_fma_f32 v1, v229, v1, v221
	v_fma_f32 v2, v229, v2, v222
	v_fma_f32 v3, v229, v3, v223
	v_fma_f32 v4, v229, v4, v224
	v_fma_f32 v5, v229, v5, v225
	v_fma_f32 v6, v229, v6, v226
	v_fma_f32 v7, v229, v7, v227
	s_add_i32 s13, s13, s10
	s_cmp_eq_u32 s13, s11
	s_cselect_b32 s13, s8, s13
	v_cvt_pk_bf16_f32 v216, v0, v1
	v_cvt_pk_bf16_f32 v217, v2, v3
	v_cvt_pk_bf16_f32 v218, v4, v5
	v_cvt_pk_bf16_f32 v219, v6, v7
	s_lshl_b32 s14, s13, 15
	s_add_u32 s16, s66, s14
	s_addc_u32 s17, s67, 0
	global_store_dwordx4 v236, v[216:219], s[16:17]
	v_readlane_b32 s18, v232, 48
	v_readlane_b32 s19, v233, 48
	s_nop 1
	v_add_f32_e32 v231, s18, v228
	v_max_f32_e32 v228, s19, v231
	v_sub_f32_e32 v231, v231, v228
	v_sub_f32_e32 v229, s19, v228
	v_mul_f32_e32 v231, 0x3fb8aa3b, v231
	v_mul_f32_e32 v229, 0x3fb8aa3b, v229
	v_exp_f32_e32 v230, v229
	v_exp_f32_e32 v229, v231
	s_nop 0
	v_lshlrev_b32_e32 v220, 16, v24
	v_and_b32_e32 v221, 0xffff0000, v24
	v_lshlrev_b32_e32 v222, 16, v25
	v_and_b32_e32 v223, 0xffff0000, v25
	v_lshlrev_b32_e32 v224, 16, v26
	v_and_b32_e32 v225, 0xffff0000, v26
	v_lshlrev_b32_e32 v226, 16, v27
	v_and_b32_e32 v227, 0xffff0000, v27
	v_mul_f32_e32 v220, v230, v220
	v_mul_f32_e32 v221, v230, v221
	v_mul_f32_e32 v222, v230, v222
	v_mul_f32_e32 v223, v230, v223
	v_mul_f32_e32 v224, v230, v224
	v_mul_f32_e32 v225, v230, v225
	v_mul_f32_e32 v226, v230, v226
	v_mul_f32_e32 v227, v230, v227
	v_fma_f32 v0, v229, v0, v220
	v_fma_f32 v1, v229, v1, v221
	v_fma_f32 v2, v229, v2, v222
	v_fma_f32 v3, v229, v3, v223
	v_fma_f32 v4, v229, v4, v224
	v_fma_f32 v5, v229, v5, v225
	v_fma_f32 v6, v229, v6, v226
	v_fma_f32 v7, v229, v7, v227
	s_add_i32 s13, s13, s10
	s_cmp_eq_u32 s13, s11
	s_cselect_b32 s13, s8, s13
	v_cvt_pk_bf16_f32 v216, v0, v1
	v_cvt_pk_bf16_f32 v217, v2, v3
	v_cvt_pk_bf16_f32 v218, v4, v5
	v_cvt_pk_bf16_f32 v219, v6, v7
	s_lshl_b32 s14, s13, 15
	s_add_u32 s16, s66, s14
	s_addc_u32 s17, s67, 0
	global_store_dwordx4 v236, v[216:219], s[16:17]
	v_readlane_b32 s18, v232, 49
	v_readlane_b32 s19, v233, 49
	s_nop 1
	v_add_f32_e32 v231, s18, v228
	v_max_f32_e32 v228, s19, v231
	v_sub_f32_e32 v231, v231, v228
	v_sub_f32_e32 v229, s19, v228
	v_mul_f32_e32 v231, 0x3fb8aa3b, v231
	v_mul_f32_e32 v229, 0x3fb8aa3b, v229
	v_exp_f32_e32 v230, v229
	v_exp_f32_e32 v229, v231
	s_nop 0
	v_lshlrev_b32_e32 v220, 16, v28
	v_and_b32_e32 v221, 0xffff0000, v28
	v_lshlrev_b32_e32 v222, 16, v29
	v_and_b32_e32 v223, 0xffff0000, v29
	v_lshlrev_b32_e32 v224, 16, v30
	v_and_b32_e32 v225, 0xffff0000, v30
	v_lshlrev_b32_e32 v226, 16, v31
	v_and_b32_e32 v227, 0xffff0000, v31
	v_mul_f32_e32 v220, v230, v220
	v_mul_f32_e32 v221, v230, v221
	v_mul_f32_e32 v222, v230, v222
	v_mul_f32_e32 v223, v230, v223
	v_mul_f32_e32 v224, v230, v224
	v_mul_f32_e32 v225, v230, v225
	v_mul_f32_e32 v226, v230, v226
	v_mul_f32_e32 v227, v230, v227
	v_fma_f32 v0, v229, v0, v220
	v_fma_f32 v1, v229, v1, v221
	v_fma_f32 v2, v229, v2, v222
	v_fma_f32 v3, v229, v3, v223
	v_fma_f32 v4, v229, v4, v224
	v_fma_f32 v5, v229, v5, v225
	v_fma_f32 v6, v229, v6, v226
	v_fma_f32 v7, v229, v7, v227
	s_add_i32 s13, s13, s10
	s_cmp_eq_u32 s13, s11
	s_cselect_b32 s13, s8, s13
	v_cvt_pk_bf16_f32 v216, v0, v1
	v_cvt_pk_bf16_f32 v217, v2, v3
	v_cvt_pk_bf16_f32 v218, v4, v5
	v_cvt_pk_bf16_f32 v219, v6, v7
	s_lshl_b32 s14, s13, 15
	s_add_u32 s16, s66, s14
	s_addc_u32 s17, s67, 0
	global_store_dwordx4 v236, v[216:219], s[16:17]
	v_readlane_b32 s18, v232, 50
	v_readlane_b32 s19, v233, 50
	s_nop 1
	v_add_f32_e32 v231, s18, v228
	v_max_f32_e32 v228, s19, v231
	v_sub_f32_e32 v231, v231, v228
	v_sub_f32_e32 v229, s19, v228
	v_mul_f32_e32 v231, 0x3fb8aa3b, v231
	v_mul_f32_e32 v229, 0x3fb8aa3b, v229
	v_exp_f32_e32 v230, v229
	v_exp_f32_e32 v229, v231
	s_nop 0
	v_lshlrev_b32_e32 v220, 16, v32
	v_and_b32_e32 v221, 0xffff0000, v32
	v_lshlrev_b32_e32 v222, 16, v33
	v_and_b32_e32 v223, 0xffff0000, v33
	v_lshlrev_b32_e32 v224, 16, v34
	v_and_b32_e32 v225, 0xffff0000, v34
	v_lshlrev_b32_e32 v226, 16, v35
	v_and_b32_e32 v227, 0xffff0000, v35
	v_mul_f32_e32 v220, v230, v220
	v_mul_f32_e32 v221, v230, v221
	v_mul_f32_e32 v222, v230, v222
	v_mul_f32_e32 v223, v230, v223
	v_mul_f32_e32 v224, v230, v224
	v_mul_f32_e32 v225, v230, v225
	v_mul_f32_e32 v226, v230, v226
	v_mul_f32_e32 v227, v230, v227
	v_fma_f32 v0, v229, v0, v220
	v_fma_f32 v1, v229, v1, v221
	v_fma_f32 v2, v229, v2, v222
	v_fma_f32 v3, v229, v3, v223
	v_fma_f32 v4, v229, v4, v224
	v_fma_f32 v5, v229, v5, v225
	v_fma_f32 v6, v229, v6, v226
	v_fma_f32 v7, v229, v7, v227
	s_add_i32 s13, s13, s10
	s_cmp_eq_u32 s13, s11
	s_cselect_b32 s13, s8, s13
	v_cvt_pk_bf16_f32 v216, v0, v1
	v_cvt_pk_bf16_f32 v217, v2, v3
	v_cvt_pk_bf16_f32 v218, v4, v5
	v_cvt_pk_bf16_f32 v219, v6, v7
	s_lshl_b32 s14, s13, 15
	s_add_u32 s16, s66, s14
	s_addc_u32 s17, s67, 0
	global_store_dwordx4 v236, v[216:219], s[16:17]
	v_readlane_b32 s18, v232, 51
	v_readlane_b32 s19, v233, 51
	s_nop 1
	v_add_f32_e32 v231, s18, v228
	v_max_f32_e32 v228, s19, v231
	v_sub_f32_e32 v231, v231, v228
	v_sub_f32_e32 v229, s19, v228
	v_mul_f32_e32 v231, 0x3fb8aa3b, v231
	v_mul_f32_e32 v229, 0x3fb8aa3b, v229
	v_exp_f32_e32 v230, v229
	v_exp_f32_e32 v229, v231
	s_nop 0
	v_lshlrev_b32_e32 v220, 16, v36
	v_and_b32_e32 v221, 0xffff0000, v36
	v_lshlrev_b32_e32 v222, 16, v37
	v_and_b32_e32 v223, 0xffff0000, v37
	v_lshlrev_b32_e32 v224, 16, v38
	v_and_b32_e32 v225, 0xffff0000, v38
	v_lshlrev_b32_e32 v226, 16, v39
	v_and_b32_e32 v227, 0xffff0000, v39
	v_mul_f32_e32 v220, v230, v220
	v_mul_f32_e32 v221, v230, v221
	v_mul_f32_e32 v222, v230, v222
	v_mul_f32_e32 v223, v230, v223
	v_mul_f32_e32 v224, v230, v224
	v_mul_f32_e32 v225, v230, v225
	v_mul_f32_e32 v226, v230, v226
	v_mul_f32_e32 v227, v230, v227
	v_fma_f32 v0, v229, v0, v220
	v_fma_f32 v1, v229, v1, v221
	v_fma_f32 v2, v229, v2, v222
	v_fma_f32 v3, v229, v3, v223
	v_fma_f32 v4, v229, v4, v224
	v_fma_f32 v5, v229, v5, v225
	v_fma_f32 v6, v229, v6, v226
	v_fma_f32 v7, v229, v7, v227
	s_add_i32 s13, s13, s10
	s_cmp_eq_u32 s13, s11
	s_cselect_b32 s13, s8, s13
	v_cvt_pk_bf16_f32 v216, v0, v1
	v_cvt_pk_bf16_f32 v217, v2, v3
	v_cvt_pk_bf16_f32 v218, v4, v5
	v_cvt_pk_bf16_f32 v219, v6, v7
	s_lshl_b32 s14, s13, 15
	s_add_u32 s16, s66, s14
	s_addc_u32 s17, s67, 0
	global_store_dwordx4 v236, v[216:219], s[16:17]
	v_readlane_b32 s18, v232, 52
	v_readlane_b32 s19, v233, 52
	s_nop 1
	v_add_f32_e32 v231, s18, v228
	v_max_f32_e32 v228, s19, v231
	v_sub_f32_e32 v231, v231, v228
	v_sub_f32_e32 v229, s19, v228
	v_mul_f32_e32 v231, 0x3fb8aa3b, v231
	v_mul_f32_e32 v229, 0x3fb8aa3b, v229
	v_exp_f32_e32 v230, v229
	v_exp_f32_e32 v229, v231
	s_nop 0
	v_lshlrev_b32_e32 v220, 16, v40
	v_and_b32_e32 v221, 0xffff0000, v40
	v_lshlrev_b32_e32 v222, 16, v41
	v_and_b32_e32 v223, 0xffff0000, v41
	v_lshlrev_b32_e32 v224, 16, v42
	v_and_b32_e32 v225, 0xffff0000, v42
	v_lshlrev_b32_e32 v226, 16, v43
	v_and_b32_e32 v227, 0xffff0000, v43
	v_mul_f32_e32 v220, v230, v220
	v_mul_f32_e32 v221, v230, v221
	v_mul_f32_e32 v222, v230, v222
	v_mul_f32_e32 v223, v230, v223
	v_mul_f32_e32 v224, v230, v224
	v_mul_f32_e32 v225, v230, v225
	v_mul_f32_e32 v226, v230, v226
	v_mul_f32_e32 v227, v230, v227
	v_fma_f32 v0, v229, v0, v220
	v_fma_f32 v1, v229, v1, v221
	v_fma_f32 v2, v229, v2, v222
	v_fma_f32 v3, v229, v3, v223
	v_fma_f32 v4, v229, v4, v224
	v_fma_f32 v5, v229, v5, v225
	v_fma_f32 v6, v229, v6, v226
	v_fma_f32 v7, v229, v7, v227
	s_add_i32 s13, s13, s10
	s_cmp_eq_u32 s13, s11
	s_cselect_b32 s13, s8, s13
	v_cvt_pk_bf16_f32 v216, v0, v1
	v_cvt_pk_bf16_f32 v217, v2, v3
	v_cvt_pk_bf16_f32 v218, v4, v5
	v_cvt_pk_bf16_f32 v219, v6, v7
	s_lshl_b32 s14, s13, 15
	s_add_u32 s16, s66, s14
	s_addc_u32 s17, s67, 0
	global_store_dwordx4 v236, v[216:219], s[16:17]
	v_readlane_b32 s18, v232, 53
	v_readlane_b32 s19, v233, 53
	s_nop 1
	v_add_f32_e32 v231, s18, v228
	v_max_f32_e32 v228, s19, v231
	v_sub_f32_e32 v231, v231, v228
	v_sub_f32_e32 v229, s19, v228
	v_mul_f32_e32 v231, 0x3fb8aa3b, v231
	v_mul_f32_e32 v229, 0x3fb8aa3b, v229
	v_exp_f32_e32 v230, v229
	v_exp_f32_e32 v229, v231
	s_nop 0
	v_lshlrev_b32_e32 v220, 16, v44
	v_and_b32_e32 v221, 0xffff0000, v44
	v_lshlrev_b32_e32 v222, 16, v45
	v_and_b32_e32 v223, 0xffff0000, v45
	v_lshlrev_b32_e32 v224, 16, v46
	v_and_b32_e32 v225, 0xffff0000, v46
	v_lshlrev_b32_e32 v226, 16, v47
	v_and_b32_e32 v227, 0xffff0000, v47
	v_mul_f32_e32 v220, v230, v220
	v_mul_f32_e32 v221, v230, v221
	v_mul_f32_e32 v222, v230, v222
	v_mul_f32_e32 v223, v230, v223
	v_mul_f32_e32 v224, v230, v224
	v_mul_f32_e32 v225, v230, v225
	v_mul_f32_e32 v226, v230, v226
	v_mul_f32_e32 v227, v230, v227
	v_fma_f32 v0, v229, v0, v220
	v_fma_f32 v1, v229, v1, v221
	v_fma_f32 v2, v229, v2, v222
	v_fma_f32 v3, v229, v3, v223
	v_fma_f32 v4, v229, v4, v224
	v_fma_f32 v5, v229, v5, v225
	v_fma_f32 v6, v229, v6, v226
	v_fma_f32 v7, v229, v7, v227
	s_add_i32 s13, s13, s10
	s_cmp_eq_u32 s13, s11
	s_cselect_b32 s13, s8, s13
	v_cvt_pk_bf16_f32 v216, v0, v1
	v_cvt_pk_bf16_f32 v217, v2, v3
	v_cvt_pk_bf16_f32 v218, v4, v5
	v_cvt_pk_bf16_f32 v219, v6, v7
	s_lshl_b32 s14, s13, 15
	s_add_u32 s16, s66, s14
	s_addc_u32 s17, s67, 0
	global_store_dwordx4 v236, v[216:219], s[16:17]
	v_readlane_b32 s18, v232, 54
	v_readlane_b32 s19, v233, 54
	s_nop 1
	v_add_f32_e32 v231, s18, v228
	v_max_f32_e32 v228, s19, v231
	v_sub_f32_e32 v231, v231, v228
	v_sub_f32_e32 v229, s19, v228
	v_mul_f32_e32 v231, 0x3fb8aa3b, v231
	v_mul_f32_e32 v229, 0x3fb8aa3b, v229
	v_exp_f32_e32 v230, v229
	v_exp_f32_e32 v229, v231
	s_nop 0
	v_lshlrev_b32_e32 v220, 16, v48
	v_and_b32_e32 v221, 0xffff0000, v48
	v_lshlrev_b32_e32 v222, 16, v49
	v_and_b32_e32 v223, 0xffff0000, v49
	v_lshlrev_b32_e32 v224, 16, v50
	v_and_b32_e32 v225, 0xffff0000, v50
	v_lshlrev_b32_e32 v226, 16, v51
	v_and_b32_e32 v227, 0xffff0000, v51
	v_mul_f32_e32 v220, v230, v220
	v_mul_f32_e32 v221, v230, v221
	v_mul_f32_e32 v222, v230, v222
	v_mul_f32_e32 v223, v230, v223
	v_mul_f32_e32 v224, v230, v224
	v_mul_f32_e32 v225, v230, v225
	v_mul_f32_e32 v226, v230, v226
	v_mul_f32_e32 v227, v230, v227
	v_fma_f32 v0, v229, v0, v220
	v_fma_f32 v1, v229, v1, v221
	v_fma_f32 v2, v229, v2, v222
	v_fma_f32 v3, v229, v3, v223
	v_fma_f32 v4, v229, v4, v224
	v_fma_f32 v5, v229, v5, v225
	v_fma_f32 v6, v229, v6, v226
	v_fma_f32 v7, v229, v7, v227
	s_add_i32 s13, s13, s10
	s_cmp_eq_u32 s13, s11
	s_cselect_b32 s13, s8, s13
	v_cvt_pk_bf16_f32 v216, v0, v1
	v_cvt_pk_bf16_f32 v217, v2, v3
	v_cvt_pk_bf16_f32 v218, v4, v5
	v_cvt_pk_bf16_f32 v219, v6, v7
	s_lshl_b32 s14, s13, 15
	s_add_u32 s16, s66, s14
	s_addc_u32 s17, s67, 0
	global_store_dwordx4 v236, v[216:219], s[16:17]
	v_readlane_b32 s18, v232, 55
	v_readlane_b32 s19, v233, 55
	s_nop 1
	v_add_f32_e32 v231, s18, v228
	v_max_f32_e32 v228, s19, v231
	v_sub_f32_e32 v231, v231, v228
	v_sub_f32_e32 v229, s19, v228
	v_mul_f32_e32 v231, 0x3fb8aa3b, v231
	v_mul_f32_e32 v229, 0x3fb8aa3b, v229
	v_exp_f32_e32 v230, v229
	v_exp_f32_e32 v229, v231
	s_nop 0
	v_lshlrev_b32_e32 v220, 16, v52
	v_and_b32_e32 v221, 0xffff0000, v52
	v_lshlrev_b32_e32 v222, 16, v53
	v_and_b32_e32 v223, 0xffff0000, v53
	v_lshlrev_b32_e32 v224, 16, v54
	v_and_b32_e32 v225, 0xffff0000, v54
	v_lshlrev_b32_e32 v226, 16, v55
	v_and_b32_e32 v227, 0xffff0000, v55
	v_mul_f32_e32 v220, v230, v220
	v_mul_f32_e32 v221, v230, v221
	v_mul_f32_e32 v222, v230, v222
	v_mul_f32_e32 v223, v230, v223
	v_mul_f32_e32 v224, v230, v224
	v_mul_f32_e32 v225, v230, v225
	v_mul_f32_e32 v226, v230, v226
	v_mul_f32_e32 v227, v230, v227
	v_fma_f32 v0, v229, v0, v220
	v_fma_f32 v1, v229, v1, v221
	v_fma_f32 v2, v229, v2, v222
	v_fma_f32 v3, v229, v3, v223
	v_fma_f32 v4, v229, v4, v224
	v_fma_f32 v5, v229, v5, v225
	v_fma_f32 v6, v229, v6, v226
	v_fma_f32 v7, v229, v7, v227
	s_add_i32 s13, s13, s10
	s_cmp_eq_u32 s13, s11
	s_cselect_b32 s13, s8, s13
	v_cvt_pk_bf16_f32 v216, v0, v1
	v_cvt_pk_bf16_f32 v217, v2, v3
	v_cvt_pk_bf16_f32 v218, v4, v5
	v_cvt_pk_bf16_f32 v219, v6, v7
	s_lshl_b32 s14, s13, 15
	s_add_u32 s16, s66, s14
	s_addc_u32 s17, s67, 0
	global_store_dwordx4 v236, v[216:219], s[16:17]
	v_readlane_b32 s18, v232, 56
	v_readlane_b32 s19, v233, 56
	s_nop 1
	v_add_f32_e32 v231, s18, v228
	v_max_f32_e32 v228, s19, v231
	v_sub_f32_e32 v231, v231, v228
	v_sub_f32_e32 v229, s19, v228
	v_mul_f32_e32 v231, 0x3fb8aa3b, v231
	v_mul_f32_e32 v229, 0x3fb8aa3b, v229
	v_exp_f32_e32 v230, v229
	v_exp_f32_e32 v229, v231
	s_nop 0
	v_lshlrev_b32_e32 v220, 16, v56
	v_and_b32_e32 v221, 0xffff0000, v56
	v_lshlrev_b32_e32 v222, 16, v57
	v_and_b32_e32 v223, 0xffff0000, v57
	v_lshlrev_b32_e32 v224, 16, v58
	v_and_b32_e32 v225, 0xffff0000, v58
	v_lshlrev_b32_e32 v226, 16, v59
	v_and_b32_e32 v227, 0xffff0000, v59
	v_mul_f32_e32 v220, v230, v220
	v_mul_f32_e32 v221, v230, v221
	v_mul_f32_e32 v222, v230, v222
	v_mul_f32_e32 v223, v230, v223
	v_mul_f32_e32 v224, v230, v224
	v_mul_f32_e32 v225, v230, v225
	v_mul_f32_e32 v226, v230, v226
	v_mul_f32_e32 v227, v230, v227
	v_fma_f32 v0, v229, v0, v220
	v_fma_f32 v1, v229, v1, v221
	v_fma_f32 v2, v229, v2, v222
	v_fma_f32 v3, v229, v3, v223
	v_fma_f32 v4, v229, v4, v224
	v_fma_f32 v5, v229, v5, v225
	v_fma_f32 v6, v229, v6, v226
	v_fma_f32 v7, v229, v7, v227
	s_add_i32 s13, s13, s10
	s_cmp_eq_u32 s13, s11
	s_cselect_b32 s13, s8, s13
	v_cvt_pk_bf16_f32 v216, v0, v1
	v_cvt_pk_bf16_f32 v217, v2, v3
	v_cvt_pk_bf16_f32 v218, v4, v5
	v_cvt_pk_bf16_f32 v219, v6, v7
	s_lshl_b32 s14, s13, 15
	s_add_u32 s16, s66, s14
	s_addc_u32 s17, s67, 0
	global_store_dwordx4 v236, v[216:219], s[16:17]
	v_readlane_b32 s18, v232, 57
	v_readlane_b32 s19, v233, 57
	s_nop 1
	v_add_f32_e32 v231, s18, v228
	v_max_f32_e32 v228, s19, v231
	v_sub_f32_e32 v231, v231, v228
	v_sub_f32_e32 v229, s19, v228
	v_mul_f32_e32 v231, 0x3fb8aa3b, v231
	v_mul_f32_e32 v229, 0x3fb8aa3b, v229
	v_exp_f32_e32 v230, v229
	v_exp_f32_e32 v229, v231
	s_nop 0
	v_lshlrev_b32_e32 v220, 16, v60
	v_and_b32_e32 v221, 0xffff0000, v60
	v_lshlrev_b32_e32 v222, 16, v61
	v_and_b32_e32 v223, 0xffff0000, v61
	v_lshlrev_b32_e32 v224, 16, v62
	v_and_b32_e32 v225, 0xffff0000, v62
	v_lshlrev_b32_e32 v226, 16, v63
	v_and_b32_e32 v227, 0xffff0000, v63
	v_mul_f32_e32 v220, v230, v220
	v_mul_f32_e32 v221, v230, v221
	v_mul_f32_e32 v222, v230, v222
	v_mul_f32_e32 v223, v230, v223
	v_mul_f32_e32 v224, v230, v224
	v_mul_f32_e32 v225, v230, v225
	v_mul_f32_e32 v226, v230, v226
	v_mul_f32_e32 v227, v230, v227
	v_fma_f32 v0, v229, v0, v220
	v_fma_f32 v1, v229, v1, v221
	v_fma_f32 v2, v229, v2, v222
	v_fma_f32 v3, v229, v3, v223
	v_fma_f32 v4, v229, v4, v224
	v_fma_f32 v5, v229, v5, v225
	v_fma_f32 v6, v229, v6, v226
	v_fma_f32 v7, v229, v7, v227
	s_add_i32 s13, s13, s10
	s_cmp_eq_u32 s13, s11
	s_cselect_b32 s13, s8, s13
	v_cvt_pk_bf16_f32 v216, v0, v1
	v_cvt_pk_bf16_f32 v217, v2, v3
	v_cvt_pk_bf16_f32 v218, v4, v5
	v_cvt_pk_bf16_f32 v219, v6, v7
	s_lshl_b32 s14, s13, 15
	s_add_u32 s16, s66, s14
	s_addc_u32 s17, s67, 0
	global_store_dwordx4 v236, v[216:219], s[16:17]
	v_readlane_b32 s18, v232, 58
	v_readlane_b32 s19, v233, 58
	s_nop 1
	v_add_f32_e32 v231, s18, v228
	v_max_f32_e32 v228, s19, v231
	v_sub_f32_e32 v231, v231, v228
	v_sub_f32_e32 v229, s19, v228
	v_mul_f32_e32 v231, 0x3fb8aa3b, v231
	v_mul_f32_e32 v229, 0x3fb8aa3b, v229
	v_exp_f32_e32 v230, v229
	v_exp_f32_e32 v229, v231
	s_nop 0
	v_lshlrev_b32_e32 v220, 16, v64
	v_and_b32_e32 v221, 0xffff0000, v64
	v_lshlrev_b32_e32 v222, 16, v65
	v_and_b32_e32 v223, 0xffff0000, v65
	v_lshlrev_b32_e32 v224, 16, v66
	v_and_b32_e32 v225, 0xffff0000, v66
	v_lshlrev_b32_e32 v226, 16, v67
	v_and_b32_e32 v227, 0xffff0000, v67
	v_mul_f32_e32 v220, v230, v220
	v_mul_f32_e32 v221, v230, v221
	v_mul_f32_e32 v222, v230, v222
	v_mul_f32_e32 v223, v230, v223
	v_mul_f32_e32 v224, v230, v224
	v_mul_f32_e32 v225, v230, v225
	v_mul_f32_e32 v226, v230, v226
	v_mul_f32_e32 v227, v230, v227
	v_fma_f32 v0, v229, v0, v220
	v_fma_f32 v1, v229, v1, v221
	v_fma_f32 v2, v229, v2, v222
	v_fma_f32 v3, v229, v3, v223
	v_fma_f32 v4, v229, v4, v224
	v_fma_f32 v5, v229, v5, v225
	v_fma_f32 v6, v229, v6, v226
	v_fma_f32 v7, v229, v7, v227
	s_add_i32 s13, s13, s10
	s_cmp_eq_u32 s13, s11
	s_cselect_b32 s13, s8, s13
	v_cvt_pk_bf16_f32 v216, v0, v1
	v_cvt_pk_bf16_f32 v217, v2, v3
	v_cvt_pk_bf16_f32 v218, v4, v5
	v_cvt_pk_bf16_f32 v219, v6, v7
	s_lshl_b32 s14, s13, 15
	s_add_u32 s16, s66, s14
	s_addc_u32 s17, s67, 0
	global_store_dwordx4 v236, v[216:219], s[16:17]
	v_readlane_b32 s18, v232, 59
	v_readlane_b32 s19, v233, 59
	s_nop 1
	v_add_f32_e32 v231, s18, v228
	v_max_f32_e32 v228, s19, v231
	v_sub_f32_e32 v231, v231, v228
	v_sub_f32_e32 v229, s19, v228
	v_mul_f32_e32 v231, 0x3fb8aa3b, v231
	v_mul_f32_e32 v229, 0x3fb8aa3b, v229
	v_exp_f32_e32 v230, v229
	v_exp_f32_e32 v229, v231
	s_nop 0
	v_lshlrev_b32_e32 v220, 16, v68
	v_and_b32_e32 v221, 0xffff0000, v68
	v_lshlrev_b32_e32 v222, 16, v69
	v_and_b32_e32 v223, 0xffff0000, v69
	v_lshlrev_b32_e32 v224, 16, v70
	v_and_b32_e32 v225, 0xffff0000, v70
	v_lshlrev_b32_e32 v226, 16, v71
	v_and_b32_e32 v227, 0xffff0000, v71
	v_mul_f32_e32 v220, v230, v220
	v_mul_f32_e32 v221, v230, v221
	v_mul_f32_e32 v222, v230, v222
	v_mul_f32_e32 v223, v230, v223
	v_mul_f32_e32 v224, v230, v224
	v_mul_f32_e32 v225, v230, v225
	v_mul_f32_e32 v226, v230, v226
	v_mul_f32_e32 v227, v230, v227
	v_fma_f32 v0, v229, v0, v220
	v_fma_f32 v1, v229, v1, v221
	v_fma_f32 v2, v229, v2, v222
	v_fma_f32 v3, v229, v3, v223
	v_fma_f32 v4, v229, v4, v224
	v_fma_f32 v5, v229, v5, v225
	v_fma_f32 v6, v229, v6, v226
	v_fma_f32 v7, v229, v7, v227
	s_add_i32 s13, s13, s10
	s_cmp_eq_u32 s13, s11
	s_cselect_b32 s13, s8, s13
	v_cvt_pk_bf16_f32 v216, v0, v1
	v_cvt_pk_bf16_f32 v217, v2, v3
	v_cvt_pk_bf16_f32 v218, v4, v5
	v_cvt_pk_bf16_f32 v219, v6, v7
	s_lshl_b32 s14, s13, 15
	s_add_u32 s16, s66, s14
	s_addc_u32 s17, s67, 0
	global_store_dwordx4 v236, v[216:219], s[16:17]
	v_readlane_b32 s18, v232, 60
	v_readlane_b32 s19, v233, 60
	s_nop 1
	v_add_f32_e32 v231, s18, v228
	v_max_f32_e32 v228, s19, v231
	v_sub_f32_e32 v231, v231, v228
	v_sub_f32_e32 v229, s19, v228
	v_mul_f32_e32 v231, 0x3fb8aa3b, v231
	v_mul_f32_e32 v229, 0x3fb8aa3b, v229
	v_exp_f32_e32 v230, v229
	v_exp_f32_e32 v229, v231
	s_nop 0
	v_lshlrev_b32_e32 v220, 16, v72
	v_and_b32_e32 v221, 0xffff0000, v72
	v_lshlrev_b32_e32 v222, 16, v73
	v_and_b32_e32 v223, 0xffff0000, v73
	v_lshlrev_b32_e32 v224, 16, v74
	v_and_b32_e32 v225, 0xffff0000, v74
	v_lshlrev_b32_e32 v226, 16, v75
	v_and_b32_e32 v227, 0xffff0000, v75
	v_mul_f32_e32 v220, v230, v220
	v_mul_f32_e32 v221, v230, v221
	v_mul_f32_e32 v222, v230, v222
	v_mul_f32_e32 v223, v230, v223
	v_mul_f32_e32 v224, v230, v224
	v_mul_f32_e32 v225, v230, v225
	v_mul_f32_e32 v226, v230, v226
	v_mul_f32_e32 v227, v230, v227
	v_fma_f32 v0, v229, v0, v220
	v_fma_f32 v1, v229, v1, v221
	v_fma_f32 v2, v229, v2, v222
	v_fma_f32 v3, v229, v3, v223
	v_fma_f32 v4, v229, v4, v224
	v_fma_f32 v5, v229, v5, v225
	v_fma_f32 v6, v229, v6, v226
	v_fma_f32 v7, v229, v7, v227
	s_add_i32 s13, s13, s10
	s_cmp_eq_u32 s13, s11
	s_cselect_b32 s13, s8, s13
	v_cvt_pk_bf16_f32 v216, v0, v1
	v_cvt_pk_bf16_f32 v217, v2, v3
	v_cvt_pk_bf16_f32 v218, v4, v5
	v_cvt_pk_bf16_f32 v219, v6, v7
	s_lshl_b32 s14, s13, 15
	s_add_u32 s16, s66, s14
	s_addc_u32 s17, s67, 0
	global_store_dwordx4 v236, v[216:219], s[16:17]
	v_readlane_b32 s18, v232, 61
	v_readlane_b32 s19, v233, 61
	s_nop 1
	v_add_f32_e32 v231, s18, v228
	v_max_f32_e32 v228, s19, v231
	v_sub_f32_e32 v231, v231, v228
	v_sub_f32_e32 v229, s19, v228
	v_mul_f32_e32 v231, 0x3fb8aa3b, v231
	v_mul_f32_e32 v229, 0x3fb8aa3b, v229
	v_exp_f32_e32 v230, v229
	v_exp_f32_e32 v229, v231
	s_nop 0
	v_lshlrev_b32_e32 v220, 16, v76
	v_and_b32_e32 v221, 0xffff0000, v76
	v_lshlrev_b32_e32 v222, 16, v77
	v_and_b32_e32 v223, 0xffff0000, v77
	v_lshlrev_b32_e32 v224, 16, v78
	v_and_b32_e32 v225, 0xffff0000, v78
	v_lshlrev_b32_e32 v226, 16, v79
	v_and_b32_e32 v227, 0xffff0000, v79
	v_mul_f32_e32 v220, v230, v220
	v_mul_f32_e32 v221, v230, v221
	v_mul_f32_e32 v222, v230, v222
	v_mul_f32_e32 v223, v230, v223
	v_mul_f32_e32 v224, v230, v224
	v_mul_f32_e32 v225, v230, v225
	v_mul_f32_e32 v226, v230, v226
	v_mul_f32_e32 v227, v230, v227
	v_fma_f32 v0, v229, v0, v220
	v_fma_f32 v1, v229, v1, v221
	v_fma_f32 v2, v229, v2, v222
	v_fma_f32 v3, v229, v3, v223
	v_fma_f32 v4, v229, v4, v224
	v_fma_f32 v5, v229, v5, v225
	v_fma_f32 v6, v229, v6, v226
	v_fma_f32 v7, v229, v7, v227
	s_add_i32 s13, s13, s10
	s_cmp_eq_u32 s13, s11
	s_cselect_b32 s13, s8, s13
	v_cvt_pk_bf16_f32 v216, v0, v1
	v_cvt_pk_bf16_f32 v217, v2, v3
	v_cvt_pk_bf16_f32 v218, v4, v5
	v_cvt_pk_bf16_f32 v219, v6, v7
	s_lshl_b32 s14, s13, 15
	s_add_u32 s16, s66, s14
	s_addc_u32 s17, s67, 0
	global_store_dwordx4 v236, v[216:219], s[16:17]
	v_readlane_b32 s18, v232, 62
	v_readlane_b32 s19, v233, 62
	s_nop 1
	v_add_f32_e32 v231, s18, v228
	v_max_f32_e32 v228, s19, v231
	v_sub_f32_e32 v231, v231, v228
	v_sub_f32_e32 v229, s19, v228
	v_mul_f32_e32 v231, 0x3fb8aa3b, v231
	v_mul_f32_e32 v229, 0x3fb8aa3b, v229
	v_exp_f32_e32 v230, v229
	v_exp_f32_e32 v229, v231
	s_nop 0
	v_lshlrev_b32_e32 v220, 16, v80
	v_and_b32_e32 v221, 0xffff0000, v80
	v_lshlrev_b32_e32 v222, 16, v81
	v_and_b32_e32 v223, 0xffff0000, v81
	v_lshlrev_b32_e32 v224, 16, v82
	v_and_b32_e32 v225, 0xffff0000, v82
	v_lshlrev_b32_e32 v226, 16, v83
	v_and_b32_e32 v227, 0xffff0000, v83
	v_mul_f32_e32 v220, v230, v220
	v_mul_f32_e32 v221, v230, v221
	v_mul_f32_e32 v222, v230, v222
	v_mul_f32_e32 v223, v230, v223
	v_mul_f32_e32 v224, v230, v224
	v_mul_f32_e32 v225, v230, v225
	v_mul_f32_e32 v226, v230, v226
	v_mul_f32_e32 v227, v230, v227
	v_fma_f32 v0, v229, v0, v220
	v_fma_f32 v1, v229, v1, v221
	v_fma_f32 v2, v229, v2, v222
	v_fma_f32 v3, v229, v3, v223
	v_fma_f32 v4, v229, v4, v224
	v_fma_f32 v5, v229, v5, v225
	v_fma_f32 v6, v229, v6, v226
	v_fma_f32 v7, v229, v7, v227
	s_add_i32 s13, s13, s10
	s_cmp_eq_u32 s13, s11
	s_cselect_b32 s13, s8, s13
	v_cvt_pk_bf16_f32 v216, v0, v1
	v_cvt_pk_bf16_f32 v217, v2, v3
	v_cvt_pk_bf16_f32 v218, v4, v5
	v_cvt_pk_bf16_f32 v219, v6, v7
	s_lshl_b32 s14, s13, 15
	s_add_u32 s16, s66, s14
	s_addc_u32 s17, s67, 0
	global_store_dwordx4 v236, v[216:219], s[16:17]
	v_readlane_b32 s18, v232, 63
	v_readlane_b32 s19, v233, 63
	s_nop 1
	v_add_f32_e32 v231, s18, v228
	v_max_f32_e32 v228, s19, v231
	v_sub_f32_e32 v231, v231, v228
	v_sub_f32_e32 v229, s19, v228
	v_mul_f32_e32 v231, 0x3fb8aa3b, v231
	v_mul_f32_e32 v229, 0x3fb8aa3b, v229
	v_exp_f32_e32 v230, v229
	v_exp_f32_e32 v229, v231
	s_nop 0
	v_lshlrev_b32_e32 v220, 16, v84
	v_and_b32_e32 v221, 0xffff0000, v84
	v_lshlrev_b32_e32 v222, 16, v85
	v_and_b32_e32 v223, 0xffff0000, v85
	v_lshlrev_b32_e32 v224, 16, v86
	v_and_b32_e32 v225, 0xffff0000, v86
	v_lshlrev_b32_e32 v226, 16, v87
	v_and_b32_e32 v227, 0xffff0000, v87
	v_mul_f32_e32 v220, v230, v220
	v_mul_f32_e32 v221, v230, v221
	v_mul_f32_e32 v222, v230, v222
	v_mul_f32_e32 v223, v230, v223
	v_mul_f32_e32 v224, v230, v224
	v_mul_f32_e32 v225, v230, v225
	v_mul_f32_e32 v226, v230, v226
	v_mul_f32_e32 v227, v230, v227
	v_fma_f32 v0, v229, v0, v220
	v_fma_f32 v1, v229, v1, v221
	v_fma_f32 v2, v229, v2, v222
	v_fma_f32 v3, v229, v3, v223
	v_fma_f32 v4, v229, v4, v224
	v_fma_f32 v5, v229, v5, v225
	v_fma_f32 v6, v229, v6, v226
	v_fma_f32 v7, v229, v7, v227
	s_add_i32 s13, s13, s10
	s_cmp_eq_u32 s13, s11
	s_cselect_b32 s13, s8, s13
	v_cvt_pk_bf16_f32 v216, v0, v1
	v_cvt_pk_bf16_f32 v217, v2, v3
	v_cvt_pk_bf16_f32 v218, v4, v5
	v_cvt_pk_bf16_f32 v219, v6, v7
	s_lshl_b32 s14, s13, 15
	s_add_u32 s16, s66, s14
	s_addc_u32 s17, s67, 0
	global_store_dwordx4 v236, v[216:219], s[16:17]
	v_readlane_b32 s18, v234, 0
	v_readlane_b32 s19, v235, 0
	s_nop 1
	v_add_f32_e32 v231, s18, v228
	v_max_f32_e32 v228, s19, v231
	v_sub_f32_e32 v231, v231, v228
	v_sub_f32_e32 v229, s19, v228
	v_mul_f32_e32 v231, 0x3fb8aa3b, v231
	v_mul_f32_e32 v229, 0x3fb8aa3b, v229
	v_exp_f32_e32 v230, v229
	v_exp_f32_e32 v229, v231
	s_nop 0
	v_lshlrev_b32_e32 v220, 16, v88
	v_and_b32_e32 v221, 0xffff0000, v88
	v_lshlrev_b32_e32 v222, 16, v89
	v_and_b32_e32 v223, 0xffff0000, v89
	v_lshlrev_b32_e32 v224, 16, v90
	v_and_b32_e32 v225, 0xffff0000, v90
	v_lshlrev_b32_e32 v226, 16, v91
	v_and_b32_e32 v227, 0xffff0000, v91
	v_mul_f32_e32 v220, v230, v220
	v_mul_f32_e32 v221, v230, v221
	v_mul_f32_e32 v222, v230, v222
	v_mul_f32_e32 v223, v230, v223
	v_mul_f32_e32 v224, v230, v224
	v_mul_f32_e32 v225, v230, v225
	v_mul_f32_e32 v226, v230, v226
	v_mul_f32_e32 v227, v230, v227
	v_fma_f32 v0, v229, v0, v220
	v_fma_f32 v1, v229, v1, v221
	v_fma_f32 v2, v229, v2, v222
	v_fma_f32 v3, v229, v3, v223
	v_fma_f32 v4, v229, v4, v224
	v_fma_f32 v5, v229, v5, v225
	v_fma_f32 v6, v229, v6, v226
	v_fma_f32 v7, v229, v7, v227
	s_add_i32 s13, s13, s10
	s_cmp_eq_u32 s13, s11
	s_cselect_b32 s13, s8, s13
	v_cvt_pk_bf16_f32 v216, v0, v1
	v_cvt_pk_bf16_f32 v217, v2, v3
	v_cvt_pk_bf16_f32 v218, v4, v5
	v_cvt_pk_bf16_f32 v219, v6, v7
	s_lshl_b32 s14, s13, 15
	s_add_u32 s16, s66, s14
	s_addc_u32 s17, s67, 0
	global_store_dwordx4 v236, v[216:219], s[16:17]
	v_readlane_b32 s18, v234, 1
	v_readlane_b32 s19, v235, 1
	s_nop 1
	v_add_f32_e32 v231, s18, v228
	v_max_f32_e32 v228, s19, v231
	v_sub_f32_e32 v231, v231, v228
	v_sub_f32_e32 v229, s19, v228
	v_mul_f32_e32 v231, 0x3fb8aa3b, v231
	v_mul_f32_e32 v229, 0x3fb8aa3b, v229
	v_exp_f32_e32 v230, v229
	v_exp_f32_e32 v229, v231
	s_nop 0
	v_lshlrev_b32_e32 v220, 16, v92
	v_and_b32_e32 v221, 0xffff0000, v92
	v_lshlrev_b32_e32 v222, 16, v93
	v_and_b32_e32 v223, 0xffff0000, v93
	v_lshlrev_b32_e32 v224, 16, v94
	v_and_b32_e32 v225, 0xffff0000, v94
	v_lshlrev_b32_e32 v226, 16, v95
	v_and_b32_e32 v227, 0xffff0000, v95
	v_mul_f32_e32 v220, v230, v220
	v_mul_f32_e32 v221, v230, v221
	v_mul_f32_e32 v222, v230, v222
	v_mul_f32_e32 v223, v230, v223
	v_mul_f32_e32 v224, v230, v224
	v_mul_f32_e32 v225, v230, v225
	v_mul_f32_e32 v226, v230, v226
	v_mul_f32_e32 v227, v230, v227
	v_fma_f32 v0, v229, v0, v220
	v_fma_f32 v1, v229, v1, v221
	v_fma_f32 v2, v229, v2, v222
	v_fma_f32 v3, v229, v3, v223
	v_fma_f32 v4, v229, v4, v224
	v_fma_f32 v5, v229, v5, v225
	v_fma_f32 v6, v229, v6, v226
	v_fma_f32 v7, v229, v7, v227
	s_add_i32 s13, s13, s10
	s_cmp_eq_u32 s13, s11
	s_cselect_b32 s13, s8, s13
	s_branch .Lgs_done
.Lgs_notc:
	s_cmp_eq_u32 s4, 2
	s_cbranch_scc0 .Lgs_done
	s_cmp_lt_u32 s2, 32
	s_cbranch_scc0 .Lgs_done
	s_mov_b32 s6, s2
	v_lshlrev_b32_e32 v236, 3, v168
	s_lshr_b32 s7, s6, 4
	s_and_b32 s8, s6, 15
	s_mul_i32 s8, s8, 66
	s_mul_i32 s9, s7, 1056
	s_add_u32 s8, s8, s9
	s_cmp_eq_u32 s7, 0
	s_cselect_b32 s9, 64, 65
	s_cselect_b32 s10, 1, -1
	s_mov_b32 s11, 0x7fff0000
	s_movk_i32 s14, 66
	s_cselect_b32 s11, s14, s11
	s_add_u32 s9, s9, s8
	s_add_u32 s11, s11, s8
	v_cmp_gt_u32_e32 vcc, 2, v168
	v_add_u32_e32 v220, 64, v168
	v_add_u32_e32 v221, -2, v168
	v_cndmask_b32_e32 v220, v221, v220, vcc
	v_sub_u32_e32 v221, 65, v168
	s_cmp_eq_u32 s7, 0
	s_cselect_b64 s[18:19], -1, 0
	v_and_b32_e32 v222, 1, v168
	v_cndmask_b32_e64 v220, v221, v220, s[18:19]
	v_add_u32_e32 v223, 62, v222
	v_sub_u32_e32 v224, 1, v222
	v_cndmask_b32_e64 v223, v224, v223, s[18:19]
	v_add_u32_e32 v220, s8, v220
	v_add_u32_e32 v223, s8, v223
	v_lshlrev_b32_e32 v220, 3, v220
	v_lshlrev_b32_e32 v223, 3, v223
	s_waitcnt lgkmcnt(0)
	global_load_dwordx2 v[232:233], v220, s[72:73]
	global_load_dwordx2 v[234:235], v223, s[72:73]
	v_mov_b32_e32 v0, 0
	v_mov_b32_e32 v1, 0
	v_mov_b32_e32 v228, 0xf149f2ca
	s_waitcnt lgkmcnt(0)
	s_mov_b32 s12, s9
	s_mov_b32 s13, s9
	s_lshl_b32 s14, s12, 9
	s_add_u32 s16, s68, s14
	s_addc_u32 s17, s69, 0
	global_load_dwordx2 v[8:9], v236, s[16:17]
	s_add_i32 s12, s12, s10
	s_cmp_eq_u32 s12, s11
	s_cselect_b32 s12, s8, s12
	s_lshl_b32 s14, s12, 9
	s_add_u32 s16, s68, s14
	s_addc_u32 s17, s69, 0
	global_load_dwordx2 v[10:11], v236, s[16:17]
	s_add_i32 s12, s12, s10
	s_cmp_eq_u32 s12, s11
	s_cselect_b32 s12, s8, s12
	s_lshl_b32 s14, s12, 9
	s_add_u32 s16, s68, s14
	s_addc_u32 s17, s69, 0
	global_load_dwordx2 v[12:13], v236, s[16:17]
	s_add_i32 s12, s12, s10
	s_cmp_eq_u32 s12, s11
	s_cselect_b32 s12, s8, s12
	s_lshl_b32 s14, s12, 9
	s_add_u32 s16, s68, s14
	s_addc_u32 s17, s69, 0
	global_load_dwordx2 v[14:15], v236, s[16:17]
	s_add_i32 s12, s12, s10
	s_cmp_eq_u32 s12, s11
	s_cselect_b32 s12, s8, s12
	s_lshl_b32 s14, s12, 9
	s_add_u32 s16, s68, s14
	s_addc_u32 s17, s69, 0
	global_load_dwordx2 v[16:17], v236, s[16:17]
	s_add_i32 s12, s12, s10
	s_cmp_eq_u32 s12, s11
	s_cselect_b32 s12, s8, s12
	s_lshl_b32 s14, s12, 9
	s_add_u32 s16, s68, s14
	s_addc_u32 s17, s69, 0
	global_load_dwordx2 v[18:19], v236, s[16:17]
	s_add_i32 s12, s12, s10
	s_cmp_eq_u32 s12, s11
	s_cselect_b32 s12, s8, s12
	s_lshl_b32 s14, s12, 9
	s_add_u32 s16, s68, s14
	s_addc_u32 s17, s69, 0
	global_load_dwordx2 v[20:21], v236, s[16:17]
	s_add_i32 s12, s12, s10
	s_cmp_eq_u32 s12, s11
	s_cselect_b32 s12, s8, s12
	s_lshl_b32 s14, s12, 9
	s_add_u32 s16, s68, s14
	s_addc_u32 s17, s69, 0
	global_load_dwordx2 v[22:23], v236, s[16:17]
	s_add_i32 s12, s12, s10
	s_cmp_eq_u32 s12, s11
	s_cselect_b32 s12, s8, s12
	s_lshl_b32 s14, s12, 9
	s_add_u32 s16, s68, s14
	s_addc_u32 s17, s69, 0
	global_load_dwordx2 v[24:25], v236, s[16:17]
	s_add_i32 s12, s12, s10
	s_cmp_eq_u32 s12, s11
	s_cselect_b32 s12, s8, s12
	s_lshl_b32 s14, s12, 9
	s_add_u32 s16, s68, s14
	s_addc_u32 s17, s69, 0
	global_load_dwordx2 v[26:27], v236, s[16:17]
	s_add_i32 s12, s12, s10
	s_cmp_eq_u32 s12, s11
	s_cselect_b32 s12, s8, s12
	s_lshl_b32 s14, s12, 9
	s_add_u32 s16, s68, s14
	s_addc_u32 s17, s69, 0
	global_load_dwordx2 v[28:29], v236, s[16:17]
	s_add_i32 s12, s12, s10
	s_cmp_eq_u32 s12, s11
	s_cselect_b32 s12, s8, s12
	s_lshl_b32 s14, s12, 9
	s_add_u32 s16, s68, s14
	s_addc_u32 s17, s69, 0
	global_load_dwordx2 v[30:31], v236, s[16:17]
	s_add_i32 s12, s12, s10
	s_cmp_eq_u32 s12, s11
	s_cselect_b32 s12, s8, s12
	s_lshl_b32 s14, s12, 9
	s_add_u32 s16, s68, s14
	s_addc_u32 s17, s69, 0
	global_load_dwordx2 v[32:33], v236, s[16:17]
	s_add_i32 s12, s12, s10
	s_cmp_eq_u32 s12, s11
	s_cselect_b32 s12, s8, s12
	s_lshl_b32 s14, s12, 9
	s_add_u32 s16, s68, s14
	s_addc_u32 s17, s69, 0
	global_load_dwordx2 v[34:35], v236, s[16:17]
	s_add_i32 s12, s12, s10
	s_cmp_eq_u32 s12, s11
	s_cselect_b32 s12, s8, s12
	s_lshl_b32 s14, s12, 9
	s_add_u32 s16, s68, s14
	s_addc_u32 s17, s69, 0
	global_load_dwordx2 v[36:37], v236, s[16:17]
	s_add_i32 s12, s12, s10
	s_cmp_eq_u32 s12, s11
	s_cselect_b32 s12, s8, s12
	s_lshl_b32 s14, s12, 9
	s_add_u32 s16, s68, s14
	s_addc_u32 s17, s69, 0
	global_load_dwordx2 v[38:39], v236, s[16:17]
	s_add_i32 s12, s12, s10
	s_cmp_eq_u32 s12, s11
	s_cselect_b32 s12, s8, s12
	s_lshl_b32 s14, s12, 9
	s_add_u32 s16, s68, s14
	s_addc_u32 s17, s69, 0
	global_load_dwordx2 v[40:41], v236, s[16:17]
	s_add_i32 s12, s12, s10
	s_cmp_eq_u32 s12, s11
	s_cselect_b32 s12, s8, s12
	s_lshl_b32 s14, s12, 9
	s_add_u32 s16, s68, s14
	s_addc_u32 s17, s69, 0
	global_load_dwordx2 v[42:43], v236, s[16:17]
	s_add_i32 s12, s12, s10
	s_cmp_eq_u32 s12, s11
	s_cselect_b32 s12, s8, s12
	s_lshl_b32 s14, s12, 9
	s_add_u32 s16, s68, s14
	s_addc_u32 s17, s69, 0
	global_load_dwordx2 v[44:45], v236, s[16:17]
	s_add_i32 s12, s12, s10
	s_cmp_eq_u32 s12, s11
	s_cselect_b32 s12, s8, s12
	s_lshl_b32 s14, s12, 9
	s_add_u32 s16, s68, s14
	s_addc_u32 s17, s69, 0
	global_load_dwordx2 v[46:47], v236, s[16:17]
	s_add_i32 s12, s12, s10
	s_cmp_eq_u32 s12, s11
	s_cselect_b32 s12, s8, s12
	s_lshl_b32 s14, s12, 9
	s_add_u32 s16, s68, s14
	s_addc_u32 s17, s69, 0
	global_load_dwordx2 v[48:49], v236, s[16:17]
	s_add_i32 s12, s12, s10
	s_cmp_eq_u32 s12, s11
	s_cselect_b32 s12, s8, s12
	s_lshl_b32 s14, s12, 9
	s_add_u32 s16, s68, s14
	s_addc_u32 s17, s69, 0
	global_load_dwordx2 v[50:51], v236, s[16:17]
	s_add_i32 s12, s12, s10
	s_cmp_eq_u32 s12, s11
	s_cselect_b32 s12, s8, s12
	s_lshl_b32 s14, s12, 9
	s_add_u32 s16, s68, s14
	s_addc_u32 s17, s69, 0
	global_load_dwordx2 v[52:53], v236, s[16:17]
	s_add_i32 s12, s12, s10
	s_cmp_eq_u32 s12, s11
	s_cselect_b32 s12, s8, s12
	s_lshl_b32 s14, s12, 9
	s_add_u32 s16, s68, s14
	s_addc_u32 s17, s69, 0
	global_load_dwordx2 v[54:55], v236, s[16:17]
	s_add_i32 s12, s12, s10
	s_cmp_eq_u32 s12, s11
	s_cselect_b32 s12, s8, s12
	s_lshl_b32 s14, s12, 9
	s_add_u32 s16, s68, s14
	s_addc_u32 s17, s69, 0
	global_load_dwordx2 v[56:57], v236, s[16:17]
	s_add_i32 s12, s12, s10
	s_cmp_eq_u32 s12, s11
	s_cselect_b32 s12, s8, s12
	s_lshl_b32 s14, s12, 9
	s_add_u32 s16, s68, s14
	s_addc_u32 s17, s69, 0
	global_load_dwordx2 v[58:59], v236, s[16:17]
	s_add_i32 s12, s12, s10
	s_cmp_eq_u32 s12, s11
	s_cselect_b32 s12, s8, s12
	s_lshl_b32 s14, s12, 9
	s_add_u32 s16, s68, s14
	s_addc_u32 s17, s69, 0
	global_load_dwordx2 v[60:61], v236, s[16:17]
	s_add_i32 s12, s12, s10
	s_cmp_eq_u32 s12, s11
	s_cselect_b32 s12, s8, s12
	s_lshl_b32 s14, s12, 9
	s_add_u32 s16, s68, s14
	s_addc_u32 s17, s69, 0
	global_load_dwordx2 v[62:63], v236, s[16:17]
	s_add_i32 s12, s12, s10
	s_cmp_eq_u32 s12, s11
	s_cselect_b32 s12, s8, s12
	s_lshl_b32 s14, s12, 9
	s_add_u32 s16, s68, s14
	s_addc_u32 s17, s69, 0
	global_load_dwordx2 v[64:65], v236, s[16:17]
	s_add_i32 s12, s12, s10
	s_cmp_eq_u32 s12, s11
	s_cselect_b32 s12, s8, s12
	s_lshl_b32 s14, s12, 9
	s_add_u32 s16, s68, s14
	s_addc_u32 s17, s69, 0
	global_load_dwordx2 v[66:67], v236, s[16:17]
	s_add_i32 s12, s12, s10
	s_cmp_eq_u32 s12, s11
	s_cselect_b32 s12, s8, s12
	s_lshl_b32 s14, s12, 9
	s_add_u32 s16, s68, s14
	s_addc_u32 s17, s69, 0
	global_load_dwordx2 v[68:69], v236, s[16:17]
	s_add_i32 s12, s12, s10
	s_cmp_eq_u32 s12, s11
	s_cselect_b32 s12, s8, s12
	s_lshl_b32 s14, s12, 9
	s_add_u32 s16, s68, s14
	s_addc_u32 s17, s69, 0
	global_load_dwordx2 v[70:71], v236, s[16:17]
	s_add_i32 s12, s12, s10
	s_cmp_eq_u32 s12, s11
	s_cselect_b32 s12, s8, s12
	s_lshl_b32 s14, s12, 9
	s_add_u32 s16, s68, s14
	s_addc_u32 s17, s69, 0
	global_load_dwordx2 v[72:73], v236, s[16:17]
	s_add_i32 s12, s12, s10
	s_cmp_eq_u32 s12, s11
	s_cselect_b32 s12, s8, s12
	s_lshl_b32 s14, s12, 9
	s_add_u32 s16, s68, s14
	s_addc_u32 s17, s69, 0
	global_load_dwordx2 v[74:75], v236, s[16:17]
	s_add_i32 s12, s12, s10
	s_cmp_eq_u32 s12, s11
	s_cselect_b32 s12, s8, s12
	s_lshl_b32 s14, s12, 9
	s_add_u32 s16, s68, s14
	s_addc_u32 s17, s69, 0
	global_load_dwordx2 v[76:77], v236, s[16:17]
	s_add_i32 s12, s12, s10
	s_cmp_eq_u32 s12, s11
	s_cselect_b32 s12, s8, s12
	s_lshl_b32 s14, s12, 9
	s_add_u32 s16, s68, s14
	s_addc_u32 s17, s69, 0
	global_load_dwordx2 v[78:79], v236, s[16:17]
	s_add_i32 s12, s12, s10
	s_cmp_eq_u32 s12, s11
	s_cselect_b32 s12, s8, s12
	s_lshl_b32 s14, s12, 9
	s_add_u32 s16, s68, s14
	s_addc_u32 s17, s69, 0
	global_load_dwordx2 v[80:81], v236, s[16:17]
	s_add_i32 s12, s12, s10
	s_cmp_eq_u32 s12, s11
	s_cselect_b32 s12, s8, s12
	s_lshl_b32 s14, s12, 9
	s_add_u32 s16, s68, s14
	s_addc_u32 s17, s69, 0
	global_load_dwordx2 v[82:83], v236, s[16:17]
	s_add_i32 s12, s12, s10
	s_cmp_eq_u32 s12, s11
	s_cselect_b32 s12, s8, s12
	s_lshl_b32 s14, s12, 9
	s_add_u32 s16, s68, s14
	s_addc_u32 s17, s69, 0
	global_load_dwordx2 v[84:85], v236, s[16:17]
	s_add_i32 s12, s12, s10
	s_cmp_eq_u32 s12, s11
	s_cselect_b32 s12, s8, s12
	s_lshl_b32 s14, s12, 9
	s_add_u32 s16, s68, s14
	s_addc_u32 s17, s69, 0
	global_load_dwordx2 v[86:87], v236, s[16:17]
	s_add_i32 s12, s12, s10
	s_cmp_eq_u32 s12, s11
	s_cselect_b32 s12, s8, s12
	s_lshl_b32 s14, s12, 9
	s_add_u32 s16, s68, s14
	s_addc_u32 s17, s69, 0
	global_load_dwordx2 v[88:89], v236, s[16:17]
	s_add_i32 s12, s12, s10
	s_cmp_eq_u32 s12, s11
	s_cselect_b32 s12, s8, s12
	s_lshl_b32 s14, s12, 9
	s_add_u32 s16, s68, s14
	s_addc_u32 s17, s69, 0
	global_load_dwordx2 v[90:91], v236, s[16:17]
	s_add_i32 s12, s12, s10
	s_cmp_eq_u32 s12, s11
	s_cselect_b32 s12, s8, s12
	s_lshl_b32 s14, s12, 9
	s_add_u32 s16, s68, s14
	s_addc_u32 s17, s69, 0
	global_load_dwordx2 v[92:93], v236, s[16:17]
	s_add_i32 s12, s12, s10
	s_cmp_eq_u32 s12, s11
	s_cselect_b32 s12, s8, s12
	s_lshl_b32 s14, s12, 9
	s_add_u32 s16, s68, s14
	s_addc_u32 s17, s69, 0
	global_load_dwordx2 v[94:95], v236, s[16:17]
	s_add_i32 s12, s12, s10
	s_cmp_eq_u32 s12, s11
	s_cselect_b32 s12, s8, s12
	s_lshl_b32 s14, s12, 9
	s_add_u32 s16, s68, s14
	s_addc_u32 s17, s69, 0
	global_load_dwordx2 v[96:97], v236, s[16:17]
	s_add_i32 s12, s12, s10
	s_cmp_eq_u32 s12, s11
	s_cselect_b32 s12, s8, s12
	s_lshl_b32 s14, s12, 9
	s_add_u32 s16, s68, s14
	s_addc_u32 s17, s69, 0
	global_load_dwordx2 v[98:99], v236, s[16:17]
	s_add_i32 s12, s12, s10
	s_cmp_eq_u32 s12, s11
	s_cselect_b32 s12, s8, s12
	s_lshl_b32 s14, s12, 9
	s_add_u32 s16, s68, s14
	s_addc_u32 s17, s69, 0
	global_load_dwordx2 v[100:101], v236, s[16:17]
	s_add_i32 s12, s12, s10
	s_cmp_eq_u32 s12, s11
	s_cselect_b32 s12, s8, s12
	s_lshl_b32 s14, s12, 9
	s_add_u32 s16, s68, s14
	s_addc_u32 s17, s69, 0
	global_load_dwordx2 v[102:103], v236, s[16:17]
	s_add_i32 s12, s12, s10
	s_cmp_eq_u32 s12, s11
	s_cselect_b32 s12, s8, s12
	s_lshl_b32 s14, s12, 9
	s_add_u32 s16, s68, s14
	s_addc_u32 s17, s69, 0
	global_load_dwordx2 v[104:105], v236, s[16:17]
	s_add_i32 s12, s12, s10
	s_cmp_eq_u32 s12, s11
	s_cselect_b32 s12, s8, s12
	s_lshl_b32 s14, s12, 9
	s_add_u32 s16, s68, s14
	s_addc_u32 s17, s69, 0
	global_load_dwordx2 v[106:107], v236, s[16:17]
	s_add_i32 s12, s12, s10
	s_cmp_eq_u32 s12, s11
	s_cselect_b32 s12, s8, s12
	s_lshl_b32 s14, s12, 9
	s_add_u32 s16, s68, s14
	s_addc_u32 s17, s69, 0
	global_load_dwordx2 v[108:109], v236, s[16:17]
	s_add_i32 s12, s12, s10
	s_cmp_eq_u32 s12, s11
	s_cselect_b32 s12, s8, s12
	s_lshl_b32 s14, s12, 9
	s_add_u32 s16, s68, s14
	s_addc_u32 s17, s69, 0
	global_load_dwordx2 v[110:111], v236, s[16:17]
	s_add_i32 s12, s12, s10
	s_cmp_eq_u32 s12, s11
	s_cselect_b32 s12, s8, s12
	s_lshl_b32 s14, s12, 9
	s_add_u32 s16, s68, s14
	s_addc_u32 s17, s69, 0
	global_load_dwordx2 v[112:113], v236, s[16:17]
	s_add_i32 s12, s12, s10
	s_cmp_eq_u32 s12, s11
	s_cselect_b32 s12, s8, s12
	s_lshl_b32 s14, s12, 9
	s_add_u32 s16, s68, s14
	s_addc_u32 s17, s69, 0
	global_load_dwordx2 v[114:115], v236, s[16:17]
	s_add_i32 s12, s12, s10
	s_cmp_eq_u32 s12, s11
	s_cselect_b32 s12, s8, s12
	s_lshl_b32 s14, s12, 9
	s_add_u32 s16, s68, s14
	s_addc_u32 s17, s69, 0
	global_load_dwordx2 v[116:117], v236, s[16:17]
	s_add_i32 s12, s12, s10
	s_cmp_eq_u32 s12, s11
	s_cselect_b32 s12, s8, s12
	s_lshl_b32 s14, s12, 9
	s_add_u32 s16, s68, s14
	s_addc_u32 s17, s69, 0
	global_load_dwordx2 v[118:119], v236, s[16:17]
	s_add_i32 s12, s12, s10
	s_cmp_eq_u32 s12, s11
	s_cselect_b32 s12, s8, s12
	s_lshl_b32 s14, s12, 9
	s_add_u32 s16, s68, s14
	s_addc_u32 s17, s69, 0
	global_load_dwordx2 v[120:121], v236, s[16:17]
	s_add_i32 s12, s12, s10
	s_cmp_eq_u32 s12, s11
	s_cselect_b32 s12, s8, s12
	s_lshl_b32 s14, s12, 9
	s_add_u32 s16, s68, s14
	s_addc_u32 s17, s69, 0
	global_load_dwordx2 v[122:123], v236, s[16:17]
	s_add_i32 s12, s12, s10
	s_cmp_eq_u32 s12, s11
	s_cselect_b32 s12, s8, s12
	s_lshl_b32 s14, s12, 9
	s_add_u32 s16, s68, s14
	s_addc_u32 s17, s69, 0
	global_load_dwordx2 v[124:125], v236, s[16:17]
	s_add_i32 s12, s12, s10
	s_cmp_eq_u32 s12, s11
	s_cselect_b32 s12, s8, s12
	s_lshl_b32 s14, s12, 9
	s_add_u32 s16, s68, s14
	s_addc_u32 s17, s69, 0
	global_load_dwordx2 v[126:127], v236, s[16:17]
	s_add_i32 s12, s12, s10
	s_cmp_eq_u32 s12, s11
	s_cselect_b32 s12, s8, s12
	s_lshl_b32 s14, s12, 9
	s_add_u32 s16, s68, s14
	s_addc_u32 s17, s69, 0
	global_load_dwordx2 v[130:131], v236, s[16:17]
	s_add_i32 s12, s12, s10
	s_cmp_eq_u32 s12, s11
	s_cselect_b32 s12, s8, s12
	s_lshl_b32 s14, s12, 9
	s_add_u32 s16, s68, s14
	s_addc_u32 s17, s69, 0
	global_load_dwordx2 v[132:133], v236, s[16:17]
	s_add_i32 s12, s12, s10
	s_cmp_eq_u32 s12, s11
	s_cselect_b32 s12, s8, s12
	s_lshl_b32 s14, s12, 9
	s_add_u32 s16, s68, s14
	s_addc_u32 s17, s69, 0
	global_load_dwordx2 v[134:135], v236, s[16:17]
	s_add_i32 s12, s12, s10
	s_cmp_eq_u32 s12, s11
	s_cselect_b32 s12, s8, s12
	s_lshl_b32 s14, s12, 9
	s_add_u32 s16, s68, s14
	s_addc_u32 s17, s69, 0
	global_load_dwordx2 v[136:137], v236, s[16:17]
	s_add_i32 s12, s12, s10
	s_cmp_eq_u32 s12, s11
	s_cselect_b32 s12, s8, s12
	s_lshl_b32 s14, s12, 9
	s_add_u32 s16, s68, s14
	s_addc_u32 s17, s69, 0
	global_load_dwordx2 v[138:139], v236, s[16:17]
	s_add_i32 s12, s12, s10
	s_cmp_eq_u32 s12, s11
	s_cselect_b32 s12, s8, s12
	s_lshl_b32 s14, s12, 9
	s_add_u32 s16, s68, s14
	s_addc_u32 s17, s69, 0
	global_load_dwordx2 v[140:141], v236, s[16:17]
	s_add_i32 s12, s12, s10
	s_cmp_eq_u32 s12, s11
	s_cselect_b32 s12, s8, s12
	s_waitcnt vmcnt(0)
	v_mov_b32_e32 v237, 0
	s_lshl_b32 s14, s13, 9
	s_add_u32 s16, s70, s14
	s_addc_u32 s17, s71, 0
	global_store_dwordx2 v236, v[0:1], s[16:17]
	s_lshl_b32 s14, s13, 2
	s_add_u32 s16, s74, s14
	s_addc_u32 s17, s75, 0
	s_mov_b64 exec, 1
	global_store_dword v237, v228, s[16:17]
	s_mov_b64 exec, -1
	v_readlane_b32 s18, v232, 0
	v_readlane_b32 s19, v233, 0
	s_nop 1
	v_add_f32_e32 v231, s18, v228
	v_max_f32_e32 v228, s19, v231
	v_sub_f32_e32 v231, v231, v228
	v_sub_f32_e32 v229, s19, v228
	v_mul_f32_e32 v231, 0x3fb8aa3b, v231
	v_mul_f32_e32 v229, 0x3fb8aa3b, v229
	v_exp_f32_e32 v230, v229
	v_exp_f32_e32 v229, v231
	s_nop 0
	v_mul_f32_e32 v220, v230, v8
	v_mul_f32_e32 v221, v230, v9
	v_fma_f32 v0, v229, v0, v220
	v_fma_f32 v1, v229, v1, v221
	s_add_i32 s13, s13, s10
	s_cmp_eq_u32 s13, s11
	s_cselect_b32 s13, s8, s13
	s_lshl_b32 s14, s13, 9
	s_add_u32 s16, s70, s14
	s_addc_u32 s17, s71, 0
	global_store_dwordx2 v236, v[0:1], s[16:17]
	s_lshl_b32 s14, s13, 2
	s_add_u32 s16, s74, s14
	s_addc_u32 s17, s75, 0
	s_mov_b64 exec, 1
	global_store_dword v237, v228, s[16:17]
	s_mov_b64 exec, -1
	v_readlane_b32 s18, v232, 1
	v_readlane_b32 s19, v233, 1
	s_nop 1
	v_add_f32_e32 v231, s18, v228
	v_max_f32_e32 v228, s19, v231
	v_sub_f32_e32 v231, v231, v228
	v_sub_f32_e32 v229, s19, v228
	v_mul_f32_e32 v231, 0x3fb8aa3b, v231
	v_mul_f32_e32 v229, 0x3fb8aa3b, v229
	v_exp_f32_e32 v230, v229
	v_exp_f32_e32 v229, v231
	s_nop 0
	v_mul_f32_e32 v220, v230, v10
	v_mul_f32_e32 v221, v230, v11
	v_fma_f32 v0, v229, v0, v220
	v_fma_f32 v1, v229, v1, v221
	s_add_i32 s13, s13, s10
	s_cmp_eq_u32 s13, s11
	s_cselect_b32 s13, s8, s13
	s_lshl_b32 s14, s13, 9
	s_add_u32 s16, s70, s14
	s_addc_u32 s17, s71, 0
	global_store_dwordx2 v236, v[0:1], s[16:17]
	s_lshl_b32 s14, s13, 2
	s_add_u32 s16, s74, s14
	s_addc_u32 s17, s75, 0
	s_mov_b64 exec, 1
	global_store_dword v237, v228, s[16:17]
	s_mov_b64 exec, -1
	v_readlane_b32 s18, v232, 2
	v_readlane_b32 s19, v233, 2
	s_nop 1
	v_add_f32_e32 v231, s18, v228
	v_max_f32_e32 v228, s19, v231
	v_sub_f32_e32 v231, v231, v228
	v_sub_f32_e32 v229, s19, v228
	v_mul_f32_e32 v231, 0x3fb8aa3b, v231
	v_mul_f32_e32 v229, 0x3fb8aa3b, v229
	v_exp_f32_e32 v230, v229
	v_exp_f32_e32 v229, v231
	s_nop 0
	v_mul_f32_e32 v220, v230, v12
	v_mul_f32_e32 v221, v230, v13
	v_fma_f32 v0, v229, v0, v220
	v_fma_f32 v1, v229, v1, v221
	s_add_i32 s13, s13, s10
	s_cmp_eq_u32 s13, s11
	s_cselect_b32 s13, s8, s13
	s_lshl_b32 s14, s13, 9
	s_add_u32 s16, s70, s14
	s_addc_u32 s17, s71, 0
	global_store_dwordx2 v236, v[0:1], s[16:17]
	s_lshl_b32 s14, s13, 2
	s_add_u32 s16, s74, s14
	s_addc_u32 s17, s75, 0
	s_mov_b64 exec, 1
	global_store_dword v237, v228, s[16:17]
	s_mov_b64 exec, -1
	v_readlane_b32 s18, v232, 3
	v_readlane_b32 s19, v233, 3
	s_nop 1
	v_add_f32_e32 v231, s18, v228
	v_max_f32_e32 v228, s19, v231
	v_sub_f32_e32 v231, v231, v228
	v_sub_f32_e32 v229, s19, v228
	v_mul_f32_e32 v231, 0x3fb8aa3b, v231
	v_mul_f32_e32 v229, 0x3fb8aa3b, v229
	v_exp_f32_e32 v230, v229
	v_exp_f32_e32 v229, v231
	s_nop 0
	v_mul_f32_e32 v220, v230, v14
	v_mul_f32_e32 v221, v230, v15
	v_fma_f32 v0, v229, v0, v220
	v_fma_f32 v1, v229, v1, v221
	s_add_i32 s13, s13, s10
	s_cmp_eq_u32 s13, s11
	s_cselect_b32 s13, s8, s13
	s_lshl_b32 s14, s13, 9
	s_add_u32 s16, s70, s14
	s_addc_u32 s17, s71, 0
	global_store_dwordx2 v236, v[0:1], s[16:17]
	s_lshl_b32 s14, s13, 2
	s_add_u32 s16, s74, s14
	s_addc_u32 s17, s75, 0
	s_mov_b64 exec, 1
	global_store_dword v237, v228, s[16:17]
	s_mov_b64 exec, -1
	v_readlane_b32 s18, v232, 4
	v_readlane_b32 s19, v233, 4
	s_nop 1
	v_add_f32_e32 v231, s18, v228
	v_max_f32_e32 v228, s19, v231
	v_sub_f32_e32 v231, v231, v228
	v_sub_f32_e32 v229, s19, v228
	v_mul_f32_e32 v231, 0x3fb8aa3b, v231
	v_mul_f32_e32 v229, 0x3fb8aa3b, v229
	v_exp_f32_e32 v230, v229
	v_exp_f32_e32 v229, v231
	s_nop 0
	v_mul_f32_e32 v220, v230, v16
	v_mul_f32_e32 v221, v230, v17
	v_fma_f32 v0, v229, v0, v220
	v_fma_f32 v1, v229, v1, v221
	s_add_i32 s13, s13, s10
	s_cmp_eq_u32 s13, s11
	s_cselect_b32 s13, s8, s13
	s_lshl_b32 s14, s13, 9
	s_add_u32 s16, s70, s14
	s_addc_u32 s17, s71, 0
	global_store_dwordx2 v236, v[0:1], s[16:17]
	s_lshl_b32 s14, s13, 2
	s_add_u32 s16, s74, s14
	s_addc_u32 s17, s75, 0
	s_mov_b64 exec, 1
	global_store_dword v237, v228, s[16:17]
	s_mov_b64 exec, -1
	v_readlane_b32 s18, v232, 5
	v_readlane_b32 s19, v233, 5
	s_nop 1
	v_add_f32_e32 v231, s18, v228
	v_max_f32_e32 v228, s19, v231
	v_sub_f32_e32 v231, v231, v228
	v_sub_f32_e32 v229, s19, v228
	v_mul_f32_e32 v231, 0x3fb8aa3b, v231
	v_mul_f32_e32 v229, 0x3fb8aa3b, v229
	v_exp_f32_e32 v230, v229
	v_exp_f32_e32 v229, v231
	s_nop 0
	v_mul_f32_e32 v220, v230, v18
	v_mul_f32_e32 v221, v230, v19
	v_fma_f32 v0, v229, v0, v220
	v_fma_f32 v1, v229, v1, v221
	s_add_i32 s13, s13, s10
	s_cmp_eq_u32 s13, s11
	s_cselect_b32 s13, s8, s13
	s_lshl_b32 s14, s13, 9
	s_add_u32 s16, s70, s14
	s_addc_u32 s17, s71, 0
	global_store_dwordx2 v236, v[0:1], s[16:17]
	s_lshl_b32 s14, s13, 2
	s_add_u32 s16, s74, s14
	s_addc_u32 s17, s75, 0
	s_mov_b64 exec, 1
	global_store_dword v237, v228, s[16:17]
	s_mov_b64 exec, -1
	v_readlane_b32 s18, v232, 6
	v_readlane_b32 s19, v233, 6
	s_nop 1
	v_add_f32_e32 v231, s18, v228
	v_max_f32_e32 v228, s19, v231
	v_sub_f32_e32 v231, v231, v228
	v_sub_f32_e32 v229, s19, v228
	v_mul_f32_e32 v231, 0x3fb8aa3b, v231
	v_mul_f32_e32 v229, 0x3fb8aa3b, v229
	v_exp_f32_e32 v230, v229
	v_exp_f32_e32 v229, v231
	s_nop 0
	v_mul_f32_e32 v220, v230, v20
	v_mul_f32_e32 v221, v230, v21
	v_fma_f32 v0, v229, v0, v220
	v_fma_f32 v1, v229, v1, v221
	s_add_i32 s13, s13, s10
	s_cmp_eq_u32 s13, s11
	s_cselect_b32 s13, s8, s13
	s_lshl_b32 s14, s13, 9
	s_add_u32 s16, s70, s14
	s_addc_u32 s17, s71, 0
	global_store_dwordx2 v236, v[0:1], s[16:17]
	s_lshl_b32 s14, s13, 2
	s_add_u32 s16, s74, s14
	s_addc_u32 s17, s75, 0
	s_mov_b64 exec, 1
	global_store_dword v237, v228, s[16:17]
	s_mov_b64 exec, -1
	v_readlane_b32 s18, v232, 7
	v_readlane_b32 s19, v233, 7
	s_nop 1
	v_add_f32_e32 v231, s18, v228
	v_max_f32_e32 v228, s19, v231
	v_sub_f32_e32 v231, v231, v228
	v_sub_f32_e32 v229, s19, v228
	v_mul_f32_e32 v231, 0x3fb8aa3b, v231
	v_mul_f32_e32 v229, 0x3fb8aa3b, v229
	v_exp_f32_e32 v230, v229
	v_exp_f32_e32 v229, v231
	s_nop 0
	v_mul_f32_e32 v220, v230, v22
	v_mul_f32_e32 v221, v230, v23
	v_fma_f32 v0, v229, v0, v220
	v_fma_f32 v1, v229, v1, v221
	s_add_i32 s13, s13, s10
	s_cmp_eq_u32 s13, s11
	s_cselect_b32 s13, s8, s13
	s_lshl_b32 s14, s13, 9
	s_add_u32 s16, s70, s14
	s_addc_u32 s17, s71, 0
	global_store_dwordx2 v236, v[0:1], s[16:17]
	s_lshl_b32 s14, s13, 2
	s_add_u32 s16, s74, s14
	s_addc_u32 s17, s75, 0
	s_mov_b64 exec, 1
	global_store_dword v237, v228, s[16:17]
	s_mov_b64 exec, -1
	v_readlane_b32 s18, v232, 8
	v_readlane_b32 s19, v233, 8
	s_nop 1
	v_add_f32_e32 v231, s18, v228
	v_max_f32_e32 v228, s19, v231
	v_sub_f32_e32 v231, v231, v228
	v_sub_f32_e32 v229, s19, v228
	v_mul_f32_e32 v231, 0x3fb8aa3b, v231
	v_mul_f32_e32 v229, 0x3fb8aa3b, v229
	v_exp_f32_e32 v230, v229
	v_exp_f32_e32 v229, v231
	s_nop 0
	v_mul_f32_e32 v220, v230, v24
	v_mul_f32_e32 v221, v230, v25
	v_fma_f32 v0, v229, v0, v220
	v_fma_f32 v1, v229, v1, v221
	s_add_i32 s13, s13, s10
	s_cmp_eq_u32 s13, s11
	s_cselect_b32 s13, s8, s13
	s_lshl_b32 s14, s13, 9
	s_add_u32 s16, s70, s14
	s_addc_u32 s17, s71, 0
	global_store_dwordx2 v236, v[0:1], s[16:17]
	s_lshl_b32 s14, s13, 2
	s_add_u32 s16, s74, s14
	s_addc_u32 s17, s75, 0
	s_mov_b64 exec, 1
	global_store_dword v237, v228, s[16:17]
	s_mov_b64 exec, -1
	v_readlane_b32 s18, v232, 9
	v_readlane_b32 s19, v233, 9
	s_nop 1
	v_add_f32_e32 v231, s18, v228
	v_max_f32_e32 v228, s19, v231
	v_sub_f32_e32 v231, v231, v228
	v_sub_f32_e32 v229, s19, v228
	v_mul_f32_e32 v231, 0x3fb8aa3b, v231
	v_mul_f32_e32 v229, 0x3fb8aa3b, v229
	v_exp_f32_e32 v230, v229
	v_exp_f32_e32 v229, v231
	s_nop 0
	v_mul_f32_e32 v220, v230, v26
	v_mul_f32_e32 v221, v230, v27
	v_fma_f32 v0, v229, v0, v220
	v_fma_f32 v1, v229, v1, v221
	s_add_i32 s13, s13, s10
	s_cmp_eq_u32 s13, s11
	s_cselect_b32 s13, s8, s13
	s_lshl_b32 s14, s13, 9
	s_add_u32 s16, s70, s14
	s_addc_u32 s17, s71, 0
	global_store_dwordx2 v236, v[0:1], s[16:17]
	s_lshl_b32 s14, s13, 2
	s_add_u32 s16, s74, s14
	s_addc_u32 s17, s75, 0
	s_mov_b64 exec, 1
	global_store_dword v237, v228, s[16:17]
	s_mov_b64 exec, -1
	v_readlane_b32 s18, v232, 10
	v_readlane_b32 s19, v233, 10
	s_nop 1
	v_add_f32_e32 v231, s18, v228
	v_max_f32_e32 v228, s19, v231
	v_sub_f32_e32 v231, v231, v228
	v_sub_f32_e32 v229, s19, v228
	v_mul_f32_e32 v231, 0x3fb8aa3b, v231
	v_mul_f32_e32 v229, 0x3fb8aa3b, v229
	v_exp_f32_e32 v230, v229
	v_exp_f32_e32 v229, v231
	s_nop 0
	v_mul_f32_e32 v220, v230, v28
	v_mul_f32_e32 v221, v230, v29
	v_fma_f32 v0, v229, v0, v220
	v_fma_f32 v1, v229, v1, v221
	s_add_i32 s13, s13, s10
	s_cmp_eq_u32 s13, s11
	s_cselect_b32 s13, s8, s13
	s_lshl_b32 s14, s13, 9
	s_add_u32 s16, s70, s14
	s_addc_u32 s17, s71, 0
	global_store_dwordx2 v236, v[0:1], s[16:17]
	s_lshl_b32 s14, s13, 2
	s_add_u32 s16, s74, s14
	s_addc_u32 s17, s75, 0
	s_mov_b64 exec, 1
	global_store_dword v237, v228, s[16:17]
	s_mov_b64 exec, -1
	v_readlane_b32 s18, v232, 11
	v_readlane_b32 s19, v233, 11
	s_nop 1
	v_add_f32_e32 v231, s18, v228
	v_max_f32_e32 v228, s19, v231
	v_sub_f32_e32 v231, v231, v228
	v_sub_f32_e32 v229, s19, v228
	v_mul_f32_e32 v231, 0x3fb8aa3b, v231
	v_mul_f32_e32 v229, 0x3fb8aa3b, v229
	v_exp_f32_e32 v230, v229
	v_exp_f32_e32 v229, v231
	s_nop 0
	v_mul_f32_e32 v220, v230, v30
	v_mul_f32_e32 v221, v230, v31
	v_fma_f32 v0, v229, v0, v220
	v_fma_f32 v1, v229, v1, v221
	s_add_i32 s13, s13, s10
	s_cmp_eq_u32 s13, s11
	s_cselect_b32 s13, s8, s13
	s_lshl_b32 s14, s13, 9
	s_add_u32 s16, s70, s14
	s_addc_u32 s17, s71, 0
	global_store_dwordx2 v236, v[0:1], s[16:17]
	s_lshl_b32 s14, s13, 2
	s_add_u32 s16, s74, s14
	s_addc_u32 s17, s75, 0
	s_mov_b64 exec, 1
	global_store_dword v237, v228, s[16:17]
	s_mov_b64 exec, -1
	v_readlane_b32 s18, v232, 12
	v_readlane_b32 s19, v233, 12
	s_nop 1
	v_add_f32_e32 v231, s18, v228
	v_max_f32_e32 v228, s19, v231
	v_sub_f32_e32 v231, v231, v228
	v_sub_f32_e32 v229, s19, v228
	v_mul_f32_e32 v231, 0x3fb8aa3b, v231
	v_mul_f32_e32 v229, 0x3fb8aa3b, v229
	v_exp_f32_e32 v230, v229
	v_exp_f32_e32 v229, v231
	s_nop 0
	v_mul_f32_e32 v220, v230, v32
	v_mul_f32_e32 v221, v230, v33
	v_fma_f32 v0, v229, v0, v220
	v_fma_f32 v1, v229, v1, v221
	s_add_i32 s13, s13, s10
	s_cmp_eq_u32 s13, s11
	s_cselect_b32 s13, s8, s13
	s_lshl_b32 s14, s13, 9
	s_add_u32 s16, s70, s14
	s_addc_u32 s17, s71, 0
	global_store_dwordx2 v236, v[0:1], s[16:17]
	s_lshl_b32 s14, s13, 2
	s_add_u32 s16, s74, s14
	s_addc_u32 s17, s75, 0
	s_mov_b64 exec, 1
	global_store_dword v237, v228, s[16:17]
	s_mov_b64 exec, -1
	v_readlane_b32 s18, v232, 13
	v_readlane_b32 s19, v233, 13
	s_nop 1
	v_add_f32_e32 v231, s18, v228
	v_max_f32_e32 v228, s19, v231
	v_sub_f32_e32 v231, v231, v228
	v_sub_f32_e32 v229, s19, v228
	v_mul_f32_e32 v231, 0x3fb8aa3b, v231
	v_mul_f32_e32 v229, 0x3fb8aa3b, v229
	v_exp_f32_e32 v230, v229
	v_exp_f32_e32 v229, v231
	s_nop 0
	v_mul_f32_e32 v220, v230, v34
	v_mul_f32_e32 v221, v230, v35
	v_fma_f32 v0, v229, v0, v220
	v_fma_f32 v1, v229, v1, v221
	s_add_i32 s13, s13, s10
	s_cmp_eq_u32 s13, s11
	s_cselect_b32 s13, s8, s13
	s_lshl_b32 s14, s13, 9
	s_add_u32 s16, s70, s14
	s_addc_u32 s17, s71, 0
	global_store_dwordx2 v236, v[0:1], s[16:17]
	s_lshl_b32 s14, s13, 2
	s_add_u32 s16, s74, s14
	s_addc_u32 s17, s75, 0
	s_mov_b64 exec, 1
	global_store_dword v237, v228, s[16:17]
	s_mov_b64 exec, -1
	v_readlane_b32 s18, v232, 14
	v_readlane_b32 s19, v233, 14
	s_nop 1
	v_add_f32_e32 v231, s18, v228
	v_max_f32_e32 v228, s19, v231
	v_sub_f32_e32 v231, v231, v228
	v_sub_f32_e32 v229, s19, v228
	v_mul_f32_e32 v231, 0x3fb8aa3b, v231
	v_mul_f32_e32 v229, 0x3fb8aa3b, v229
	v_exp_f32_e32 v230, v229
	v_exp_f32_e32 v229, v231
	s_nop 0
	v_mul_f32_e32 v220, v230, v36
	v_mul_f32_e32 v221, v230, v37
	v_fma_f32 v0, v229, v0, v220
	v_fma_f32 v1, v229, v1, v221
	s_add_i32 s13, s13, s10
	s_cmp_eq_u32 s13, s11
	s_cselect_b32 s13, s8, s13
	s_lshl_b32 s14, s13, 9
	s_add_u32 s16, s70, s14
	s_addc_u32 s17, s71, 0
	global_store_dwordx2 v236, v[0:1], s[16:17]
	s_lshl_b32 s14, s13, 2
	s_add_u32 s16, s74, s14
	s_addc_u32 s17, s75, 0
	s_mov_b64 exec, 1
	global_store_dword v237, v228, s[16:17]
	s_mov_b64 exec, -1
	v_readlane_b32 s18, v232, 15
	v_readlane_b32 s19, v233, 15
	s_nop 1
	v_add_f32_e32 v231, s18, v228
	v_max_f32_e32 v228, s19, v231
	v_sub_f32_e32 v231, v231, v228
	v_sub_f32_e32 v229, s19, v228
	v_mul_f32_e32 v231, 0x3fb8aa3b, v231
	v_mul_f32_e32 v229, 0x3fb8aa3b, v229
	v_exp_f32_e32 v230, v229
	v_exp_f32_e32 v229, v231
	s_nop 0
	v_mul_f32_e32 v220, v230, v38
	v_mul_f32_e32 v221, v230, v39
	v_fma_f32 v0, v229, v0, v220
	v_fma_f32 v1, v229, v1, v221
	s_add_i32 s13, s13, s10
	s_cmp_eq_u32 s13, s11
	s_cselect_b32 s13, s8, s13
	s_lshl_b32 s14, s13, 9
	s_add_u32 s16, s70, s14
	s_addc_u32 s17, s71, 0
	global_store_dwordx2 v236, v[0:1], s[16:17]
	s_lshl_b32 s14, s13, 2
	s_add_u32 s16, s74, s14
	s_addc_u32 s17, s75, 0
	s_mov_b64 exec, 1
	global_store_dword v237, v228, s[16:17]
	s_mov_b64 exec, -1
	v_readlane_b32 s18, v232, 16
	v_readlane_b32 s19, v233, 16
	s_nop 1
	v_add_f32_e32 v231, s18, v228
	v_max_f32_e32 v228, s19, v231
	v_sub_f32_e32 v231, v231, v228
	v_sub_f32_e32 v229, s19, v228
	v_mul_f32_e32 v231, 0x3fb8aa3b, v231
	v_mul_f32_e32 v229, 0x3fb8aa3b, v229
	v_exp_f32_e32 v230, v229
	v_exp_f32_e32 v229, v231
	s_nop 0
	v_mul_f32_e32 v220, v230, v40
	v_mul_f32_e32 v221, v230, v41
	v_fma_f32 v0, v229, v0, v220
	v_fma_f32 v1, v229, v1, v221
	s_add_i32 s13, s13, s10
	s_cmp_eq_u32 s13, s11
	s_cselect_b32 s13, s8, s13
	s_lshl_b32 s14, s13, 9
	s_add_u32 s16, s70, s14
	s_addc_u32 s17, s71, 0
	global_store_dwordx2 v236, v[0:1], s[16:17]
	s_lshl_b32 s14, s13, 2
	s_add_u32 s16, s74, s14
	s_addc_u32 s17, s75, 0
	s_mov_b64 exec, 1
	global_store_dword v237, v228, s[16:17]
	s_mov_b64 exec, -1
	v_readlane_b32 s18, v232, 17
	v_readlane_b32 s19, v233, 17
	s_nop 1
	v_add_f32_e32 v231, s18, v228
	v_max_f32_e32 v228, s19, v231
	v_sub_f32_e32 v231, v231, v228
	v_sub_f32_e32 v229, s19, v228
	v_mul_f32_e32 v231, 0x3fb8aa3b, v231
	v_mul_f32_e32 v229, 0x3fb8aa3b, v229
	v_exp_f32_e32 v230, v229
	v_exp_f32_e32 v229, v231
	s_nop 0
	v_mul_f32_e32 v220, v230, v42
	v_mul_f32_e32 v221, v230, v43
	v_fma_f32 v0, v229, v0, v220
	v_fma_f32 v1, v229, v1, v221
	s_add_i32 s13, s13, s10
	s_cmp_eq_u32 s13, s11
	s_cselect_b32 s13, s8, s13
	s_lshl_b32 s14, s13, 9
	s_add_u32 s16, s70, s14
	s_addc_u32 s17, s71, 0
	global_store_dwordx2 v236, v[0:1], s[16:17]
	s_lshl_b32 s14, s13, 2
	s_add_u32 s16, s74, s14
	s_addc_u32 s17, s75, 0
	s_mov_b64 exec, 1
	global_store_dword v237, v228, s[16:17]
	s_mov_b64 exec, -1
	v_readlane_b32 s18, v232, 18
	v_readlane_b32 s19, v233, 18
	s_nop 1
	v_add_f32_e32 v231, s18, v228
	v_max_f32_e32 v228, s19, v231
	v_sub_f32_e32 v231, v231, v228
	v_sub_f32_e32 v229, s19, v228
	v_mul_f32_e32 v231, 0x3fb8aa3b, v231
	v_mul_f32_e32 v229, 0x3fb8aa3b, v229
	v_exp_f32_e32 v230, v229
	v_exp_f32_e32 v229, v231
	s_nop 0
	v_mul_f32_e32 v220, v230, v44
	v_mul_f32_e32 v221, v230, v45
	v_fma_f32 v0, v229, v0, v220
	v_fma_f32 v1, v229, v1, v221
	s_add_i32 s13, s13, s10
	s_cmp_eq_u32 s13, s11
	s_cselect_b32 s13, s8, s13
	s_lshl_b32 s14, s13, 9
	s_add_u32 s16, s70, s14
	s_addc_u32 s17, s71, 0
	global_store_dwordx2 v236, v[0:1], s[16:17]
	s_lshl_b32 s14, s13, 2
	s_add_u32 s16, s74, s14
	s_addc_u32 s17, s75, 0
	s_mov_b64 exec, 1
	global_store_dword v237, v228, s[16:17]
	s_mov_b64 exec, -1
	v_readlane_b32 s18, v232, 19
	v_readlane_b32 s19, v233, 19
	s_nop 1
	v_add_f32_e32 v231, s18, v228
	v_max_f32_e32 v228, s19, v231
	v_sub_f32_e32 v231, v231, v228
	v_sub_f32_e32 v229, s19, v228
	v_mul_f32_e32 v231, 0x3fb8aa3b, v231
	v_mul_f32_e32 v229, 0x3fb8aa3b, v229
	v_exp_f32_e32 v230, v229
	v_exp_f32_e32 v229, v231
	s_nop 0
	v_mul_f32_e32 v220, v230, v46
	v_mul_f32_e32 v221, v230, v47
	v_fma_f32 v0, v229, v0, v220
	v_fma_f32 v1, v229, v1, v221
	s_add_i32 s13, s13, s10
	s_cmp_eq_u32 s13, s11
	s_cselect_b32 s13, s8, s13
	s_lshl_b32 s14, s13, 9
	s_add_u32 s16, s70, s14
	s_addc_u32 s17, s71, 0
	global_store_dwordx2 v236, v[0:1], s[16:17]
	s_lshl_b32 s14, s13, 2
	s_add_u32 s16, s74, s14
	s_addc_u32 s17, s75, 0
	s_mov_b64 exec, 1
	global_store_dword v237, v228, s[16:17]
	s_mov_b64 exec, -1
	v_readlane_b32 s18, v232, 20
	v_readlane_b32 s19, v233, 20
	s_nop 1
	v_add_f32_e32 v231, s18, v228
	v_max_f32_e32 v228, s19, v231
	v_sub_f32_e32 v231, v231, v228
	v_sub_f32_e32 v229, s19, v228
	v_mul_f32_e32 v231, 0x3fb8aa3b, v231
	v_mul_f32_e32 v229, 0x3fb8aa3b, v229
	v_exp_f32_e32 v230, v229
	v_exp_f32_e32 v229, v231
	s_nop 0
	v_mul_f32_e32 v220, v230, v48
	v_mul_f32_e32 v221, v230, v49
	v_fma_f32 v0, v229, v0, v220
	v_fma_f32 v1, v229, v1, v221
	s_add_i32 s13, s13, s10
	s_cmp_eq_u32 s13, s11
	s_cselect_b32 s13, s8, s13
	s_lshl_b32 s14, s13, 9
	s_add_u32 s16, s70, s14
	s_addc_u32 s17, s71, 0
	global_store_dwordx2 v236, v[0:1], s[16:17]
	s_lshl_b32 s14, s13, 2
	s_add_u32 s16, s74, s14
	s_addc_u32 s17, s75, 0
	s_mov_b64 exec, 1
	global_store_dword v237, v228, s[16:17]
	s_mov_b64 exec, -1
	v_readlane_b32 s18, v232, 21
	v_readlane_b32 s19, v233, 21
	s_nop 1
	v_add_f32_e32 v231, s18, v228
	v_max_f32_e32 v228, s19, v231
	v_sub_f32_e32 v231, v231, v228
	v_sub_f32_e32 v229, s19, v228
	v_mul_f32_e32 v231, 0x3fb8aa3b, v231
	v_mul_f32_e32 v229, 0x3fb8aa3b, v229
	v_exp_f32_e32 v230, v229
	v_exp_f32_e32 v229, v231
	s_nop 0
	v_mul_f32_e32 v220, v230, v50
	v_mul_f32_e32 v221, v230, v51
	v_fma_f32 v0, v229, v0, v220
	v_fma_f32 v1, v229, v1, v221
	s_add_i32 s13, s13, s10
	s_cmp_eq_u32 s13, s11
	s_cselect_b32 s13, s8, s13
	s_lshl_b32 s14, s13, 9
	s_add_u32 s16, s70, s14
	s_addc_u32 s17, s71, 0
	global_store_dwordx2 v236, v[0:1], s[16:17]
	s_lshl_b32 s14, s13, 2
	s_add_u32 s16, s74, s14
	s_addc_u32 s17, s75, 0
	s_mov_b64 exec, 1
	global_store_dword v237, v228, s[16:17]
	s_mov_b64 exec, -1
	v_readlane_b32 s18, v232, 22
	v_readlane_b32 s19, v233, 22
	s_nop 1
	v_add_f32_e32 v231, s18, v228
	v_max_f32_e32 v228, s19, v231
	v_sub_f32_e32 v231, v231, v228
	v_sub_f32_e32 v229, s19, v228
	v_mul_f32_e32 v231, 0x3fb8aa3b, v231
	v_mul_f32_e32 v229, 0x3fb8aa3b, v229
	v_exp_f32_e32 v230, v229
	v_exp_f32_e32 v229, v231
	s_nop 0
	v_mul_f32_e32 v220, v230, v52
	v_mul_f32_e32 v221, v230, v53
	v_fma_f32 v0, v229, v0, v220
	v_fma_f32 v1, v229, v1, v221
	s_add_i32 s13, s13, s10
	s_cmp_eq_u32 s13, s11
	s_cselect_b32 s13, s8, s13
	s_lshl_b32 s14, s13, 9
	s_add_u32 s16, s70, s14
	s_addc_u32 s17, s71, 0
	global_store_dwordx2 v236, v[0:1], s[16:17]
	s_lshl_b32 s14, s13, 2
	s_add_u32 s16, s74, s14
	s_addc_u32 s17, s75, 0
	s_mov_b64 exec, 1
	global_store_dword v237, v228, s[16:17]
	s_mov_b64 exec, -1
	v_readlane_b32 s18, v232, 23
	v_readlane_b32 s19, v233, 23
	s_nop 1
	v_add_f32_e32 v231, s18, v228
	v_max_f32_e32 v228, s19, v231
	v_sub_f32_e32 v231, v231, v228
	v_sub_f32_e32 v229, s19, v228
	v_mul_f32_e32 v231, 0x3fb8aa3b, v231
	v_mul_f32_e32 v229, 0x3fb8aa3b, v229
	v_exp_f32_e32 v230, v229
	v_exp_f32_e32 v229, v231
	s_nop 0
	v_mul_f32_e32 v220, v230, v54
	v_mul_f32_e32 v221, v230, v55
	v_fma_f32 v0, v229, v0, v220
	v_fma_f32 v1, v229, v1, v221
	s_add_i32 s13, s13, s10
	s_cmp_eq_u32 s13, s11
	s_cselect_b32 s13, s8, s13
	s_lshl_b32 s14, s13, 9
	s_add_u32 s16, s70, s14
	s_addc_u32 s17, s71, 0
	global_store_dwordx2 v236, v[0:1], s[16:17]
	s_lshl_b32 s14, s13, 2
	s_add_u32 s16, s74, s14
	s_addc_u32 s17, s75, 0
	s_mov_b64 exec, 1
	global_store_dword v237, v228, s[16:17]
	s_mov_b64 exec, -1
	v_readlane_b32 s18, v232, 24
	v_readlane_b32 s19, v233, 24
	s_nop 1
	v_add_f32_e32 v231, s18, v228
	v_max_f32_e32 v228, s19, v231
	v_sub_f32_e32 v231, v231, v228
	v_sub_f32_e32 v229, s19, v228
	v_mul_f32_e32 v231, 0x3fb8aa3b, v231
	v_mul_f32_e32 v229, 0x3fb8aa3b, v229
	v_exp_f32_e32 v230, v229
	v_exp_f32_e32 v229, v231
	s_nop 0
	v_mul_f32_e32 v220, v230, v56
	v_mul_f32_e32 v221, v230, v57
	v_fma_f32 v0, v229, v0, v220
	v_fma_f32 v1, v229, v1, v221
	s_add_i32 s13, s13, s10
	s_cmp_eq_u32 s13, s11
	s_cselect_b32 s13, s8, s13
	s_lshl_b32 s14, s13, 9
	s_add_u32 s16, s70, s14
	s_addc_u32 s17, s71, 0
	global_store_dwordx2 v236, v[0:1], s[16:17]
	s_lshl_b32 s14, s13, 2
	s_add_u32 s16, s74, s14
	s_addc_u32 s17, s75, 0
	s_mov_b64 exec, 1
	global_store_dword v237, v228, s[16:17]
	s_mov_b64 exec, -1
	v_readlane_b32 s18, v232, 25
	v_readlane_b32 s19, v233, 25
	s_nop 1
	v_add_f32_e32 v231, s18, v228
	v_max_f32_e32 v228, s19, v231
	v_sub_f32_e32 v231, v231, v228
	v_sub_f32_e32 v229, s19, v228
	v_mul_f32_e32 v231, 0x3fb8aa3b, v231
	v_mul_f32_e32 v229, 0x3fb8aa3b, v229
	v_exp_f32_e32 v230, v229
	v_exp_f32_e32 v229, v231
	s_nop 0
	v_mul_f32_e32 v220, v230, v58
	v_mul_f32_e32 v221, v230, v59
	v_fma_f32 v0, v229, v0, v220
	v_fma_f32 v1, v229, v1, v221
	s_add_i32 s13, s13, s10
	s_cmp_eq_u32 s13, s11
	s_cselect_b32 s13, s8, s13
	s_lshl_b32 s14, s13, 9
	s_add_u32 s16, s70, s14
	s_addc_u32 s17, s71, 0
	global_store_dwordx2 v236, v[0:1], s[16:17]
	s_lshl_b32 s14, s13, 2
	s_add_u32 s16, s74, s14
	s_addc_u32 s17, s75, 0
	s_mov_b64 exec, 1
	global_store_dword v237, v228, s[16:17]
	s_mov_b64 exec, -1
	v_readlane_b32 s18, v232, 26
	v_readlane_b32 s19, v233, 26
	s_nop 1
	v_add_f32_e32 v231, s18, v228
	v_max_f32_e32 v228, s19, v231
	v_sub_f32_e32 v231, v231, v228
	v_sub_f32_e32 v229, s19, v228
	v_mul_f32_e32 v231, 0x3fb8aa3b, v231
	v_mul_f32_e32 v229, 0x3fb8aa3b, v229
	v_exp_f32_e32 v230, v229
	v_exp_f32_e32 v229, v231
	s_nop 0
	v_mul_f32_e32 v220, v230, v60
	v_mul_f32_e32 v221, v230, v61
	v_fma_f32 v0, v229, v0, v220
	v_fma_f32 v1, v229, v1, v221
	s_add_i32 s13, s13, s10
	s_cmp_eq_u32 s13, s11
	s_cselect_b32 s13, s8, s13
	s_lshl_b32 s14, s13, 9
	s_add_u32 s16, s70, s14
	s_addc_u32 s17, s71, 0
	global_store_dwordx2 v236, v[0:1], s[16:17]
	s_lshl_b32 s14, s13, 2
	s_add_u32 s16, s74, s14
	s_addc_u32 s17, s75, 0
	s_mov_b64 exec, 1
	global_store_dword v237, v228, s[16:17]
	s_mov_b64 exec, -1
	v_readlane_b32 s18, v232, 27
	v_readlane_b32 s19, v233, 27
	s_nop 1
	v_add_f32_e32 v231, s18, v228
	v_max_f32_e32 v228, s19, v231
	v_sub_f32_e32 v231, v231, v228
	v_sub_f32_e32 v229, s19, v228
	v_mul_f32_e32 v231, 0x3fb8aa3b, v231
	v_mul_f32_e32 v229, 0x3fb8aa3b, v229
	v_exp_f32_e32 v230, v229
	v_exp_f32_e32 v229, v231
	s_nop 0
	v_mul_f32_e32 v220, v230, v62
	v_mul_f32_e32 v221, v230, v63
	v_fma_f32 v0, v229, v0, v220
	v_fma_f32 v1, v229, v1, v221
	s_add_i32 s13, s13, s10
	s_cmp_eq_u32 s13, s11
	s_cselect_b32 s13, s8, s13
	s_lshl_b32 s14, s13, 9
	s_add_u32 s16, s70, s14
	s_addc_u32 s17, s71, 0
	global_store_dwordx2 v236, v[0:1], s[16:17]
	s_lshl_b32 s14, s13, 2
	s_add_u32 s16, s74, s14
	s_addc_u32 s17, s75, 0
	s_mov_b64 exec, 1
	global_store_dword v237, v228, s[16:17]
	s_mov_b64 exec, -1
	v_readlane_b32 s18, v232, 28
	v_readlane_b32 s19, v233, 28
	s_nop 1
	v_add_f32_e32 v231, s18, v228
	v_max_f32_e32 v228, s19, v231
	v_sub_f32_e32 v231, v231, v228
	v_sub_f32_e32 v229, s19, v228
	v_mul_f32_e32 v231, 0x3fb8aa3b, v231
	v_mul_f32_e32 v229, 0x3fb8aa3b, v229
	v_exp_f32_e32 v230, v229
	v_exp_f32_e32 v229, v231
	s_nop 0
	v_mul_f32_e32 v220, v230, v64
	v_mul_f32_e32 v221, v230, v65
	v_fma_f32 v0, v229, v0, v220
	v_fma_f32 v1, v229, v1, v221
	s_add_i32 s13, s13, s10
	s_cmp_eq_u32 s13, s11
	s_cselect_b32 s13, s8, s13
	s_lshl_b32 s14, s13, 9
	s_add_u32 s16, s70, s14
	s_addc_u32 s17, s71, 0
	global_store_dwordx2 v236, v[0:1], s[16:17]
	s_lshl_b32 s14, s13, 2
	s_add_u32 s16, s74, s14
	s_addc_u32 s17, s75, 0
	s_mov_b64 exec, 1
	global_store_dword v237, v228, s[16:17]
	s_mov_b64 exec, -1
	v_readlane_b32 s18, v232, 29
	v_readlane_b32 s19, v233, 29
	s_nop 1
	v_add_f32_e32 v231, s18, v228
	v_max_f32_e32 v228, s19, v231
	v_sub_f32_e32 v231, v231, v228
	v_sub_f32_e32 v229, s19, v228
	v_mul_f32_e32 v231, 0x3fb8aa3b, v231
	v_mul_f32_e32 v229, 0x3fb8aa3b, v229
	v_exp_f32_e32 v230, v229
	v_exp_f32_e32 v229, v231
	s_nop 0
	v_mul_f32_e32 v220, v230, v66
	v_mul_f32_e32 v221, v230, v67
	v_fma_f32 v0, v229, v0, v220
	v_fma_f32 v1, v229, v1, v221
	s_add_i32 s13, s13, s10
	s_cmp_eq_u32 s13, s11
	s_cselect_b32 s13, s8, s13
	s_lshl_b32 s14, s13, 9
	s_add_u32 s16, s70, s14
	s_addc_u32 s17, s71, 0
	global_store_dwordx2 v236, v[0:1], s[16:17]
	s_lshl_b32 s14, s13, 2
	s_add_u32 s16, s74, s14
	s_addc_u32 s17, s75, 0
	s_mov_b64 exec, 1
	global_store_dword v237, v228, s[16:17]
	s_mov_b64 exec, -1
	v_readlane_b32 s18, v232, 30
	v_readlane_b32 s19, v233, 30
	s_nop 1
	v_add_f32_e32 v231, s18, v228
	v_max_f32_e32 v228, s19, v231
	v_sub_f32_e32 v231, v231, v228
	v_sub_f32_e32 v229, s19, v228
	v_mul_f32_e32 v231, 0x3fb8aa3b, v231
	v_mul_f32_e32 v229, 0x3fb8aa3b, v229
	v_exp_f32_e32 v230, v229
	v_exp_f32_e32 v229, v231
	s_nop 0
	v_mul_f32_e32 v220, v230, v68
	v_mul_f32_e32 v221, v230, v69
	v_fma_f32 v0, v229, v0, v220
	v_fma_f32 v1, v229, v1, v221
	s_add_i32 s13, s13, s10
	s_cmp_eq_u32 s13, s11
	s_cselect_b32 s13, s8, s13
	s_lshl_b32 s14, s13, 9
	s_add_u32 s16, s70, s14
	s_addc_u32 s17, s71, 0
	global_store_dwordx2 v236, v[0:1], s[16:17]
	s_lshl_b32 s14, s13, 2
	s_add_u32 s16, s74, s14
	s_addc_u32 s17, s75, 0
	s_mov_b64 exec, 1
	global_store_dword v237, v228, s[16:17]
	s_mov_b64 exec, -1
	v_readlane_b32 s18, v232, 31
	v_readlane_b32 s19, v233, 31
	s_nop 1
	v_add_f32_e32 v231, s18, v228
	v_max_f32_e32 v228, s19, v231
	v_sub_f32_e32 v231, v231, v228
	v_sub_f32_e32 v229, s19, v228
	v_mul_f32_e32 v231, 0x3fb8aa3b, v231
	v_mul_f32_e32 v229, 0x3fb8aa3b, v229
	v_exp_f32_e32 v230, v229
	v_exp_f32_e32 v229, v231
	s_nop 0
	v_mul_f32_e32 v220, v230, v70
	v_mul_f32_e32 v221, v230, v71
	v_fma_f32 v0, v229, v0, v220
	v_fma_f32 v1, v229, v1, v221
	s_add_i32 s13, s13, s10
	s_cmp_eq_u32 s13, s11
	s_cselect_b32 s13, s8, s13
	s_lshl_b32 s14, s13, 9
	s_add_u32 s16, s70, s14
	s_addc_u32 s17, s71, 0
	global_store_dwordx2 v236, v[0:1], s[16:17]
	s_lshl_b32 s14, s13, 2
	s_add_u32 s16, s74, s14
	s_addc_u32 s17, s75, 0
	s_mov_b64 exec, 1
	global_store_dword v237, v228, s[16:17]
	s_mov_b64 exec, -1
	v_readlane_b32 s18, v232, 32
	v_readlane_b32 s19, v233, 32
	s_nop 1
	v_add_f32_e32 v231, s18, v228
	v_max_f32_e32 v228, s19, v231
	v_sub_f32_e32 v231, v231, v228
	v_sub_f32_e32 v229, s19, v228
	v_mul_f32_e32 v231, 0x3fb8aa3b, v231
	v_mul_f32_e32 v229, 0x3fb8aa3b, v229
	v_exp_f32_e32 v230, v229
	v_exp_f32_e32 v229, v231
	s_nop 0
	v_mul_f32_e32 v220, v230, v72
	v_mul_f32_e32 v221, v230, v73
	v_fma_f32 v0, v229, v0, v220
	v_fma_f32 v1, v229, v1, v221
	s_add_i32 s13, s13, s10
	s_cmp_eq_u32 s13, s11
	s_cselect_b32 s13, s8, s13
	s_lshl_b32 s14, s13, 9
	s_add_u32 s16, s70, s14
	s_addc_u32 s17, s71, 0
	global_store_dwordx2 v236, v[0:1], s[16:17]
	s_lshl_b32 s14, s13, 2
	s_add_u32 s16, s74, s14
	s_addc_u32 s17, s75, 0
	s_mov_b64 exec, 1
	global_store_dword v237, v228, s[16:17]
	s_mov_b64 exec, -1
	v_readlane_b32 s18, v232, 33
	v_readlane_b32 s19, v233, 33
	s_nop 1
	v_add_f32_e32 v231, s18, v228
	v_max_f32_e32 v228, s19, v231
	v_sub_f32_e32 v231, v231, v228
	v_sub_f32_e32 v229, s19, v228
	v_mul_f32_e32 v231, 0x3fb8aa3b, v231
	v_mul_f32_e32 v229, 0x3fb8aa3b, v229
	v_exp_f32_e32 v230, v229
	v_exp_f32_e32 v229, v231
	s_nop 0
	v_mul_f32_e32 v220, v230, v74
	v_mul_f32_e32 v221, v230, v75
	v_fma_f32 v0, v229, v0, v220
	v_fma_f32 v1, v229, v1, v221
	s_add_i32 s13, s13, s10
	s_cmp_eq_u32 s13, s11
	s_cselect_b32 s13, s8, s13
	s_lshl_b32 s14, s13, 9
	s_add_u32 s16, s70, s14
	s_addc_u32 s17, s71, 0
	global_store_dwordx2 v236, v[0:1], s[16:17]
	s_lshl_b32 s14, s13, 2
	s_add_u32 s16, s74, s14
	s_addc_u32 s17, s75, 0
	s_mov_b64 exec, 1
	global_store_dword v237, v228, s[16:17]
	s_mov_b64 exec, -1
	v_readlane_b32 s18, v232, 34
	v_readlane_b32 s19, v233, 34
	s_nop 1
	v_add_f32_e32 v231, s18, v228
	v_max_f32_e32 v228, s19, v231
	v_sub_f32_e32 v231, v231, v228
	v_sub_f32_e32 v229, s19, v228
	v_mul_f32_e32 v231, 0x3fb8aa3b, v231
	v_mul_f32_e32 v229, 0x3fb8aa3b, v229
	v_exp_f32_e32 v230, v229
	v_exp_f32_e32 v229, v231
	s_nop 0
	v_mul_f32_e32 v220, v230, v76
	v_mul_f32_e32 v221, v230, v77
	v_fma_f32 v0, v229, v0, v220
	v_fma_f32 v1, v229, v1, v221
	s_add_i32 s13, s13, s10
	s_cmp_eq_u32 s13, s11
	s_cselect_b32 s13, s8, s13
	s_lshl_b32 s14, s13, 9
	s_add_u32 s16, s70, s14
	s_addc_u32 s17, s71, 0
	global_store_dwordx2 v236, v[0:1], s[16:17]
	s_lshl_b32 s14, s13, 2
	s_add_u32 s16, s74, s14
	s_addc_u32 s17, s75, 0
	s_mov_b64 exec, 1
	global_store_dword v237, v228, s[16:17]
	s_mov_b64 exec, -1
	v_readlane_b32 s18, v232, 35
	v_readlane_b32 s19, v233, 35
	s_nop 1
	v_add_f32_e32 v231, s18, v228
	v_max_f32_e32 v228, s19, v231
	v_sub_f32_e32 v231, v231, v228
	v_sub_f32_e32 v229, s19, v228
	v_mul_f32_e32 v231, 0x3fb8aa3b, v231
	v_mul_f32_e32 v229, 0x3fb8aa3b, v229
	v_exp_f32_e32 v230, v229
	v_exp_f32_e32 v229, v231
	s_nop 0
	v_mul_f32_e32 v220, v230, v78
	v_mul_f32_e32 v221, v230, v79
	v_fma_f32 v0, v229, v0, v220
	v_fma_f32 v1, v229, v1, v221
	s_add_i32 s13, s13, s10
	s_cmp_eq_u32 s13, s11
	s_cselect_b32 s13, s8, s13
	s_lshl_b32 s14, s13, 9
	s_add_u32 s16, s70, s14
	s_addc_u32 s17, s71, 0
	global_store_dwordx2 v236, v[0:1], s[16:17]
	s_lshl_b32 s14, s13, 2
	s_add_u32 s16, s74, s14
	s_addc_u32 s17, s75, 0
	s_mov_b64 exec, 1
	global_store_dword v237, v228, s[16:17]
	s_mov_b64 exec, -1
	v_readlane_b32 s18, v232, 36
	v_readlane_b32 s19, v233, 36
	s_nop 1
	v_add_f32_e32 v231, s18, v228
	v_max_f32_e32 v228, s19, v231
	v_sub_f32_e32 v231, v231, v228
	v_sub_f32_e32 v229, s19, v228
	v_mul_f32_e32 v231, 0x3fb8aa3b, v231
	v_mul_f32_e32 v229, 0x3fb8aa3b, v229
	v_exp_f32_e32 v230, v229
	v_exp_f32_e32 v229, v231
	s_nop 0
	v_mul_f32_e32 v220, v230, v80
	v_mul_f32_e32 v221, v230, v81
	v_fma_f32 v0, v229, v0, v220
	v_fma_f32 v1, v229, v1, v221
	s_add_i32 s13, s13, s10
	s_cmp_eq_u32 s13, s11
	s_cselect_b32 s13, s8, s13
	s_lshl_b32 s14, s13, 9
	s_add_u32 s16, s70, s14
	s_addc_u32 s17, s71, 0
	global_store_dwordx2 v236, v[0:1], s[16:17]
	s_lshl_b32 s14, s13, 2
	s_add_u32 s16, s74, s14
	s_addc_u32 s17, s75, 0
	s_mov_b64 exec, 1
	global_store_dword v237, v228, s[16:17]
	s_mov_b64 exec, -1
	v_readlane_b32 s18, v232, 37
	v_readlane_b32 s19, v233, 37
	s_nop 1
	v_add_f32_e32 v231, s18, v228
	v_max_f32_e32 v228, s19, v231
	v_sub_f32_e32 v231, v231, v228
	v_sub_f32_e32 v229, s19, v228
	v_mul_f32_e32 v231, 0x3fb8aa3b, v231
	v_mul_f32_e32 v229, 0x3fb8aa3b, v229
	v_exp_f32_e32 v230, v229
	v_exp_f32_e32 v229, v231
	s_nop 0
	v_mul_f32_e32 v220, v230, v82
	v_mul_f32_e32 v221, v230, v83
	v_fma_f32 v0, v229, v0, v220
	v_fma_f32 v1, v229, v1, v221
	s_add_i32 s13, s13, s10
	s_cmp_eq_u32 s13, s11
	s_cselect_b32 s13, s8, s13
	s_lshl_b32 s14, s13, 9
	s_add_u32 s16, s70, s14
	s_addc_u32 s17, s71, 0
	global_store_dwordx2 v236, v[0:1], s[16:17]
	s_lshl_b32 s14, s13, 2
	s_add_u32 s16, s74, s14
	s_addc_u32 s17, s75, 0
	s_mov_b64 exec, 1
	global_store_dword v237, v228, s[16:17]
	s_mov_b64 exec, -1
	v_readlane_b32 s18, v232, 38
	v_readlane_b32 s19, v233, 38
	s_nop 1
	v_add_f32_e32 v231, s18, v228
	v_max_f32_e32 v228, s19, v231
	v_sub_f32_e32 v231, v231, v228
	v_sub_f32_e32 v229, s19, v228
	v_mul_f32_e32 v231, 0x3fb8aa3b, v231
	v_mul_f32_e32 v229, 0x3fb8aa3b, v229
	v_exp_f32_e32 v230, v229
	v_exp_f32_e32 v229, v231
	s_nop 0
	v_mul_f32_e32 v220, v230, v84
	v_mul_f32_e32 v221, v230, v85
	v_fma_f32 v0, v229, v0, v220
	v_fma_f32 v1, v229, v1, v221
	s_add_i32 s13, s13, s10
	s_cmp_eq_u32 s13, s11
	s_cselect_b32 s13, s8, s13
	s_lshl_b32 s14, s13, 9
	s_add_u32 s16, s70, s14
	s_addc_u32 s17, s71, 0
	global_store_dwordx2 v236, v[0:1], s[16:17]
	s_lshl_b32 s14, s13, 2
	s_add_u32 s16, s74, s14
	s_addc_u32 s17, s75, 0
	s_mov_b64 exec, 1
	global_store_dword v237, v228, s[16:17]
	s_mov_b64 exec, -1
	v_readlane_b32 s18, v232, 39
	v_readlane_b32 s19, v233, 39
	s_nop 1
	v_add_f32_e32 v231, s18, v228
	v_max_f32_e32 v228, s19, v231
	v_sub_f32_e32 v231, v231, v228
	v_sub_f32_e32 v229, s19, v228
	v_mul_f32_e32 v231, 0x3fb8aa3b, v231
	v_mul_f32_e32 v229, 0x3fb8aa3b, v229
	v_exp_f32_e32 v230, v229
	v_exp_f32_e32 v229, v231
	s_nop 0
	v_mul_f32_e32 v220, v230, v86
	v_mul_f32_e32 v221, v230, v87
	v_fma_f32 v0, v229, v0, v220
	v_fma_f32 v1, v229, v1, v221
	s_add_i32 s13, s13, s10
	s_cmp_eq_u32 s13, s11
	s_cselect_b32 s13, s8, s13
	s_lshl_b32 s14, s13, 9
	s_add_u32 s16, s70, s14
	s_addc_u32 s17, s71, 0
	global_store_dwordx2 v236, v[0:1], s[16:17]
	s_lshl_b32 s14, s13, 2
	s_add_u32 s16, s74, s14
	s_addc_u32 s17, s75, 0
	s_mov_b64 exec, 1
	global_store_dword v237, v228, s[16:17]
	s_mov_b64 exec, -1
	v_readlane_b32 s18, v232, 40
	v_readlane_b32 s19, v233, 40
	s_nop 1
	v_add_f32_e32 v231, s18, v228
	v_max_f32_e32 v228, s19, v231
	v_sub_f32_e32 v231, v231, v228
	v_sub_f32_e32 v229, s19, v228
	v_mul_f32_e32 v231, 0x3fb8aa3b, v231
	v_mul_f32_e32 v229, 0x3fb8aa3b, v229
	v_exp_f32_e32 v230, v229
	v_exp_f32_e32 v229, v231
	s_nop 0
	v_mul_f32_e32 v220, v230, v88
	v_mul_f32_e32 v221, v230, v89
	v_fma_f32 v0, v229, v0, v220
	v_fma_f32 v1, v229, v1, v221
	s_add_i32 s13, s13, s10
	s_cmp_eq_u32 s13, s11
	s_cselect_b32 s13, s8, s13
	s_lshl_b32 s14, s13, 9
	s_add_u32 s16, s70, s14
	s_addc_u32 s17, s71, 0
	global_store_dwordx2 v236, v[0:1], s[16:17]
	s_lshl_b32 s14, s13, 2
	s_add_u32 s16, s74, s14
	s_addc_u32 s17, s75, 0
	s_mov_b64 exec, 1
	global_store_dword v237, v228, s[16:17]
	s_mov_b64 exec, -1
	v_readlane_b32 s18, v232, 41
	v_readlane_b32 s19, v233, 41
	s_nop 1
	v_add_f32_e32 v231, s18, v228
	v_max_f32_e32 v228, s19, v231
	v_sub_f32_e32 v231, v231, v228
	v_sub_f32_e32 v229, s19, v228
	v_mul_f32_e32 v231, 0x3fb8aa3b, v231
	v_mul_f32_e32 v229, 0x3fb8aa3b, v229
	v_exp_f32_e32 v230, v229
	v_exp_f32_e32 v229, v231
	s_nop 0
	v_mul_f32_e32 v220, v230, v90
	v_mul_f32_e32 v221, v230, v91
	v_fma_f32 v0, v229, v0, v220
	v_fma_f32 v1, v229, v1, v221
	s_add_i32 s13, s13, s10
	s_cmp_eq_u32 s13, s11
	s_cselect_b32 s13, s8, s13
	s_lshl_b32 s14, s13, 9
	s_add_u32 s16, s70, s14
	s_addc_u32 s17, s71, 0
	global_store_dwordx2 v236, v[0:1], s[16:17]
	s_lshl_b32 s14, s13, 2
	s_add_u32 s16, s74, s14
	s_addc_u32 s17, s75, 0
	s_mov_b64 exec, 1
	global_store_dword v237, v228, s[16:17]
	s_mov_b64 exec, -1
	v_readlane_b32 s18, v232, 42
	v_readlane_b32 s19, v233, 42
	s_nop 1
	v_add_f32_e32 v231, s18, v228
	v_max_f32_e32 v228, s19, v231
	v_sub_f32_e32 v231, v231, v228
	v_sub_f32_e32 v229, s19, v228
	v_mul_f32_e32 v231, 0x3fb8aa3b, v231
	v_mul_f32_e32 v229, 0x3fb8aa3b, v229
	v_exp_f32_e32 v230, v229
	v_exp_f32_e32 v229, v231
	s_nop 0
	v_mul_f32_e32 v220, v230, v92
	v_mul_f32_e32 v221, v230, v93
	v_fma_f32 v0, v229, v0, v220
	v_fma_f32 v1, v229, v1, v221
	s_add_i32 s13, s13, s10
	s_cmp_eq_u32 s13, s11
	s_cselect_b32 s13, s8, s13
	s_lshl_b32 s14, s13, 9
	s_add_u32 s16, s70, s14
	s_addc_u32 s17, s71, 0
	global_store_dwordx2 v236, v[0:1], s[16:17]
	s_lshl_b32 s14, s13, 2
	s_add_u32 s16, s74, s14
	s_addc_u32 s17, s75, 0
	s_mov_b64 exec, 1
	global_store_dword v237, v228, s[16:17]
	s_mov_b64 exec, -1
	v_readlane_b32 s18, v232, 43
	v_readlane_b32 s19, v233, 43
	s_nop 1
	v_add_f32_e32 v231, s18, v228
	v_max_f32_e32 v228, s19, v231
	v_sub_f32_e32 v231, v231, v228
	v_sub_f32_e32 v229, s19, v228
	v_mul_f32_e32 v231, 0x3fb8aa3b, v231
	v_mul_f32_e32 v229, 0x3fb8aa3b, v229
	v_exp_f32_e32 v230, v229
	v_exp_f32_e32 v229, v231
	s_nop 0
	v_mul_f32_e32 v220, v230, v94
	v_mul_f32_e32 v221, v230, v95
	v_fma_f32 v0, v229, v0, v220
	v_fma_f32 v1, v229, v1, v221
	s_add_i32 s13, s13, s10
	s_cmp_eq_u32 s13, s11
	s_cselect_b32 s13, s8, s13
	s_lshl_b32 s14, s13, 9
	s_add_u32 s16, s70, s14
	s_addc_u32 s17, s71, 0
	global_store_dwordx2 v236, v[0:1], s[16:17]
	s_lshl_b32 s14, s13, 2
	s_add_u32 s16, s74, s14
	s_addc_u32 s17, s75, 0
	s_mov_b64 exec, 1
	global_store_dword v237, v228, s[16:17]
	s_mov_b64 exec, -1
	v_readlane_b32 s18, v232, 44
	v_readlane_b32 s19, v233, 44
	s_nop 1
	v_add_f32_e32 v231, s18, v228
	v_max_f32_e32 v228, s19, v231
	v_sub_f32_e32 v231, v231, v228
	v_sub_f32_e32 v229, s19, v228
	v_mul_f32_e32 v231, 0x3fb8aa3b, v231
	v_mul_f32_e32 v229, 0x3fb8aa3b, v229
	v_exp_f32_e32 v230, v229
	v_exp_f32_e32 v229, v231
	s_nop 0
	v_mul_f32_e32 v220, v230, v96
	v_mul_f32_e32 v221, v230, v97
	v_fma_f32 v0, v229, v0, v220
	v_fma_f32 v1, v229, v1, v221
	s_add_i32 s13, s13, s10
	s_cmp_eq_u32 s13, s11
	s_cselect_b32 s13, s8, s13
	s_lshl_b32 s14, s13, 9
	s_add_u32 s16, s70, s14
	s_addc_u32 s17, s71, 0
	global_store_dwordx2 v236, v[0:1], s[16:17]
	s_lshl_b32 s14, s13, 2
	s_add_u32 s16, s74, s14
	s_addc_u32 s17, s75, 0
	s_mov_b64 exec, 1
	global_store_dword v237, v228, s[16:17]
	s_mov_b64 exec, -1
	v_readlane_b32 s18, v232, 45
	v_readlane_b32 s19, v233, 45
	s_nop 1
	v_add_f32_e32 v231, s18, v228
	v_max_f32_e32 v228, s19, v231
	v_sub_f32_e32 v231, v231, v228
	v_sub_f32_e32 v229, s19, v228
	v_mul_f32_e32 v231, 0x3fb8aa3b, v231
	v_mul_f32_e32 v229, 0x3fb8aa3b, v229
	v_exp_f32_e32 v230, v229
	v_exp_f32_e32 v229, v231
	s_nop 0
	v_mul_f32_e32 v220, v230, v98
	v_mul_f32_e32 v221, v230, v99
	v_fma_f32 v0, v229, v0, v220
	v_fma_f32 v1, v229, v1, v221
	s_add_i32 s13, s13, s10
	s_cmp_eq_u32 s13, s11
	s_cselect_b32 s13, s8, s13
	s_lshl_b32 s14, s13, 9
	s_add_u32 s16, s70, s14
	s_addc_u32 s17, s71, 0
	global_store_dwordx2 v236, v[0:1], s[16:17]
	s_lshl_b32 s14, s13, 2
	s_add_u32 s16, s74, s14
	s_addc_u32 s17, s75, 0
	s_mov_b64 exec, 1
	global_store_dword v237, v228, s[16:17]
	s_mov_b64 exec, -1
	v_readlane_b32 s18, v232, 46
	v_readlane_b32 s19, v233, 46
	s_nop 1
	v_add_f32_e32 v231, s18, v228
	v_max_f32_e32 v228, s19, v231
	v_sub_f32_e32 v231, v231, v228
	v_sub_f32_e32 v229, s19, v228
	v_mul_f32_e32 v231, 0x3fb8aa3b, v231
	v_mul_f32_e32 v229, 0x3fb8aa3b, v229
	v_exp_f32_e32 v230, v229
	v_exp_f32_e32 v229, v231
	s_nop 0
	v_mul_f32_e32 v220, v230, v100
	v_mul_f32_e32 v221, v230, v101
	v_fma_f32 v0, v229, v0, v220
	v_fma_f32 v1, v229, v1, v221
	s_add_i32 s13, s13, s10
	s_cmp_eq_u32 s13, s11
	s_cselect_b32 s13, s8, s13
	s_lshl_b32 s14, s13, 9
	s_add_u32 s16, s70, s14
	s_addc_u32 s17, s71, 0
	global_store_dwordx2 v236, v[0:1], s[16:17]
	s_lshl_b32 s14, s13, 2
	s_add_u32 s16, s74, s14
	s_addc_u32 s17, s75, 0
	s_mov_b64 exec, 1
	global_store_dword v237, v228, s[16:17]
	s_mov_b64 exec, -1
	v_readlane_b32 s18, v232, 47
	v_readlane_b32 s19, v233, 47
	s_nop 1
	v_add_f32_e32 v231, s18, v228
	v_max_f32_e32 v228, s19, v231
	v_sub_f32_e32 v231, v231, v228
	v_sub_f32_e32 v229, s19, v228
	v_mul_f32_e32 v231, 0x3fb8aa3b, v231
	v_mul_f32_e32 v229, 0x3fb8aa3b, v229
	v_exp_f32_e32 v230, v229
	v_exp_f32_e32 v229, v231
	s_nop 0
	v_mul_f32_e32 v220, v230, v102
	v_mul_f32_e32 v221, v230, v103
	v_fma_f32 v0, v229, v0, v220
	v_fma_f32 v1, v229, v1, v221
	s_add_i32 s13, s13, s10
	s_cmp_eq_u32 s13, s11
	s_cselect_b32 s13, s8, s13
	s_lshl_b32 s14, s13, 9
	s_add_u32 s16, s70, s14
	s_addc_u32 s17, s71, 0
	global_store_dwordx2 v236, v[0:1], s[16:17]
	s_lshl_b32 s14, s13, 2
	s_add_u32 s16, s74, s14
	s_addc_u32 s17, s75, 0
	s_mov_b64 exec, 1
	global_store_dword v237, v228, s[16:17]
	s_mov_b64 exec, -1
	v_readlane_b32 s18, v232, 48
	v_readlane_b32 s19, v233, 48
	s_nop 1
	v_add_f32_e32 v231, s18, v228
	v_max_f32_e32 v228, s19, v231
	v_sub_f32_e32 v231, v231, v228
	v_sub_f32_e32 v229, s19, v228
	v_mul_f32_e32 v231, 0x3fb8aa3b, v231
	v_mul_f32_e32 v229, 0x3fb8aa3b, v229
	v_exp_f32_e32 v230, v229
	v_exp_f32_e32 v229, v231
	s_nop 0
	v_mul_f32_e32 v220, v230, v104
	v_mul_f32_e32 v221, v230, v105
	v_fma_f32 v0, v229, v0, v220
	v_fma_f32 v1, v229, v1, v221
	s_add_i32 s13, s13, s10
	s_cmp_eq_u32 s13, s11
	s_cselect_b32 s13, s8, s13
	s_lshl_b32 s14, s13, 9
	s_add_u32 s16, s70, s14
	s_addc_u32 s17, s71, 0
	global_store_dwordx2 v236, v[0:1], s[16:17]
	s_lshl_b32 s14, s13, 2
	s_add_u32 s16, s74, s14
	s_addc_u32 s17, s75, 0
	s_mov_b64 exec, 1
	global_store_dword v237, v228, s[16:17]
	s_mov_b64 exec, -1
	v_readlane_b32 s18, v232, 49
	v_readlane_b32 s19, v233, 49
	s_nop 1
	v_add_f32_e32 v231, s18, v228
	v_max_f32_e32 v228, s19, v231
	v_sub_f32_e32 v231, v231, v228
	v_sub_f32_e32 v229, s19, v228
	v_mul_f32_e32 v231, 0x3fb8aa3b, v231
	v_mul_f32_e32 v229, 0x3fb8aa3b, v229
	v_exp_f32_e32 v230, v229
	v_exp_f32_e32 v229, v231
	s_nop 0
	v_mul_f32_e32 v220, v230, v106
	v_mul_f32_e32 v221, v230, v107
	v_fma_f32 v0, v229, v0, v220
	v_fma_f32 v1, v229, v1, v221
	s_add_i32 s13, s13, s10
	s_cmp_eq_u32 s13, s11
	s_cselect_b32 s13, s8, s13
	s_lshl_b32 s14, s13, 9
	s_add_u32 s16, s70, s14
	s_addc_u32 s17, s71, 0
	global_store_dwordx2 v236, v[0:1], s[16:17]
	s_lshl_b32 s14, s13, 2
	s_add_u32 s16, s74, s14
	s_addc_u32 s17, s75, 0
	s_mov_b64 exec, 1
	global_store_dword v237, v228, s[16:17]
	s_mov_b64 exec, -1
	v_readlane_b32 s18, v232, 50
	v_readlane_b32 s19, v233, 50
	s_nop 1
	v_add_f32_e32 v231, s18, v228
	v_max_f32_e32 v228, s19, v231
	v_sub_f32_e32 v231, v231, v228
	v_sub_f32_e32 v229, s19, v228
	v_mul_f32_e32 v231, 0x3fb8aa3b, v231
	v_mul_f32_e32 v229, 0x3fb8aa3b, v229
	v_exp_f32_e32 v230, v229
	v_exp_f32_e32 v229, v231
	s_nop 0
	v_mul_f32_e32 v220, v230, v108
	v_mul_f32_e32 v221, v230, v109
	v_fma_f32 v0, v229, v0, v220
	v_fma_f32 v1, v229, v1, v221
	s_add_i32 s13, s13, s10
	s_cmp_eq_u32 s13, s11
	s_cselect_b32 s13, s8, s13
	s_lshl_b32 s14, s13, 9
	s_add_u32 s16, s70, s14
	s_addc_u32 s17, s71, 0
	global_store_dwordx2 v236, v[0:1], s[16:17]
	s_lshl_b32 s14, s13, 2
	s_add_u32 s16, s74, s14
	s_addc_u32 s17, s75, 0
	s_mov_b64 exec, 1
	global_store_dword v237, v228, s[16:17]
	s_mov_b64 exec, -1
	v_readlane_b32 s18, v232, 51
	v_readlane_b32 s19, v233, 51
	s_nop 1
	v_add_f32_e32 v231, s18, v228
	v_max_f32_e32 v228, s19, v231
	v_sub_f32_e32 v231, v231, v228
	v_sub_f32_e32 v229, s19, v228
	v_mul_f32_e32 v231, 0x3fb8aa3b, v231
	v_mul_f32_e32 v229, 0x3fb8aa3b, v229
	v_exp_f32_e32 v230, v229
	v_exp_f32_e32 v229, v231
	s_nop 0
	v_mul_f32_e32 v220, v230, v110
	v_mul_f32_e32 v221, v230, v111
	v_fma_f32 v0, v229, v0, v220
	v_fma_f32 v1, v229, v1, v221
	s_add_i32 s13, s13, s10
	s_cmp_eq_u32 s13, s11
	s_cselect_b32 s13, s8, s13
	s_lshl_b32 s14, s13, 9
	s_add_u32 s16, s70, s14
	s_addc_u32 s17, s71, 0
	global_store_dwordx2 v236, v[0:1], s[16:17]
	s_lshl_b32 s14, s13, 2
	s_add_u32 s16, s74, s14
	s_addc_u32 s17, s75, 0
	s_mov_b64 exec, 1
	global_store_dword v237, v228, s[16:17]
	s_mov_b64 exec, -1
	v_readlane_b32 s18, v232, 52
	v_readlane_b32 s19, v233, 52
	s_nop 1
	v_add_f32_e32 v231, s18, v228
	v_max_f32_e32 v228, s19, v231
	v_sub_f32_e32 v231, v231, v228
	v_sub_f32_e32 v229, s19, v228
	v_mul_f32_e32 v231, 0x3fb8aa3b, v231
	v_mul_f32_e32 v229, 0x3fb8aa3b, v229
	v_exp_f32_e32 v230, v229
	v_exp_f32_e32 v229, v231
	s_nop 0
	v_mul_f32_e32 v220, v230, v112
	v_mul_f32_e32 v221, v230, v113
	v_fma_f32 v0, v229, v0, v220
	v_fma_f32 v1, v229, v1, v221
	s_add_i32 s13, s13, s10
	s_cmp_eq_u32 s13, s11
	s_cselect_b32 s13, s8, s13
	s_lshl_b32 s14, s13, 9
	s_add_u32 s16, s70, s14
	s_addc_u32 s17, s71, 0
	global_store_dwordx2 v236, v[0:1], s[16:17]
	s_lshl_b32 s14, s13, 2
	s_add_u32 s16, s74, s14
	s_addc_u32 s17, s75, 0
	s_mov_b64 exec, 1
	global_store_dword v237, v228, s[16:17]
	s_mov_b64 exec, -1
	v_readlane_b32 s18, v232, 53
	v_readlane_b32 s19, v233, 53
	s_nop 1
	v_add_f32_e32 v231, s18, v228
	v_max_f32_e32 v228, s19, v231
	v_sub_f32_e32 v231, v231, v228
	v_sub_f32_e32 v229, s19, v228
	v_mul_f32_e32 v231, 0x3fb8aa3b, v231
	v_mul_f32_e32 v229, 0x3fb8aa3b, v229
	v_exp_f32_e32 v230, v229
	v_exp_f32_e32 v229, v231
	s_nop 0
	v_mul_f32_e32 v220, v230, v114
	v_mul_f32_e32 v221, v230, v115
	v_fma_f32 v0, v229, v0, v220
	v_fma_f32 v1, v229, v1, v221
	s_add_i32 s13, s13, s10
	s_cmp_eq_u32 s13, s11
	s_cselect_b32 s13, s8, s13
	s_lshl_b32 s14, s13, 9
	s_add_u32 s16, s70, s14
	s_addc_u32 s17, s71, 0
	global_store_dwordx2 v236, v[0:1], s[16:17]
	s_lshl_b32 s14, s13, 2
	s_add_u32 s16, s74, s14
	s_addc_u32 s17, s75, 0
	s_mov_b64 exec, 1
	global_store_dword v237, v228, s[16:17]
	s_mov_b64 exec, -1
	v_readlane_b32 s18, v232, 54
	v_readlane_b32 s19, v233, 54
	s_nop 1
	v_add_f32_e32 v231, s18, v228
	v_max_f32_e32 v228, s19, v231
	v_sub_f32_e32 v231, v231, v228
	v_sub_f32_e32 v229, s19, v228
	v_mul_f32_e32 v231, 0x3fb8aa3b, v231
	v_mul_f32_e32 v229, 0x3fb8aa3b, v229
	v_exp_f32_e32 v230, v229
	v_exp_f32_e32 v229, v231
	s_nop 0
	v_mul_f32_e32 v220, v230, v116
	v_mul_f32_e32 v221, v230, v117
	v_fma_f32 v0, v229, v0, v220
	v_fma_f32 v1, v229, v1, v221
	s_add_i32 s13, s13, s10
	s_cmp_eq_u32 s13, s11
	s_cselect_b32 s13, s8, s13
	s_lshl_b32 s14, s13, 9
	s_add_u32 s16, s70, s14
	s_addc_u32 s17, s71, 0
	global_store_dwordx2 v236, v[0:1], s[16:17]
	s_lshl_b32 s14, s13, 2
	s_add_u32 s16, s74, s14
	s_addc_u32 s17, s75, 0
	s_mov_b64 exec, 1
	global_store_dword v237, v228, s[16:17]
	s_mov_b64 exec, -1
	v_readlane_b32 s18, v232, 55
	v_readlane_b32 s19, v233, 55
	s_nop 1
	v_add_f32_e32 v231, s18, v228
	v_max_f32_e32 v228, s19, v231
	v_sub_f32_e32 v231, v231, v228
	v_sub_f32_e32 v229, s19, v228
	v_mul_f32_e32 v231, 0x3fb8aa3b, v231
	v_mul_f32_e32 v229, 0x3fb8aa3b, v229
	v_exp_f32_e32 v230, v229
	v_exp_f32_e32 v229, v231
	s_nop 0
	v_mul_f32_e32 v220, v230, v118
	v_mul_f32_e32 v221, v230, v119
	v_fma_f32 v0, v229, v0, v220
	v_fma_f32 v1, v229, v1, v221
	s_add_i32 s13, s13, s10
	s_cmp_eq_u32 s13, s11
	s_cselect_b32 s13, s8, s13
	s_lshl_b32 s14, s13, 9
	s_add_u32 s16, s70, s14
	s_addc_u32 s17, s71, 0
	global_store_dwordx2 v236, v[0:1], s[16:17]
	s_lshl_b32 s14, s13, 2
	s_add_u32 s16, s74, s14
	s_addc_u32 s17, s75, 0
	s_mov_b64 exec, 1
	global_store_dword v237, v228, s[16:17]
	s_mov_b64 exec, -1
	v_readlane_b32 s18, v232, 56
	v_readlane_b32 s19, v233, 56
	s_nop 1
	v_add_f32_e32 v231, s18, v228
	v_max_f32_e32 v228, s19, v231
	v_sub_f32_e32 v231, v231, v228
	v_sub_f32_e32 v229, s19, v228
	v_mul_f32_e32 v231, 0x3fb8aa3b, v231
	v_mul_f32_e32 v229, 0x3fb8aa3b, v229
	v_exp_f32_e32 v230, v229
	v_exp_f32_e32 v229, v231
	s_nop 0
	v_mul_f32_e32 v220, v230, v120
	v_mul_f32_e32 v221, v230, v121
	v_fma_f32 v0, v229, v0, v220
	v_fma_f32 v1, v229, v1, v221
	s_add_i32 s13, s13, s10
	s_cmp_eq_u32 s13, s11
	s_cselect_b32 s13, s8, s13
	s_lshl_b32 s14, s13, 9
	s_add_u32 s16, s70, s14
	s_addc_u32 s17, s71, 0
	global_store_dwordx2 v236, v[0:1], s[16:17]
	s_lshl_b32 s14, s13, 2
	s_add_u32 s16, s74, s14
	s_addc_u32 s17, s75, 0
	s_mov_b64 exec, 1
	global_store_dword v237, v228, s[16:17]
	s_mov_b64 exec, -1
	v_readlane_b32 s18, v232, 57
	v_readlane_b32 s19, v233, 57
	s_nop 1
	v_add_f32_e32 v231, s18, v228
	v_max_f32_e32 v228, s19, v231
	v_sub_f32_e32 v231, v231, v228
	v_sub_f32_e32 v229, s19, v228
	v_mul_f32_e32 v231, 0x3fb8aa3b, v231
	v_mul_f32_e32 v229, 0x3fb8aa3b, v229
	v_exp_f32_e32 v230, v229
	v_exp_f32_e32 v229, v231
	s_nop 0
	v_mul_f32_e32 v220, v230, v122
	v_mul_f32_e32 v221, v230, v123
	v_fma_f32 v0, v229, v0, v220
	v_fma_f32 v1, v229, v1, v221
	s_add_i32 s13, s13, s10
	s_cmp_eq_u32 s13, s11
	s_cselect_b32 s13, s8, s13
	s_lshl_b32 s14, s13, 9
	s_add_u32 s16, s70, s14
	s_addc_u32 s17, s71, 0
	global_store_dwordx2 v236, v[0:1], s[16:17]
	s_lshl_b32 s14, s13, 2
	s_add_u32 s16, s74, s14
	s_addc_u32 s17, s75, 0
	s_mov_b64 exec, 1
	global_store_dword v237, v228, s[16:17]
	s_mov_b64 exec, -1
	v_readlane_b32 s18, v232, 58
	v_readlane_b32 s19, v233, 58
	s_nop 1
	v_add_f32_e32 v231, s18, v228
	v_max_f32_e32 v228, s19, v231
	v_sub_f32_e32 v231, v231, v228
	v_sub_f32_e32 v229, s19, v228
	v_mul_f32_e32 v231, 0x3fb8aa3b, v231
	v_mul_f32_e32 v229, 0x3fb8aa3b, v229
	v_exp_f32_e32 v230, v229
	v_exp_f32_e32 v229, v231
	s_nop 0
	v_mul_f32_e32 v220, v230, v124
	v_mul_f32_e32 v221, v230, v125
	v_fma_f32 v0, v229, v0, v220
	v_fma_f32 v1, v229, v1, v221
	s_add_i32 s13, s13, s10
	s_cmp_eq_u32 s13, s11
	s_cselect_b32 s13, s8, s13
	s_lshl_b32 s14, s13, 9
	s_add_u32 s16, s70, s14
	s_addc_u32 s17, s71, 0
	global_store_dwordx2 v236, v[0:1], s[16:17]
	s_lshl_b32 s14, s13, 2
	s_add_u32 s16, s74, s14
	s_addc_u32 s17, s75, 0
	s_mov_b64 exec, 1
	global_store_dword v237, v228, s[16:17]
	s_mov_b64 exec, -1
	v_readlane_b32 s18, v232, 59
	v_readlane_b32 s19, v233, 59
	s_nop 1
	v_add_f32_e32 v231, s18, v228
	v_max_f32_e32 v228, s19, v231
	v_sub_f32_e32 v231, v231, v228
	v_sub_f32_e32 v229, s19, v228
	v_mul_f32_e32 v231, 0x3fb8aa3b, v231
	v_mul_f32_e32 v229, 0x3fb8aa3b, v229
	v_exp_f32_e32 v230, v229
	v_exp_f32_e32 v229, v231
	s_nop 0
	v_mul_f32_e32 v220, v230, v126
	v_mul_f32_e32 v221, v230, v127
	v_fma_f32 v0, v229, v0, v220
	v_fma_f32 v1, v229, v1, v221
	s_add_i32 s13, s13, s10
	s_cmp_eq_u32 s13, s11
	s_cselect_b32 s13, s8, s13
	s_lshl_b32 s14, s13, 9
	s_add_u32 s16, s70, s14
	s_addc_u32 s17, s71, 0
	global_store_dwordx2 v236, v[0:1], s[16:17]
	s_lshl_b32 s14, s13, 2
	s_add_u32 s16, s74, s14
	s_addc_u32 s17, s75, 0
	s_mov_b64 exec, 1
	global_store_dword v237, v228, s[16:17]
	s_mov_b64 exec, -1
	v_readlane_b32 s18, v232, 60
	v_readlane_b32 s19, v233, 60
	s_nop 1
	v_add_f32_e32 v231, s18, v228
	v_max_f32_e32 v228, s19, v231
	v_sub_f32_e32 v231, v231, v228
	v_sub_f32_e32 v229, s19, v228
	v_mul_f32_e32 v231, 0x3fb8aa3b, v231
	v_mul_f32_e32 v229, 0x3fb8aa3b, v229
	v_exp_f32_e32 v230, v229
	v_exp_f32_e32 v229, v231
	s_nop 0
	v_mul_f32_e32 v220, v230, v130
	v_mul_f32_e32 v221, v230, v131
	v_fma_f32 v0, v229, v0, v220
	v_fma_f32 v1, v229, v1, v221
	s_add_i32 s13, s13, s10
	s_cmp_eq_u32 s13, s11
	s_cselect_b32 s13, s8, s13
	s_lshl_b32 s14, s13, 9
	s_add_u32 s16, s70, s14
	s_addc_u32 s17, s71, 0
	global_store_dwordx2 v236, v[0:1], s[16:17]
	s_lshl_b32 s14, s13, 2
	s_add_u32 s16, s74, s14
	s_addc_u32 s17, s75, 0
	s_mov_b64 exec, 1
	global_store_dword v237, v228, s[16:17]
	s_mov_b64 exec, -1
	v_readlane_b32 s18, v232, 61
	v_readlane_b32 s19, v233, 61
	s_nop 1
	v_add_f32_e32 v231, s18, v228
	v_max_f32_e32 v228, s19, v231
	v_sub_f32_e32 v231, v231, v228
	v_sub_f32_e32 v229, s19, v228
	v_mul_f32_e32 v231, 0x3fb8aa3b, v231
	v_mul_f32_e32 v229, 0x3fb8aa3b, v229
	v_exp_f32_e32 v230, v229
	v_exp_f32_e32 v229, v231
	s_nop 0
	v_mul_f32_e32 v220, v230, v132
	v_mul_f32_e32 v221, v230, v133
	v_fma_f32 v0, v229, v0, v220
	v_fma_f32 v1, v229, v1, v221
	s_add_i32 s13, s13, s10
	s_cmp_eq_u32 s13, s11
	s_cselect_b32 s13, s8, s13
	s_lshl_b32 s14, s13, 9
	s_add_u32 s16, s70, s14
	s_addc_u32 s17, s71, 0
	global_store_dwordx2 v236, v[0:1], s[16:17]
	s_lshl_b32 s14, s13, 2
	s_add_u32 s16, s74, s14
	s_addc_u32 s17, s75, 0
	s_mov_b64 exec, 1
	global_store_dword v237, v228, s[16:17]
	s_mov_b64 exec, -1
	v_readlane_b32 s18, v232, 62
	v_readlane_b32 s19, v233, 62
	s_nop 1
	v_add_f32_e32 v231, s18, v228
	v_max_f32_e32 v228, s19, v231
	v_sub_f32_e32 v231, v231, v228
	v_sub_f32_e32 v229, s19, v228
	v_mul_f32_e32 v231, 0x3fb8aa3b, v231
	v_mul_f32_e32 v229, 0x3fb8aa3b, v229
	v_exp_f32_e32 v230, v229
	v_exp_f32_e32 v229, v231
	s_nop 0
	v_mul_f32_e32 v220, v230, v134
	v_mul_f32_e32 v221, v230, v135
	v_fma_f32 v0, v229, v0, v220
	v_fma_f32 v1, v229, v1, v221
	s_add_i32 s13, s13, s10
	s_cmp_eq_u32 s13, s11
	s_cselect_b32 s13, s8, s13
	s_lshl_b32 s14, s13, 9
	s_add_u32 s16, s70, s14
	s_addc_u32 s17, s71, 0
	global_store_dwordx2 v236, v[0:1], s[16:17]
	s_lshl_b32 s14, s13, 2
	s_add_u32 s16, s74, s14
	s_addc_u32 s17, s75, 0
	s_mov_b64 exec, 1
	global_store_dword v237, v228, s[16:17]
	s_mov_b64 exec, -1
	v_readlane_b32 s18, v232, 63
	v_readlane_b32 s19, v233, 63
	s_nop 1
	v_add_f32_e32 v231, s18, v228
	v_max_f32_e32 v228, s19, v231
	v_sub_f32_e32 v231, v231, v228
	v_sub_f32_e32 v229, s19, v228
	v_mul_f32_e32 v231, 0x3fb8aa3b, v231
	v_mul_f32_e32 v229, 0x3fb8aa3b, v229
	v_exp_f32_e32 v230, v229
	v_exp_f32_e32 v229, v231
	s_nop 0
	v_mul_f32_e32 v220, v230, v136
	v_mul_f32_e32 v221, v230, v137
	v_fma_f32 v0, v229, v0, v220
	v_fma_f32 v1, v229, v1, v221
	s_add_i32 s13, s13, s10
	s_cmp_eq_u32 s13, s11
	s_cselect_b32 s13, s8, s13
	s_lshl_b32 s14, s13, 9
	s_add_u32 s16, s70, s14
	s_addc_u32 s17, s71, 0
	global_store_dwordx2 v236, v[0:1], s[16:17]
	s_lshl_b32 s14, s13, 2
	s_add_u32 s16, s74, s14
	s_addc_u32 s17, s75, 0
	s_mov_b64 exec, 1
	global_store_dword v237, v228, s[16:17]
	s_mov_b64 exec, -1
	v_readlane_b32 s18, v234, 0
	v_readlane_b32 s19, v235, 0
	s_nop 1
	v_add_f32_e32 v231, s18, v228
	v_max_f32_e32 v228, s19, v231
	v_sub_f32_e32 v231, v231, v228
	v_sub_f32_e32 v229, s19, v228
	v_mul_f32_e32 v231, 0x3fb8aa3b, v231
	v_mul_f32_e32 v229, 0x3fb8aa3b, v229
	v_exp_f32_e32 v230, v229
	v_exp_f32_e32 v229, v231
	s_nop 0
	v_mul_f32_e32 v220, v230, v138
	v_mul_f32_e32 v221, v230, v139
	v_fma_f32 v0, v229, v0, v220
	v_fma_f32 v1, v229, v1, v221
	s_add_i32 s13, s13, s10
	s_cmp_eq_u32 s13, s11
	s_cselect_b32 s13, s8, s13
	s_lshl_b32 s14, s13, 9
	s_add_u32 s16, s70, s14
	s_addc_u32 s17, s71, 0
	global_store_dwordx2 v236, v[0:1], s[16:17]
	s_lshl_b32 s14, s13, 2
	s_add_u32 s16, s74, s14
	s_addc_u32 s17, s75, 0
	s_mov_b64 exec, 1
	global_store_dword v237, v228, s[16:17]
	s_mov_b64 exec, -1
	v_readlane_b32 s18, v234, 1
	v_readlane_b32 s19, v235, 1
	s_nop 1
	v_add_f32_e32 v231, s18, v228
	v_max_f32_e32 v228, s19, v231
	v_sub_f32_e32 v231, v231, v228
	v_sub_f32_e32 v229, s19, v228
	v_mul_f32_e32 v231, 0x3fb8aa3b, v231
	v_mul_f32_e32 v229, 0x3fb8aa3b, v229
	v_exp_f32_e32 v230, v229
	v_exp_f32_e32 v229, v231
	s_nop 0
	v_mul_f32_e32 v220, v230, v140
	v_mul_f32_e32 v221, v230, v141
	v_fma_f32 v0, v229, v0, v220
	v_fma_f32 v1, v229, v1, v221
	s_add_i32 s13, s13, s10
	s_cmp_eq_u32 s13, s11
	s_cselect_b32 s13, s8, s13
.Lgs_done:
	s_waitcnt vmcnt(0) lgkmcnt(0)
	s_mov_b64 exec, -1
	s_mov_b64 s[30:31], -1
	s_branch .LBB1_980
.LBB1_861:
	s_mov_b64 s[30:31], 0
